# GEMM MFMA clusters reordered so the two k-steps of each accumulator issue back to back (accumulate chains of 2)
# speedup vs baseline: 1.0133x; 1.0084x over previous
; #define PG8_STAGE(bufoff, gbase, voff) do { _Pragma("unroll") for (int _i = 0; _i < 2; ++_i) \
;         __builtin_amdgcn_global_load_lds((const unsigned*)((const char*)(gbase) + (voff)[_i]), (LAS unsigned*)(lds + (bufoff) + ldsw + _i * 8192), 16, 0, 0); } while (0)
; #define PG8_LDA(dst, b, h) do { _Pragma("unroll") for (int m = 0; m < 4; ++m) _Pragma("unroll") for (int k = 0; k < 2; ++k) dst[m][k] = *(const LAS bf16x8*)(lds + PG8_SA(b, h) + aoff + m * 2048 + k * 1024); } while (0)
; #define PG8_LDB(dst, b, h) do { _Pragma("unroll") for (int n = 0; n < 2; ++n) _Pragma("unroll") for (int k = 0; k < 2; ++k) dst[n][k] = *(const LAS bf16x8*)(lds + PG8_SB(b, h) + boff + n * 2048 + k * 1024); } while (0)
; #define PG8_MMA(ai, bj, At, Bt) do { __builtin_amdgcn_s_setprio(1); _Pragma("unroll") for (int m = 0; m < 4; ++m) _Pragma("unroll") for (int n = 0; n < 2; ++n) _Pragma("unroll") for (int k = 0; k < 2; ++k) \
;         acc[ai][bj][m][n] = __builtin_amdgcn_mfma_f32_16x16x32_bf16(Bt[n][k], At[m][k], acc[ai][bj][m][n], 0, 0, 0); __builtin_amdgcn_s_setprio(0); } while (0)
; #define PG8_WAIT_V(n) asm volatile("s_waitcnt vmcnt(" #n ")" ::: "memory")
; #define PG8_BAR __builtin_amdgcn_s_barrier()
; template <class Epi, class Sched>
; __device__ __forceinline__ void gemm_phase(LAS unsigned char* lds, const Gemm g, const Sched& S, const Epi& E) {
;     ...
;         for (int t = 0; t < ntu; t += 2) {
;             const bool last = (t == ntu - 2);
;             const char* a1 = cA + (size_t)(t + 1) * kstep;
;             const char* a2 = last ? nA : cA + (size_t)(t + 2) * kstep; const char* b2 = last ? nB : cB + (size_t)(t + 2) * kstep;
;             const char* a3 = a2 + kstep; const char* b3 = b2 + kstep;
;             if (last && has_next) S.a_ready(nxt);
;             PG8_LDB(B0, 0, 0); PG8_SCHED; PG8_LDA(At, 0, 0); PG8_STAGE(PG8_SA(1, 1), a1 + hstepA, voffA);
;             PG8_WAIT_L(8); PG8_BAR; PG8_WAIT_L(0); PG8_MMA(0, 0, At, B0); PG8_BAR; PG8_SCHED;
;             PG8_LDB(B1, 0, 1); PG8_STAGE(PG8_SB(0, 0), b2, voffB);
;             PG8_BAR; PG8_WAIT_L(0); PG8_MMA(0, 1, At, B1); PG8_BAR;
;             PG8_LDA(At, 0, 1); PG8_STAGE(PG8_SA(0, 0), a2, voffA);
;             PG8_BAR; PG8_WAIT_L(0); PG8_MMA(1, 0, At, B0); PG8_BAR; PG8_SCHED;
;             PG8_STAGE(PG8_SB(0, 1), b2 + hstepB, voffB);
;             PG8_WAIT_V(6); PG8_BAR; PG8_MMA(1, 1, At, B1); PG8_BAR;
.LBB0_381:
	s_add_u32 s37, s12, 0xfff80080
	s_addc_u32 s38, s13, -1
	s_add_i32 s46, 0, 0x10000
	v_add_u32_e32 v162, s46, v170
	ds_read_b128 v[150:153], v162
	ds_read_b128 v[154:157], v162 offset:1024
	ds_read_b128 v[158:161], v162 offset:2048
	ds_read_b128 v[162:165], v162 offset:3072
	s_cmp_eq_u32 s36, 28
	s_cselect_b32 s55, s1, s38
	s_cselect_b32 s54, s25, s37
	s_cselect_b32 s53, s23, s30
	s_cselect_b32 s52, s28, s29
	ds_read_b128 v[186:189], v176
	ds_read_b128 v[190:193], v176 offset:1024
	ds_read_b128 v[194:197], v176 offset:2048
	ds_read_b128 v[198:201], v176 offset:3072
	ds_read_b128 v[202:205], v176 offset:4096
	ds_read_b128 v[206:209], v176 offset:5120
	ds_read_b128 v[210:213], v176 offset:6144
	ds_read_b128 v[214:217], v176 offset:7168
	s_mov_b32 s98, 0xfff80000
	s_mov_b32 s99, -1
	v_lshl_add_u64 v[232:233], s[12:13], 0, v[146:147]
	v_lshl_add_u64 v[232:233], v[232:233], 0, s[98:99]
	s_mov_b32 m0, s70
	s_nop 0
	global_load_lds_dwordx4 v[232:233], off
	v_lshl_add_u64 v[232:233], s[12:13], 0, v[148:149]
	v_lshl_add_u64 v[232:233], v[232:233], 0, s[98:99]
	s_mov_b32 m0, s71
	s_nop 0
	global_load_lds_dwordx4 v[232:233], off
	v_lshl_add_u64 v[232:233], s[12:13], 0, v[146:147]
	s_add_i32 m0, s63, 0xc000
	s_nop 0
	global_load_lds_dwordx4 v[232:233], off
	v_lshl_add_u64 v[232:233], s[12:13], 0, v[148:149]
	s_add_i32 m0, s63, 0xe000
	s_nop 0
	global_load_lds_dwordx4 v[232:233], off
	s_add_i32 s37, 0, 0x14000
	v_add_u32_e32 v166, s37, v170
	ds_read_b128 v[218:221], v166
	ds_read_b128 v[222:225], v166 offset:1024
	ds_read_b128 v[226:229], v166 offset:2048
	ds_read_b128 v[244:247], v166 offset:3072
	s_waitcnt lgkmcnt(0)
	s_barrier
	v_mfma_f32_16x16x32_bf16 v[126:129], v[150:153], v[186:189], v[126:129]
	v_mfma_f32_16x16x32_bf16 v[126:129], v[154:157], v[190:193], v[126:129]
	v_mfma_f32_16x16x32_bf16 v[110:113], v[150:153], v[194:197], v[110:113]
	v_mfma_f32_16x16x32_bf16 v[110:113], v[154:157], v[198:201], v[110:113]
	v_mfma_f32_16x16x32_bf16 v[94:97], v[150:153], v[202:205], v[94:97]
	v_mfma_f32_16x16x32_bf16 v[94:97], v[154:157], v[206:209], v[94:97]
	v_mfma_f32_16x16x32_bf16 v[78:81], v[150:153], v[210:213], v[78:81]
	v_mfma_f32_16x16x32_bf16 v[78:81], v[154:157], v[214:217], v[78:81]
	v_mfma_f32_16x16x32_bf16 v[122:125], v[158:161], v[186:189], v[122:125]
	v_mfma_f32_16x16x32_bf16 v[122:125], v[162:165], v[190:193], v[122:125]
	v_mfma_f32_16x16x32_bf16 v[106:109], v[158:161], v[194:197], v[106:109]
	v_mfma_f32_16x16x32_bf16 v[106:109], v[162:165], v[198:201], v[106:109]
	v_mfma_f32_16x16x32_bf16 v[90:93], v[158:161], v[202:205], v[90:93]
	v_mfma_f32_16x16x32_bf16 v[90:93], v[162:165], v[206:209], v[90:93]
	v_mfma_f32_16x16x32_bf16 v[74:77], v[158:161], v[210:213], v[74:77]
	v_mfma_f32_16x16x32_bf16 v[74:77], v[162:165], v[214:217], v[74:77]
	v_mfma_f32_16x16x32_bf16 v[118:121], v[218:221], v[186:189], v[118:121]
	v_mfma_f32_16x16x32_bf16 v[118:121], v[222:225], v[190:193], v[118:121]
	v_mfma_f32_16x16x32_bf16 v[102:105], v[218:221], v[194:197], v[102:105]
	v_mfma_f32_16x16x32_bf16 v[102:105], v[222:225], v[198:201], v[102:105]
	v_mfma_f32_16x16x32_bf16 v[86:89], v[218:221], v[202:205], v[86:89]
	v_mfma_f32_16x16x32_bf16 v[86:89], v[222:225], v[206:209], v[86:89]
	v_mfma_f32_16x16x32_bf16 v[70:73], v[218:221], v[210:213], v[70:73]
	v_mfma_f32_16x16x32_bf16 v[70:73], v[222:225], v[214:217], v[70:73]
	v_mfma_f32_16x16x32_bf16 v[114:117], v[226:229], v[186:189], v[114:117]
	v_mfma_f32_16x16x32_bf16 v[114:117], v[244:247], v[190:193], v[114:117]
	v_mfma_f32_16x16x32_bf16 v[98:101], v[226:229], v[194:197], v[98:101]
	v_mfma_f32_16x16x32_bf16 v[98:101], v[244:247], v[198:201], v[98:101]
	v_mfma_f32_16x16x32_bf16 v[82:85], v[226:229], v[202:205], v[82:85]
	v_mfma_f32_16x16x32_bf16 v[82:85], v[244:247], v[206:209], v[82:85]
	v_mfma_f32_16x16x32_bf16 v[66:69], v[226:229], v[210:213], v[66:69]
	v_mfma_f32_16x16x32_bf16 v[66:69], v[244:247], v[214:217], v[66:69]
	s_barrier
	ds_read_b128 v[186:189], v176 offset:16384
	ds_read_b128 v[190:193], v176 offset:17408
	ds_read_b128 v[194:197], v176 offset:18432
	ds_read_b128 v[198:201], v176 offset:19456
	ds_read_b128 v[202:205], v176 offset:20480
	ds_read_b128 v[206:209], v176 offset:21504
	ds_read_b128 v[210:213], v176 offset:22528
	ds_read_b128 v[214:217], v176 offset:23552
	s_add_i32 s38, s46, s62
	v_lshl_add_u64 v[166:167], s[52:53], 0, v[134:135]
	s_mov_b32 m0, s38
	v_lshl_add_u64 v[182:183], s[52:53], 0, v[130:131]
	global_load_lds_dwordx4 v[166:167], off
	s_add_i32 m0, s38, 0x2000
	s_nop 0
	global_load_lds_dwordx4 v[182:183], off
	s_add_u32 s76, s52, 0x80000
	s_addc_u32 s77, s53, 0
	s_add_i32 s37, s37, s62
	v_lshl_add_u64 v[234:235], s[76:77], 0, v[134:135]
	s_mov_b32 m0, s37
	s_nop 0
	global_load_lds_dwordx4 v[234:235], off
	v_lshl_add_u64 v[234:235], s[76:77], 0, v[130:131]
	s_add_i32 m0, s37, 0x2000
	s_nop 0
	global_load_lds_dwordx4 v[234:235], off
	s_waitcnt vmcnt(4)
	s_waitcnt lgkmcnt(0)
	s_barrier
; #define PG8_STAGE(bufoff, gbase, voff) do { _Pragma("unroll") for (int _i = 0; _i < 2; ++_i) \
;         __builtin_amdgcn_global_load_lds((const unsigned*)((const char*)(gbase) + (voff)[_i]), (LAS unsigned*)(lds + (bufoff) + ldsw + _i * 8192), 16, 0, 0); } while (0)
; #define PG8_LDA(dst, b, h) do { _Pragma("unroll") for (int m = 0; m < 4; ++m) _Pragma("unroll") for (int k = 0; k < 2; ++k) dst[m][k] = *(const LAS bf16x8*)(lds + PG8_SA(b, h) + aoff + m * 2048 + k * 1024); } while (0)
; #define PG8_LDB(dst, b, h) do { _Pragma("unroll") for (int n = 0; n < 2; ++n) _Pragma("unroll") for (int k = 0; k < 2; ++k) dst[n][k] = *(const LAS bf16x8*)(lds + PG8_SB(b, h) + boff + n * 2048 + k * 1024); } while (0)
; #define PG8_MMA(ai, bj, At, Bt) do { __builtin_amdgcn_s_setprio(1); _Pragma("unroll") for (int m = 0; m < 4; ++m) _Pragma("unroll") for (int n = 0; n < 2; ++n) _Pragma("unroll") for (int k = 0; k < 2; ++k) \
;         acc[ai][bj][m][n] = __builtin_amdgcn_mfma_f32_16x16x32_bf16(Bt[n][k], At[m][k], acc[ai][bj][m][n], 0, 0, 0); __builtin_amdgcn_s_setprio(0); } while (0)
; #define PG8_WAIT_V(n) asm volatile("s_waitcnt vmcnt(" #n ")" ::: "memory")
; #define PG8_WAIT_L(n) asm volatile("s_waitcnt lgkmcnt(" #n ")" ::: "memory")
; #define PG8_BAR __builtin_amdgcn_s_barrier()
; #define PG8_SCHED __builtin_amdgcn_sched_barrier(0)
; template <class Epi, class Sched>
; __device__ __forceinline__ void gemm_phase(LAS unsigned char* lds, const Gemm g, const Sched& S, const Epi& E) {
;     ...
;             PG8_BAR; PG8_WAIT_L(0); PG8_MMA(1, 0, At, B0); PG8_BAR; PG8_SCHED;
;             PG8_STAGE(PG8_SB(0, 1), b2 + hstepB, voffB);
;             PG8_WAIT_V(6); PG8_BAR; PG8_MMA(1, 1, At, B1); PG8_BAR;
;             PG8_LDB(B0, 1, 0); PG8_SCHED; PG8_LDA(At, 1, 0); PG8_STAGE(PG8_SA(0, 1), a2 + hstepA, voffA);
;             PG8_WAIT_L(8); PG8_BAR; PG8_WAIT_L(0); PG8_MMA(0, 0, At, B0); PG8_BAR; PG8_SCHED;
;             PG8_LDB(B1, 1, 1); PG8_STAGE(PG8_SB(1, 0), b3, voffB);
;             PG8_BAR; PG8_WAIT_L(0); PG8_MMA(0, 1, At, B1); PG8_BAR;
	v_mfma_f32_16x16x32_bf16 v[62:65], v[150:153], v[186:189], v[62:65]
	v_mfma_f32_16x16x32_bf16 v[62:65], v[154:157], v[190:193], v[62:65]
	v_mfma_f32_16x16x32_bf16 v[46:49], v[150:153], v[194:197], v[46:49]
	v_mfma_f32_16x16x32_bf16 v[46:49], v[154:157], v[198:201], v[46:49]
	v_mfma_f32_16x16x32_bf16 v[30:33], v[150:153], v[202:205], v[30:33]
	v_mfma_f32_16x16x32_bf16 v[30:33], v[154:157], v[206:209], v[30:33]
	v_mfma_f32_16x16x32_bf16 v[14:17], v[150:153], v[210:213], v[14:17]
	v_mfma_f32_16x16x32_bf16 v[14:17], v[154:157], v[214:217], v[14:17]
	v_mfma_f32_16x16x32_bf16 v[58:61], v[158:161], v[186:189], v[58:61]
	v_mfma_f32_16x16x32_bf16 v[58:61], v[162:165], v[190:193], v[58:61]
	v_mfma_f32_16x16x32_bf16 v[42:45], v[158:161], v[194:197], v[42:45]
	v_mfma_f32_16x16x32_bf16 v[42:45], v[162:165], v[198:201], v[42:45]
	v_mfma_f32_16x16x32_bf16 v[26:29], v[158:161], v[202:205], v[26:29]
	v_mfma_f32_16x16x32_bf16 v[26:29], v[162:165], v[206:209], v[26:29]
	v_mfma_f32_16x16x32_bf16 v[10:13], v[158:161], v[210:213], v[10:13]
	v_mfma_f32_16x16x32_bf16 v[10:13], v[162:165], v[214:217], v[10:13]
	v_mfma_f32_16x16x32_bf16 v[54:57], v[218:221], v[186:189], v[54:57]
	v_mfma_f32_16x16x32_bf16 v[54:57], v[222:225], v[190:193], v[54:57]
	v_mfma_f32_16x16x32_bf16 v[38:41], v[218:221], v[194:197], v[38:41]
	v_mfma_f32_16x16x32_bf16 v[38:41], v[222:225], v[198:201], v[38:41]
	v_mfma_f32_16x16x32_bf16 v[22:25], v[218:221], v[202:205], v[22:25]
	v_mfma_f32_16x16x32_bf16 v[22:25], v[222:225], v[206:209], v[22:25]
	v_mfma_f32_16x16x32_bf16 v[6:9], v[218:221], v[210:213], v[6:9]
	v_mfma_f32_16x16x32_bf16 v[6:9], v[222:225], v[214:217], v[6:9]
	v_mfma_f32_16x16x32_bf16 v[50:53], v[226:229], v[186:189], v[50:53]
	v_mfma_f32_16x16x32_bf16 v[50:53], v[244:247], v[190:193], v[50:53]
	v_mfma_f32_16x16x32_bf16 v[34:37], v[226:229], v[194:197], v[34:37]
	v_mfma_f32_16x16x32_bf16 v[34:37], v[244:247], v[198:201], v[34:37]
	v_mfma_f32_16x16x32_bf16 v[18:21], v[226:229], v[202:205], v[18:21]
	v_mfma_f32_16x16x32_bf16 v[18:21], v[244:247], v[206:209], v[18:21]
	v_mfma_f32_16x16x32_bf16 v[2:5], v[226:229], v[210:213], v[2:5]
	v_mfma_f32_16x16x32_bf16 v[2:5], v[244:247], v[214:217], v[2:5]
	s_add_i32 s37, 0, 0x18000
	v_add_u32_e32 v162, s37, v170
	s_barrier
	ds_read_b128 v[150:153], v162
	ds_read_b128 v[154:157], v162 offset:1024
	ds_read_b128 v[158:161], v162 offset:2048
	ds_read_b128 v[162:165], v162 offset:3072
	ds_read_b128 v[186:189], v176 offset:32768
	ds_read_b128 v[190:193], v176 offset:33792
	ds_read_b128 v[194:197], v176 offset:34816
	ds_read_b128 v[198:201], v176 offset:35840
	ds_read_b128 v[202:205], v176 offset:36864
	ds_read_b128 v[206:209], v176 offset:37888
	ds_read_b128 v[210:213], v176 offset:38912
	ds_read_b128 v[214:217], v176 offset:39936
	s_mov_b32 m0, s63
	v_lshl_add_u64 v[184:185], s[54:55], 0, v[136:137]
	global_load_lds_dwordx4 v[184:185], off
	v_lshl_add_u64 v[230:231], s[54:55], 0, v[132:133]
	s_mov_b32 m0, s66
	s_nop 0
	global_load_lds_dwordx4 v[230:231], off
	s_add_u32 s54, s54, 0x80000
	s_addc_u32 s55, s55, 0
	s_mov_b32 m0, s67
	v_lshl_add_u64 v[236:237], s[54:55], 0, v[136:137]
	global_load_lds_dwordx4 v[236:237], off
	v_lshl_add_u64 v[236:237], s[54:55], 0, v[132:133]
	s_mov_b32 m0, s68
	s_nop 0
	global_load_lds_dwordx4 v[236:237], off
	s_add_i32 s38, 0, 0x1c000
	v_add_u32_e32 v177, s38, v170
	ds_read_b128 v[218:221], v177
	ds_read_b128 v[222:225], v177 offset:1024
	ds_read_b128 v[226:229], v177 offset:2048
	ds_read_b128 v[244:247], v177 offset:3072
	s_waitcnt lgkmcnt(0)
	s_barrier
	v_mfma_f32_16x16x32_bf16 v[126:129], v[150:153], v[186:189], v[126:129]
	v_mfma_f32_16x16x32_bf16 v[126:129], v[154:157], v[190:193], v[126:129]
	v_mfma_f32_16x16x32_bf16 v[110:113], v[150:153], v[194:197], v[110:113]
	v_mfma_f32_16x16x32_bf16 v[110:113], v[154:157], v[198:201], v[110:113]
	v_mfma_f32_16x16x32_bf16 v[94:97], v[150:153], v[202:205], v[94:97]
	v_mfma_f32_16x16x32_bf16 v[94:97], v[154:157], v[206:209], v[94:97]
	v_mfma_f32_16x16x32_bf16 v[78:81], v[150:153], v[210:213], v[78:81]
	v_mfma_f32_16x16x32_bf16 v[78:81], v[154:157], v[214:217], v[78:81]
	v_mfma_f32_16x16x32_bf16 v[122:125], v[158:161], v[186:189], v[122:125]
	v_mfma_f32_16x16x32_bf16 v[122:125], v[162:165], v[190:193], v[122:125]
	v_mfma_f32_16x16x32_bf16 v[106:109], v[158:161], v[194:197], v[106:109]
	v_mfma_f32_16x16x32_bf16 v[106:109], v[162:165], v[198:201], v[106:109]
	v_mfma_f32_16x16x32_bf16 v[90:93], v[158:161], v[202:205], v[90:93]
	v_mfma_f32_16x16x32_bf16 v[90:93], v[162:165], v[206:209], v[90:93]
	v_mfma_f32_16x16x32_bf16 v[74:77], v[158:161], v[210:213], v[74:77]
	v_mfma_f32_16x16x32_bf16 v[74:77], v[162:165], v[214:217], v[74:77]
	v_mfma_f32_16x16x32_bf16 v[118:121], v[218:221], v[186:189], v[118:121]
	v_mfma_f32_16x16x32_bf16 v[118:121], v[222:225], v[190:193], v[118:121]
	v_mfma_f32_16x16x32_bf16 v[102:105], v[218:221], v[194:197], v[102:105]
	v_mfma_f32_16x16x32_bf16 v[102:105], v[222:225], v[198:201], v[102:105]
	v_mfma_f32_16x16x32_bf16 v[86:89], v[218:221], v[202:205], v[86:89]
	v_mfma_f32_16x16x32_bf16 v[86:89], v[222:225], v[206:209], v[86:89]
	v_mfma_f32_16x16x32_bf16 v[70:73], v[218:221], v[210:213], v[70:73]
	v_mfma_f32_16x16x32_bf16 v[70:73], v[222:225], v[214:217], v[70:73]
	v_mfma_f32_16x16x32_bf16 v[114:117], v[226:229], v[186:189], v[114:117]
	v_mfma_f32_16x16x32_bf16 v[114:117], v[244:247], v[190:193], v[114:117]
	v_mfma_f32_16x16x32_bf16 v[98:101], v[226:229], v[194:197], v[98:101]
	v_mfma_f32_16x16x32_bf16 v[98:101], v[244:247], v[198:201], v[98:101]
	v_mfma_f32_16x16x32_bf16 v[82:85], v[226:229], v[202:205], v[82:85]
	v_mfma_f32_16x16x32_bf16 v[82:85], v[244:247], v[206:209], v[82:85]
	v_mfma_f32_16x16x32_bf16 v[66:69], v[226:229], v[210:213], v[66:69]
	v_mfma_f32_16x16x32_bf16 v[66:69], v[244:247], v[214:217], v[66:69]
	s_barrier
;     __device__ __forceinline__ void st8(bf16_t* p, const float (&v)[8]) const { u32x4 w; w.x = cvt_pk_bf16(v[0], v[1]); w.y = cvt_pk_bf16(v[2], v[3]); w.z = cvt_pk_bf16(v[4], v[5]); w.w = cvt_pk_bf16(v[6], v[7]); __builtin_nontemporal_store(w, (u32x4*)p); }
; #define PG8_STAGE(bufoff, gbase, voff) do { _Pragma("unroll") for (int _i = 0; _i < 2; ++_i) \
;         __builtin_amdgcn_global_load_lds((const unsigned*)((const char*)(gbase) + (voff)[_i]), (LAS unsigned*)(lds + (bufoff) + ldsw + _i * 8192), 16, 0, 0); } while (0)
; #define PG8_LDA(dst, b, h) do { _Pragma("unroll") for (int m = 0; m < 4; ++m) _Pragma("unroll") for (int k = 0; k < 2; ++k) dst[m][k] = *(const LAS bf16x8*)(lds + PG8_SA(b, h) + aoff + m * 2048 + k * 1024); } while (0)
; #define PG8_BAR __builtin_amdgcn_s_barrier()
;     __device__ __forceinline__ void operator()(f32x4 (&acc)[2][2][4][2], const Unit& u, int wr, int wc, int fr, int fq) const {
;     ...
;         } else if (pn < 20 && lat) {
; #pragma unroll
;             for (int ai = 0; ai < 2; ++ai) { f32x4 c01[4], c23[4];
; #pragma unroll
;                 for (int m = 0; m < 4; ++m) { const int prow = (pmb - 1) * 4 + 2 * ai + wr, pcol = 16 * m + fr;
;                     const float2* tp = T128 + ((wc >> 1) ? pcol : prow) * 32 + 16 * (wc & 1) + 4 * fq; c01[m] = *(const f32x4*)tp; c23[m] = *(const f32x4*)(tp + 2); }
;                 __builtin_amdgcn_sched_barrier(0);
; #pragma unroll
;                 for (int m = 0; m < 4; ++m) {
;                     const float cs[4] = {c01[m][0], c01[m][2], c23[m][0], c23[m][2]}, sn[4] = {c01[m][1], c01[m][3], c23[m][1], c23[m][3]};
; #pragma unroll
;                     for (int bj = 0; bj < 2; ++bj) { float v[8];
; #pragma unroll
;                         for (int p = 0; p < 4; ++p) { const float x1 = EW_V(bj, 2 * p), x2 = EW_V(bj, 2 * p + 1); v[2 * p] = x1 * cs[p] - x2 * sn[p]; v[2 * p + 1] = x2 * cs[p] + x1 * sn[p]; }
;                         st8(EW_ZP(bj), v); } } }
; template <class Epi, class Sched>
; __device__ __forceinline__ void gemm_phase(LAS unsigned char* lds, const Gemm g, const Sched& S, const Epi& E) {
;     ...
;             PG8_LDA(At, 1, 1); PG8_STAGE(PG8_SA(1, 0), a3, voffA);
;             PG8_BAR; PG8_WAIT_L(0); PG8_MMA(1, 0, At, B0); PG8_BAR; PG8_SCHED;
;             PG8_STAGE(PG8_SB(1, 1), b3 + hstepB, voffB);
;             PG8_WAIT_V(6); PG8_BAR; PG8_MMA(1, 1, At, B1); PG8_BAR;
;         }
	ds_read_b128 v[186:189], v176 offset:49152
	ds_read_b128 v[190:193], v176 offset:50176
	ds_read_b128 v[194:197], v176 offset:51200
	ds_read_b128 v[198:201], v176 offset:52224
	ds_read_b128 v[202:205], v176 offset:53248
	ds_read_b128 v[206:209], v176 offset:54272
	ds_read_b128 v[210:213], v176 offset:55296
	ds_read_b128 v[214:217], v176 offset:56320
	s_add_i32 s37, s37, s62
	v_lshl_add_u64 v[166:167], v[166:167], 0, s[92:93]
	s_mov_b32 m0, s37
	s_nop 0
	global_load_lds_dwordx4 v[166:167], off
	v_lshl_add_u64 v[166:167], v[182:183], 0, s[92:93]
	s_add_i32 m0, s37, 0x2000
	s_nop 0
	global_load_lds_dwordx4 v[166:167], off
	s_add_u32 s52, s52, 0x80080
	s_addc_u32 s53, s53, 0
	s_add_i32 s37, s38, s62
	v_lshl_add_u64 v[238:239], s[52:53], 0, v[134:135]
	s_mov_b32 m0, s37
	s_nop 0
	global_load_lds_dwordx4 v[238:239], off
	v_lshl_add_u64 v[238:239], s[52:53], 0, v[130:131]
	s_add_i32 m0, s37, 0x2000
	s_nop 0
	global_load_lds_dwordx4 v[238:239], off
	s_waitcnt vmcnt(4)
	s_waitcnt lgkmcnt(0)
	s_barrier
	v_mfma_f32_16x16x32_bf16 v[62:65], v[150:153], v[186:189], v[62:65]
	v_mfma_f32_16x16x32_bf16 v[62:65], v[154:157], v[190:193], v[62:65]
	v_mfma_f32_16x16x32_bf16 v[46:49], v[150:153], v[194:197], v[46:49]
	v_mfma_f32_16x16x32_bf16 v[46:49], v[154:157], v[198:201], v[46:49]
	v_mfma_f32_16x16x32_bf16 v[30:33], v[150:153], v[202:205], v[30:33]
	v_mfma_f32_16x16x32_bf16 v[30:33], v[154:157], v[206:209], v[30:33]
	v_mfma_f32_16x16x32_bf16 v[14:17], v[150:153], v[210:213], v[14:17]
	v_mfma_f32_16x16x32_bf16 v[14:17], v[154:157], v[214:217], v[14:17]
	v_mfma_f32_16x16x32_bf16 v[58:61], v[158:161], v[186:189], v[58:61]
	v_mfma_f32_16x16x32_bf16 v[58:61], v[162:165], v[190:193], v[58:61]
	v_mfma_f32_16x16x32_bf16 v[42:45], v[158:161], v[194:197], v[42:45]
	v_mfma_f32_16x16x32_bf16 v[42:45], v[162:165], v[198:201], v[42:45]
	v_mfma_f32_16x16x32_bf16 v[26:29], v[158:161], v[202:205], v[26:29]
	v_mfma_f32_16x16x32_bf16 v[26:29], v[162:165], v[206:209], v[26:29]
	v_mfma_f32_16x16x32_bf16 v[10:13], v[158:161], v[210:213], v[10:13]
	v_mfma_f32_16x16x32_bf16 v[10:13], v[162:165], v[214:217], v[10:13]
	v_mfma_f32_16x16x32_bf16 v[54:57], v[218:221], v[186:189], v[54:57]
	v_mfma_f32_16x16x32_bf16 v[54:57], v[222:225], v[190:193], v[54:57]
	v_mfma_f32_16x16x32_bf16 v[38:41], v[218:221], v[194:197], v[38:41]
	v_mfma_f32_16x16x32_bf16 v[38:41], v[222:225], v[198:201], v[38:41]
	v_mfma_f32_16x16x32_bf16 v[22:25], v[218:221], v[202:205], v[22:25]
	v_mfma_f32_16x16x32_bf16 v[22:25], v[222:225], v[206:209], v[22:25]
	v_mfma_f32_16x16x32_bf16 v[6:9], v[218:221], v[210:213], v[6:9]
	v_mfma_f32_16x16x32_bf16 v[6:9], v[222:225], v[214:217], v[6:9]
	v_mfma_f32_16x16x32_bf16 v[50:53], v[226:229], v[186:189], v[50:53]
	v_mfma_f32_16x16x32_bf16 v[50:53], v[244:247], v[190:193], v[50:53]
	v_mfma_f32_16x16x32_bf16 v[34:37], v[226:229], v[194:197], v[34:37]
	v_mfma_f32_16x16x32_bf16 v[34:37], v[244:247], v[198:201], v[34:37]
	v_mfma_f32_16x16x32_bf16 v[18:21], v[226:229], v[202:205], v[18:21]
	v_mfma_f32_16x16x32_bf16 v[18:21], v[244:247], v[206:209], v[18:21]
	v_mfma_f32_16x16x32_bf16 v[2:5], v[226:229], v[210:213], v[2:5]
	v_mfma_f32_16x16x32_bf16 v[2:5], v[244:247], v[214:217], v[2:5]
	s_add_i32 s36, s36, 2
	s_add_u32 s12, s12, 0x100
	s_addc_u32 s13, s13, 0
	s_add_u32 s29, s29, 0x100
	s_addc_u32 s30, s30, 0
	s_cmp_gt_u32 s36, 29
	s_barrier
	s_cbranch_scc0 .LBB0_381
	v_lshl_add_u32 v152, s0, 8, v169
	v_mov_b64_e32 v[150:151], s[16:17]
	v_mad_i64_i32 v[150:151], s[12:13], v152, s84, v[150:151]
	s_lshl_b32 s12, s33, 8
	s_ashr_i32 s13, s12, 31
	v_lshl_add_u64 v[150:151], s[12:13], 1, v[150:151]
	v_readlane_b32 s76, v255, 26
	v_ashrrev_i32_e32 v153, 31, v152
	v_lshl_add_u64 v[150:151], v[150:151], 0, v[178:179]
	s_cmp_gt_i32 s33, 3
	s_mov_b64 s[12:13], -1
	v_readlane_b32 s77, v255, 27
	s_mov_b64 s[36:37], s[74:75]
	v_mov_b32_e32 v230, 0x3727c5ac
	s_cbranch_scc0 .LBB0_446
	s_cmp_gt_u32 s33, 7
	s_cbranch_scc0 .LBB0_443
	s_cmp_gt_u32 s33, 11
	s_cbranch_scc0 .LBB0_424
	s_mul_hi_i32 s1, s0, 0x78787879
	s_lshr_b32 s12, s1, 31
	s_ashr_i32 s1, s1, 3
	s_add_i32 s1, s1, s12
	s_mul_i32 s1, s1, 17
	s_sub_i32 s1, s0, s1
	s_cmp_lg_u32 s1, 0
	s_cselect_b64 s[28:29], -1, 0
	s_cmp_lt_u32 s33, 20
	s_cselect_b64 s[12:13], -1, 0
	s_and_b64 s[12:13], s[12:13], s[28:29]
	s_andn2_b64 vcc, exec, s[12:13]
	s_mov_b64 s[12:13], -1
	s_cbranch_vccz .LBB0_421
	s_cmp_gt_u32 s33, 23
	s_cbranch_scc0 .LBB0_418
	s_cmp_gt_u32 s33, 47
	s_cbranch_scc0 .LBB0_415
	s_andn2_b64 vcc, exec, s[4:5]
	s_cbranch_vccnz .LBB0_414
	s_lshl_b32 s23, s1, 2
	v_cndmask_b32_e64 v154, 0, 1, s[28:29]
	v_cmp_ne_u32_e64 s[12:13], 1, v154
	s_andn2_b64 vcc, exec, s[28:29]
	s_add_i32 s23, s23, s79
	s_cbranch_vccnz .LBB0_391
	v_mov_b32_e32 v154, s23
	v_cndmask_b32_e64 v154, v168, v154, s[6:7]
	v_lshlrev_b32_e32 v154, 4, v154
	v_ashrrev_i32_e32 v155, 31, v154
	v_lshl_add_u64 v[154:155], v[154:155], 3, v[138:139]
	global_load_dwordx4 v[164:167], v[154:155], off offset:16
	global_load_dwordx4 v[156:159], v[154:155], off
	s_waitcnt vmcnt(0)
	v_pk_mul_f32 v[162:163], v[122:123], v[164:165] op_sel:[1,1] op_sel_hi:[0,1]
	v_pk_mul_f32 v[184:185], v[126:127], v[156:157] op_sel:[1,1] op_sel_hi:[0,1]
	v_pk_fma_f32 v[154:155], v[126:127], v[156:157], v[184:185] op_sel_hi:[1,0,1]
	v_pk_mul_f32 v[182:183], v[126:127], v[156:157]
	v_mov_b32_e32 v154, v159
	v_pk_mul_f32 v[160:161], v[128:129], v[154:155] op_sel:[1,0] op_sel_hi:[0,0]
	v_mul_f32_e32 v154, v125, v167
	v_pk_fma_f32 v[156:157], v[128:129], v[158:159], v[160:161] op_sel_hi:[1,0,1] neg_lo:[0,0,1] neg_hi:[0,0,1]
	v_pk_fma_f32 v[158:159], v[128:129], v[158:159], v[160:161] op_sel_hi:[1,0,1]
	v_pk_fma_f32 v[160:161], v[122:123], v[164:165], v[162:163] op_sel_hi:[1,0,1] neg_lo:[0,0,1] neg_hi:[0,0,1]
	v_pk_fma_f32 v[162:163], v[122:123], v[164:165], v[162:163] op_sel_hi:[1,0,1]
	v_pk_fma_f32 v[164:165], v[124:125], v[166:167], v[154:155] op_sel_hi:[1,1,0] neg_lo:[0,0,1] neg_hi:[0,0,1]
	v_mul_f32_e32 v154, v124, v167
	v_pk_fma_f32 v[166:167], v[124:125], v[166:167], v[154:155] op_sel:[1,0,0] op_sel_hi:[0,1,0]
	v_sub_f32_e32 v154, v182, v184
	s_branch .LBB0_392

; #define PG8_STAGE(bufoff, gbase, voff) do { _Pragma("unroll") for (int _i = 0; _i < 2; ++_i) \
;         __builtin_amdgcn_global_load_lds((const unsigned*)((const char*)(gbase) + (voff)[_i]), (LAS unsigned*)(lds + (bufoff) + ldsw + _i * 8192), 16, 0, 0); } while (0)
; #define PG8_LDA(dst, b, h) do { _Pragma("unroll") for (int m = 0; m < 4; ++m) _Pragma("unroll") for (int k = 0; k < 2; ++k) dst[m][k] = *(const LAS bf16x8*)(lds + PG8_SA(b, h) + aoff + m * 2048 + k * 1024); } while (0)
; #define PG8_LDB(dst, b, h) do { _Pragma("unroll") for (int n = 0; n < 2; ++n) _Pragma("unroll") for (int k = 0; k < 2; ++k) dst[n][k] = *(const LAS bf16x8*)(lds + PG8_SB(b, h) + boff + n * 2048 + k * 1024); } while (0)
; #define PG8_MMA(ai, bj, At, Bt) do { __builtin_amdgcn_s_setprio(1); _Pragma("unroll") for (int m = 0; m < 4; ++m) _Pragma("unroll") for (int n = 0; n < 2; ++n) _Pragma("unroll") for (int k = 0; k < 2; ++k) \
;         acc[ai][bj][m][n] = __builtin_amdgcn_mfma_f32_16x16x32_bf16(Bt[n][k], At[m][k], acc[ai][bj][m][n], 0, 0, 0); __builtin_amdgcn_s_setprio(0); } while (0)
; #define PG8_WAIT_V(n) asm volatile("s_waitcnt vmcnt(" #n ")" ::: "memory")
; #define PG8_BAR __builtin_amdgcn_s_barrier()
; template <class Epi, class Sched>
; __device__ __forceinline__ void gemm_phase(LAS unsigned char* lds, const Gemm g, const Sched& S, const Epi& E) {
;     ...
;         for (int t = 0; t < ntu; t += 2) {
;             const bool last = (t == ntu - 2);
;             const char* a1 = cA + (size_t)(t + 1) * kstep;
;             const char* a2 = last ? nA : cA + (size_t)(t + 2) * kstep; const char* b2 = last ? nB : cB + (size_t)(t + 2) * kstep;
;             const char* a3 = a2 + kstep; const char* b3 = b2 + kstep;
;             if (last && has_next) S.a_ready(nxt);
;             PG8_LDB(B0, 0, 0); PG8_SCHED; PG8_LDA(At, 0, 0); PG8_STAGE(PG8_SA(1, 1), a1 + hstepA, voffA);
;             PG8_WAIT_L(8); PG8_BAR; PG8_WAIT_L(0); PG8_MMA(0, 0, At, B0); PG8_BAR; PG8_SCHED;
;             PG8_LDB(B1, 0, 1); PG8_STAGE(PG8_SB(0, 0), b2, voffB);
;             PG8_BAR; PG8_WAIT_L(0); PG8_MMA(0, 1, At, B1); PG8_BAR;
;             PG8_LDA(At, 0, 1); PG8_STAGE(PG8_SA(0, 0), a2, voffA);
;             PG8_BAR; PG8_WAIT_L(0); PG8_MMA(1, 0, At, B0); PG8_BAR; PG8_SCHED;
;             PG8_STAGE(PG8_SB(0, 1), b2 + hstepB, voffB);
;             PG8_WAIT_V(6); PG8_BAR; PG8_MMA(1, 1, At, B1); PG8_BAR;
.LBB0_571:
	s_add_u32 s6, s56, 0x100
	s_addc_u32 s7, s57, 0
	s_add_i32 s77, 0, 0x10000
	v_add_u32_e32 v142, s77, v197
	ds_read_b128 v[130:133], v142
	ds_read_b128 v[134:137], v142 offset:1024
	ds_read_b128 v[138:141], v142 offset:2048
	ds_read_b128 v[142:145], v142 offset:3072
	s_cmp_eq_u32 s76, 4
	s_cselect_b32 s63, s53, s7
	s_cselect_b32 s62, s52, s6
	s_cselect_b32 s59, s28, s51
	s_cselect_b32 s58, s29, s30
	ds_read_b128 v[164:167], v201
	ds_read_b128 v[168:171], v201 offset:1024
	ds_read_b128 v[172:175], v201 offset:2048
	ds_read_b128 v[186:189], v201 offset:3072
	ds_read_b128 v[202:205], v201 offset:4096
	ds_read_b128 v[206:209], v201 offset:5120
	ds_read_b128 v[210:213], v201 offset:6144
	ds_read_b128 v[214:217], v201 offset:7168
	s_mov_b32 s98, 0xffe7c000
	s_mov_b32 s99, -1
	v_lshl_add_u64 v[232:233], s[56:57], 0, v[160:161]
	v_lshl_add_u64 v[232:233], v[232:233], 0, s[98:99]
	s_mov_b32 m0, s66
	s_nop 0
	global_load_lds_dwordx4 v[232:233], off
	v_lshl_add_u64 v[232:233], s[56:57], 0, v[162:163]
	v_lshl_add_u64 v[232:233], v[232:233], 0, s[98:99]
	s_mov_b32 m0, s67
	s_nop 0
	global_load_lds_dwordx4 v[232:233], off
	v_lshl_add_u64 v[232:233], s[56:57], 0, v[160:161]
	s_add_i32 m0, s38, 0xc000
	s_nop 0
	global_load_lds_dwordx4 v[232:233], off
	v_lshl_add_u64 v[232:233], s[56:57], 0, v[162:163]
	s_add_i32 m0, s38, 0xe000
	s_nop 0
	global_load_lds_dwordx4 v[232:233], off
	s_add_i32 s79, 0, 0x14000
	v_add_u32_e32 v176, s79, v197
	ds_read_b128 v[218:221], v176
	ds_read_b128 v[222:225], v176 offset:1024
	ds_read_b128 v[226:229], v176 offset:2048
	ds_read_b128 v[244:247], v176 offset:3072
	s_waitcnt lgkmcnt(0)
	s_barrier
	v_mfma_f32_16x16x32_bf16 v[126:129], v[130:133], v[164:167], v[126:129]
	v_mfma_f32_16x16x32_bf16 v[126:129], v[134:137], v[168:171], v[126:129]
	v_mfma_f32_16x16x32_bf16 v[118:121], v[130:133], v[172:175], v[118:121]
	v_mfma_f32_16x16x32_bf16 v[118:121], v[134:137], v[186:189], v[118:121]
	v_mfma_f32_16x16x32_bf16 v[110:113], v[130:133], v[202:205], v[110:113]
	v_mfma_f32_16x16x32_bf16 v[110:113], v[134:137], v[206:209], v[110:113]
	v_mfma_f32_16x16x32_bf16 v[102:105], v[130:133], v[210:213], v[102:105]
	v_mfma_f32_16x16x32_bf16 v[102:105], v[134:137], v[214:217], v[102:105]
	v_mfma_f32_16x16x32_bf16 v[122:125], v[138:141], v[164:167], v[122:125]
	v_mfma_f32_16x16x32_bf16 v[122:125], v[142:145], v[168:171], v[122:125]
	v_mfma_f32_16x16x32_bf16 v[114:117], v[138:141], v[172:175], v[114:117]
	v_mfma_f32_16x16x32_bf16 v[114:117], v[142:145], v[186:189], v[114:117]
	v_mfma_f32_16x16x32_bf16 v[106:109], v[138:141], v[202:205], v[106:109]
	v_mfma_f32_16x16x32_bf16 v[106:109], v[142:145], v[206:209], v[106:109]
	v_mfma_f32_16x16x32_bf16 v[98:101], v[138:141], v[210:213], v[98:101]
	v_mfma_f32_16x16x32_bf16 v[98:101], v[142:145], v[214:217], v[98:101]
	v_mfma_f32_16x16x32_bf16 v[94:97], v[218:221], v[164:167], v[94:97]
	v_mfma_f32_16x16x32_bf16 v[94:97], v[222:225], v[168:171], v[94:97]
	v_mfma_f32_16x16x32_bf16 v[86:89], v[218:221], v[172:175], v[86:89]
	v_mfma_f32_16x16x32_bf16 v[86:89], v[222:225], v[186:189], v[86:89]
	v_mfma_f32_16x16x32_bf16 v[78:81], v[218:221], v[202:205], v[78:81]
	v_mfma_f32_16x16x32_bf16 v[78:81], v[222:225], v[206:209], v[78:81]
	v_mfma_f32_16x16x32_bf16 v[70:73], v[218:221], v[210:213], v[70:73]
	v_mfma_f32_16x16x32_bf16 v[70:73], v[222:225], v[214:217], v[70:73]
	v_mfma_f32_16x16x32_bf16 v[90:93], v[226:229], v[164:167], v[90:93]
	v_mfma_f32_16x16x32_bf16 v[90:93], v[244:247], v[168:171], v[90:93]
	v_mfma_f32_16x16x32_bf16 v[82:85], v[226:229], v[172:175], v[82:85]
	v_mfma_f32_16x16x32_bf16 v[82:85], v[244:247], v[186:189], v[82:85]
	v_mfma_f32_16x16x32_bf16 v[74:77], v[226:229], v[202:205], v[74:77]
	v_mfma_f32_16x16x32_bf16 v[74:77], v[244:247], v[206:209], v[74:77]
	v_mfma_f32_16x16x32_bf16 v[66:69], v[226:229], v[210:213], v[66:69]
	v_mfma_f32_16x16x32_bf16 v[66:69], v[244:247], v[214:217], v[66:69]
	s_barrier
	ds_read_b128 v[164:167], v201 offset:16384
	ds_read_b128 v[168:171], v201 offset:17408
	ds_read_b128 v[172:175], v201 offset:18432
	ds_read_b128 v[186:189], v201 offset:19456
	ds_read_b128 v[202:205], v201 offset:20480
	ds_read_b128 v[206:209], v201 offset:21504
	ds_read_b128 v[210:213], v201 offset:22528
	ds_read_b128 v[214:217], v201 offset:23552
	s_add_i32 s56, s77, s33
	v_lshl_add_u64 v[176:177], s[58:59], 0, v[152:153]
	s_mov_b32 m0, s56
	v_lshl_add_u64 v[182:183], s[58:59], 0, v[148:149]
	global_load_lds_dwordx4 v[176:177], off
	s_add_i32 m0, s56, 0x2000
	s_nop 0
	global_load_lds_dwordx4 v[182:183], off
	s_add_u32 s56, s58, 0x20000
	s_addc_u32 s57, s59, 0
	s_add_i32 s77, s79, s33
	v_lshl_add_u64 v[234:235], s[56:57], 0, v[152:153]
	s_mov_b32 m0, s77
	s_nop 0
	global_load_lds_dwordx4 v[234:235], off
	v_lshl_add_u64 v[234:235], s[56:57], 0, v[148:149]
	s_add_i32 m0, s77, 0x2000
	s_nop 0
	global_load_lds_dwordx4 v[234:235], off
	s_waitcnt vmcnt(4)
	s_waitcnt lgkmcnt(0)
	s_barrier
; #define PG8_STAGE(bufoff, gbase, voff) do { _Pragma("unroll") for (int _i = 0; _i < 2; ++_i) \
;         __builtin_amdgcn_global_load_lds((const unsigned*)((const char*)(gbase) + (voff)[_i]), (LAS unsigned*)(lds + (bufoff) + ldsw + _i * 8192), 16, 0, 0); } while (0)
; #define PG8_LDA(dst, b, h) do { _Pragma("unroll") for (int m = 0; m < 4; ++m) _Pragma("unroll") for (int k = 0; k < 2; ++k) dst[m][k] = *(const LAS bf16x8*)(lds + PG8_SA(b, h) + aoff + m * 2048 + k * 1024); } while (0)
; #define PG8_LDB(dst, b, h) do { _Pragma("unroll") for (int n = 0; n < 2; ++n) _Pragma("unroll") for (int k = 0; k < 2; ++k) dst[n][k] = *(const LAS bf16x8*)(lds + PG8_SB(b, h) + boff + n * 2048 + k * 1024); } while (0)
; #define PG8_MMA(ai, bj, At, Bt) do { __builtin_amdgcn_s_setprio(1); _Pragma("unroll") for (int m = 0; m < 4; ++m) _Pragma("unroll") for (int n = 0; n < 2; ++n) _Pragma("unroll") for (int k = 0; k < 2; ++k) \
;         acc[ai][bj][m][n] = __builtin_amdgcn_mfma_f32_16x16x32_bf16(Bt[n][k], At[m][k], acc[ai][bj][m][n], 0, 0, 0); __builtin_amdgcn_s_setprio(0); } while (0)
; #define PG8_WAIT_V(n) asm volatile("s_waitcnt vmcnt(" #n ")" ::: "memory")
; #define PG8_WAIT_L(n) asm volatile("s_waitcnt lgkmcnt(" #n ")" ::: "memory")
; #define PG8_BAR __builtin_amdgcn_s_barrier()
; #define PG8_SCHED __builtin_amdgcn_sched_barrier(0)
; template <class Epi, class Sched>
; __device__ __forceinline__ void gemm_phase(LAS unsigned char* lds, const Gemm g, const Sched& S, const Epi& E) {
;     ...
;             PG8_BAR; PG8_WAIT_L(0); PG8_MMA(1, 0, At, B0); PG8_BAR; PG8_SCHED;
;             PG8_STAGE(PG8_SB(0, 1), b2 + hstepB, voffB);
;             PG8_WAIT_V(6); PG8_BAR; PG8_MMA(1, 1, At, B1); PG8_BAR;
;             PG8_LDB(B0, 1, 0); PG8_SCHED; PG8_LDA(At, 1, 0); PG8_STAGE(PG8_SA(0, 1), a2 + hstepA, voffA);
;             PG8_WAIT_L(8); PG8_BAR; PG8_WAIT_L(0); PG8_MMA(0, 0, At, B0); PG8_BAR; PG8_SCHED;
;             PG8_LDB(B1, 1, 1); PG8_STAGE(PG8_SB(1, 0), b3, voffB);
;             PG8_BAR; PG8_WAIT_L(0); PG8_MMA(0, 1, At, B1); PG8_BAR;
	v_mfma_f32_16x16x32_bf16 v[62:65], v[130:133], v[164:167], v[62:65]
	v_mfma_f32_16x16x32_bf16 v[62:65], v[134:137], v[168:171], v[62:65]
	v_mfma_f32_16x16x32_bf16 v[54:57], v[130:133], v[172:175], v[54:57]
	v_mfma_f32_16x16x32_bf16 v[54:57], v[134:137], v[186:189], v[54:57]
	v_mfma_f32_16x16x32_bf16 v[46:49], v[130:133], v[202:205], v[46:49]
	v_mfma_f32_16x16x32_bf16 v[46:49], v[134:137], v[206:209], v[46:49]
	v_mfma_f32_16x16x32_bf16 v[38:41], v[130:133], v[210:213], v[38:41]
	v_mfma_f32_16x16x32_bf16 v[38:41], v[134:137], v[214:217], v[38:41]
	v_mfma_f32_16x16x32_bf16 v[58:61], v[138:141], v[164:167], v[58:61]
	v_mfma_f32_16x16x32_bf16 v[58:61], v[142:145], v[168:171], v[58:61]
	v_mfma_f32_16x16x32_bf16 v[50:53], v[138:141], v[172:175], v[50:53]
	v_mfma_f32_16x16x32_bf16 v[50:53], v[142:145], v[186:189], v[50:53]
	v_mfma_f32_16x16x32_bf16 v[42:45], v[138:141], v[202:205], v[42:45]
	v_mfma_f32_16x16x32_bf16 v[42:45], v[142:145], v[206:209], v[42:45]
	v_mfma_f32_16x16x32_bf16 v[34:37], v[138:141], v[210:213], v[34:37]
	v_mfma_f32_16x16x32_bf16 v[34:37], v[142:145], v[214:217], v[34:37]
	v_mfma_f32_16x16x32_bf16 v[30:33], v[218:221], v[164:167], v[30:33]
	v_mfma_f32_16x16x32_bf16 v[30:33], v[222:225], v[168:171], v[30:33]
	v_mfma_f32_16x16x32_bf16 v[22:25], v[218:221], v[172:175], v[22:25]
	v_mfma_f32_16x16x32_bf16 v[22:25], v[222:225], v[186:189], v[22:25]
	v_mfma_f32_16x16x32_bf16 v[14:17], v[218:221], v[202:205], v[14:17]
	v_mfma_f32_16x16x32_bf16 v[14:17], v[222:225], v[206:209], v[14:17]
	v_mfma_f32_16x16x32_bf16 v[6:9], v[218:221], v[210:213], v[6:9]
	v_mfma_f32_16x16x32_bf16 v[6:9], v[222:225], v[214:217], v[6:9]
	v_mfma_f32_16x16x32_bf16 v[26:29], v[226:229], v[164:167], v[26:29]
	v_mfma_f32_16x16x32_bf16 v[26:29], v[244:247], v[168:171], v[26:29]
	v_mfma_f32_16x16x32_bf16 v[18:21], v[226:229], v[172:175], v[18:21]
	v_mfma_f32_16x16x32_bf16 v[18:21], v[244:247], v[186:189], v[18:21]
	v_mfma_f32_16x16x32_bf16 v[10:13], v[226:229], v[202:205], v[10:13]
	v_mfma_f32_16x16x32_bf16 v[10:13], v[244:247], v[206:209], v[10:13]
	v_mfma_f32_16x16x32_bf16 v[2:5], v[226:229], v[210:213], v[2:5]
	v_mfma_f32_16x16x32_bf16 v[2:5], v[244:247], v[214:217], v[2:5]
	s_add_i32 s77, 0, 0x18000
	v_add_u32_e32 v142, s77, v197
	s_barrier
	ds_read_b128 v[130:133], v142
	ds_read_b128 v[134:137], v142 offset:1024
	ds_read_b128 v[138:141], v142 offset:2048
	ds_read_b128 v[142:145], v142 offset:3072
	ds_read_b128 v[164:167], v201 offset:32768
	ds_read_b128 v[168:171], v201 offset:33792
	ds_read_b128 v[172:175], v201 offset:34816
	ds_read_b128 v[186:189], v201 offset:35840
	ds_read_b128 v[202:205], v201 offset:36864
	ds_read_b128 v[206:209], v201 offset:37888
	ds_read_b128 v[210:213], v201 offset:38912
	ds_read_b128 v[214:217], v201 offset:39936
	s_mov_b32 m0, s38
	v_lshl_add_u64 v[184:185], s[62:63], 0, v[154:155]
	global_load_lds_dwordx4 v[184:185], off
	v_lshl_add_u64 v[190:191], s[62:63], 0, v[150:151]
	s_mov_b32 m0, s39
	s_nop 0
	global_load_lds_dwordx4 v[190:191], off
	s_add_u32 s56, s62, 0x184000
	s_addc_u32 s57, s63, 0
	s_mov_b32 m0, s46
	v_lshl_add_u64 v[236:237], s[56:57], 0, v[154:155]
	global_load_lds_dwordx4 v[236:237], off
	v_lshl_add_u64 v[236:237], s[56:57], 0, v[150:151]
	s_mov_b32 m0, s64
	s_nop 0
	global_load_lds_dwordx4 v[236:237], off
	s_add_i32 s62, 0, 0x1c000
	v_add_u32_e32 v178, s62, v197
	ds_read_b128 v[218:221], v178
	ds_read_b128 v[222:225], v178 offset:1024
	ds_read_b128 v[226:229], v178 offset:2048
	ds_read_b128 v[244:247], v178 offset:3072
	s_waitcnt lgkmcnt(0)
	s_barrier
	v_mfma_f32_16x16x32_bf16 v[126:129], v[130:133], v[164:167], v[126:129]
	v_mfma_f32_16x16x32_bf16 v[126:129], v[134:137], v[168:171], v[126:129]
	v_mfma_f32_16x16x32_bf16 v[118:121], v[130:133], v[172:175], v[118:121]
	v_mfma_f32_16x16x32_bf16 v[118:121], v[134:137], v[186:189], v[118:121]
	v_mfma_f32_16x16x32_bf16 v[110:113], v[130:133], v[202:205], v[110:113]
	v_mfma_f32_16x16x32_bf16 v[110:113], v[134:137], v[206:209], v[110:113]
	v_mfma_f32_16x16x32_bf16 v[102:105], v[130:133], v[210:213], v[102:105]
	v_mfma_f32_16x16x32_bf16 v[102:105], v[134:137], v[214:217], v[102:105]
	v_mfma_f32_16x16x32_bf16 v[122:125], v[138:141], v[164:167], v[122:125]
	v_mfma_f32_16x16x32_bf16 v[122:125], v[142:145], v[168:171], v[122:125]
	v_mfma_f32_16x16x32_bf16 v[114:117], v[138:141], v[172:175], v[114:117]
	v_mfma_f32_16x16x32_bf16 v[114:117], v[142:145], v[186:189], v[114:117]
	v_mfma_f32_16x16x32_bf16 v[106:109], v[138:141], v[202:205], v[106:109]
	v_mfma_f32_16x16x32_bf16 v[106:109], v[142:145], v[206:209], v[106:109]
	v_mfma_f32_16x16x32_bf16 v[98:101], v[138:141], v[210:213], v[98:101]
	v_mfma_f32_16x16x32_bf16 v[98:101], v[142:145], v[214:217], v[98:101]
	v_mfma_f32_16x16x32_bf16 v[94:97], v[218:221], v[164:167], v[94:97]
	v_mfma_f32_16x16x32_bf16 v[94:97], v[222:225], v[168:171], v[94:97]
	v_mfma_f32_16x16x32_bf16 v[86:89], v[218:221], v[172:175], v[86:89]
	v_mfma_f32_16x16x32_bf16 v[86:89], v[222:225], v[186:189], v[86:89]
	v_mfma_f32_16x16x32_bf16 v[78:81], v[218:221], v[202:205], v[78:81]
	v_mfma_f32_16x16x32_bf16 v[78:81], v[222:225], v[206:209], v[78:81]
	v_mfma_f32_16x16x32_bf16 v[70:73], v[218:221], v[210:213], v[70:73]
	v_mfma_f32_16x16x32_bf16 v[70:73], v[222:225], v[214:217], v[70:73]
	v_mfma_f32_16x16x32_bf16 v[90:93], v[226:229], v[164:167], v[90:93]
	v_mfma_f32_16x16x32_bf16 v[90:93], v[244:247], v[168:171], v[90:93]
	v_mfma_f32_16x16x32_bf16 v[82:85], v[226:229], v[172:175], v[82:85]
	v_mfma_f32_16x16x32_bf16 v[82:85], v[244:247], v[186:189], v[82:85]
	v_mfma_f32_16x16x32_bf16 v[74:77], v[226:229], v[202:205], v[74:77]
	v_mfma_f32_16x16x32_bf16 v[74:77], v[244:247], v[206:209], v[74:77]
	v_mfma_f32_16x16x32_bf16 v[66:69], v[226:229], v[210:213], v[66:69]
	v_mfma_f32_16x16x32_bf16 v[66:69], v[244:247], v[214:217], v[66:69]
	s_barrier
; #define PG8_STAGE(bufoff, gbase, voff) do { _Pragma("unroll") for (int _i = 0; _i < 2; ++_i) \
;         __builtin_amdgcn_global_load_lds((const unsigned*)((const char*)(gbase) + (voff)[_i]), (LAS unsigned*)(lds + (bufoff) + ldsw + _i * 8192), 16, 0, 0); } while (0)
; #define PG8_LDA(dst, b, h) do { _Pragma("unroll") for (int m = 0; m < 4; ++m) _Pragma("unroll") for (int k = 0; k < 2; ++k) dst[m][k] = *(const LAS bf16x8*)(lds + PG8_SA(b, h) + aoff + m * 2048 + k * 1024); } while (0)
; #define PG8_MMA(ai, bj, At, Bt) do { __builtin_amdgcn_s_setprio(1); _Pragma("unroll") for (int m = 0; m < 4; ++m) _Pragma("unroll") for (int n = 0; n < 2; ++n) _Pragma("unroll") for (int k = 0; k < 2; ++k) \
;         acc[ai][bj][m][n] = __builtin_amdgcn_mfma_f32_16x16x32_bf16(Bt[n][k], At[m][k], acc[ai][bj][m][n], 0, 0, 0); __builtin_amdgcn_s_setprio(0); } while (0)
; #define PG8_WAIT_V(n) asm volatile("s_waitcnt vmcnt(" #n ")" ::: "memory")
; #define PG8_WAIT_L(n) asm volatile("s_waitcnt lgkmcnt(" #n ")" ::: "memory")
; #define PG8_BAR __builtin_amdgcn_s_barrier()
; #define PG8_SCHED __builtin_amdgcn_sched_barrier(0)
;     __device__ __forceinline__ void operator()(f32x4 (&acc)[2][2][4][2], const Unit& u, int wr, int wc, int fr, int fq) const {
;         const int row0 = u.pm * BM + wr * 64 + fr;
; #pragma unroll
;         for (int ai = 0; ai < 2; ++ai) {
;             f32x4 s0[4], s1[4]; float rstd[4];
; #pragma unroll
;             for (int m = 0; m < 4; ++m) { const float* sp = SSQ + (size_t)(row0 + ai * HALF + m * 16) * 16 + 8; s0[m] = *(const f32x4*)sp; s1[m] = *(const f32x4*)(sp + 4); }
; #pragma unroll
;             for (int m = 0; m < 4; ++m) rstd[m] = rsqrtf(((s0[m][0] + s0[m][1]) + (s0[m][2] + s0[m][3]) + (s1[m][0] + s1[m][1]) + (s1[m][2] + s1[m][3])) * (1.0f / 512.0f) + EPS);
;             if (u.pn < 4) {
; template <class Epi, class Sched>
; __device__ __forceinline__ void gemm_phase(LAS unsigned char* lds, const Gemm g, const Sched& S, const Epi& E) {
;     ...
;             PG8_LDA(At, 1, 1); PG8_STAGE(PG8_SA(1, 0), a3, voffA);
;             PG8_BAR; PG8_WAIT_L(0); PG8_MMA(1, 0, At, B0); PG8_BAR; PG8_SCHED;
;             PG8_STAGE(PG8_SB(1, 1), b3 + hstepB, voffB);
;             PG8_WAIT_V(6); PG8_BAR; PG8_MMA(1, 1, At, B1); PG8_BAR;
;         }
	ds_read_b128 v[164:167], v201 offset:49152
	ds_read_b128 v[168:171], v201 offset:50176
	ds_read_b128 v[172:175], v201 offset:51200
	ds_read_b128 v[186:189], v201 offset:52224
	ds_read_b128 v[202:205], v201 offset:53248
	ds_read_b128 v[206:209], v201 offset:54272
	ds_read_b128 v[210:213], v201 offset:55296
	ds_read_b128 v[214:217], v201 offset:56320
	s_add_i32 s56, s77, s33
	v_lshl_add_u64 v[176:177], v[176:177], 0, s[92:93]
	s_mov_b32 m0, s56
	s_nop 0
	global_load_lds_dwordx4 v[176:177], off
	v_lshl_add_u64 v[176:177], v[182:183], 0, s[92:93]
	s_add_i32 m0, s56, 0x2000
	s_nop 0
	global_load_lds_dwordx4 v[176:177], off
	s_add_u32 s56, s58, 0x20080
	s_addc_u32 s57, s59, 0
	s_add_i32 s58, s62, s33
	v_lshl_add_u64 v[238:239], s[56:57], 0, v[152:153]
	s_mov_b32 m0, s58
	s_nop 0
	global_load_lds_dwordx4 v[238:239], off
	v_lshl_add_u64 v[238:239], s[56:57], 0, v[148:149]
	s_add_i32 m0, s58, 0x2000
	s_nop 0
	global_load_lds_dwordx4 v[238:239], off
	s_waitcnt vmcnt(4)
	s_waitcnt lgkmcnt(0)
	s_barrier
	v_mfma_f32_16x16x32_bf16 v[62:65], v[130:133], v[164:167], v[62:65]
	v_mfma_f32_16x16x32_bf16 v[62:65], v[134:137], v[168:171], v[62:65]
	v_mfma_f32_16x16x32_bf16 v[54:57], v[130:133], v[172:175], v[54:57]
	v_mfma_f32_16x16x32_bf16 v[54:57], v[134:137], v[186:189], v[54:57]
	v_mfma_f32_16x16x32_bf16 v[46:49], v[130:133], v[202:205], v[46:49]
	v_mfma_f32_16x16x32_bf16 v[46:49], v[134:137], v[206:209], v[46:49]
	v_mfma_f32_16x16x32_bf16 v[38:41], v[130:133], v[210:213], v[38:41]
	v_mfma_f32_16x16x32_bf16 v[38:41], v[134:137], v[214:217], v[38:41]
	v_mfma_f32_16x16x32_bf16 v[58:61], v[138:141], v[164:167], v[58:61]
	v_mfma_f32_16x16x32_bf16 v[58:61], v[142:145], v[168:171], v[58:61]
	v_mfma_f32_16x16x32_bf16 v[50:53], v[138:141], v[172:175], v[50:53]
	v_mfma_f32_16x16x32_bf16 v[50:53], v[142:145], v[186:189], v[50:53]
	v_mfma_f32_16x16x32_bf16 v[42:45], v[138:141], v[202:205], v[42:45]
	v_mfma_f32_16x16x32_bf16 v[42:45], v[142:145], v[206:209], v[42:45]
	v_mfma_f32_16x16x32_bf16 v[34:37], v[138:141], v[210:213], v[34:37]
	v_mfma_f32_16x16x32_bf16 v[34:37], v[142:145], v[214:217], v[34:37]
	v_mfma_f32_16x16x32_bf16 v[30:33], v[218:221], v[164:167], v[30:33]
	v_mfma_f32_16x16x32_bf16 v[30:33], v[222:225], v[168:171], v[30:33]
	v_mfma_f32_16x16x32_bf16 v[22:25], v[218:221], v[172:175], v[22:25]
	v_mfma_f32_16x16x32_bf16 v[22:25], v[222:225], v[186:189], v[22:25]
	v_mfma_f32_16x16x32_bf16 v[14:17], v[218:221], v[202:205], v[14:17]
	v_mfma_f32_16x16x32_bf16 v[14:17], v[222:225], v[206:209], v[14:17]
	v_mfma_f32_16x16x32_bf16 v[6:9], v[218:221], v[210:213], v[6:9]
	v_mfma_f32_16x16x32_bf16 v[6:9], v[222:225], v[214:217], v[6:9]
	v_mfma_f32_16x16x32_bf16 v[26:29], v[226:229], v[164:167], v[26:29]
	v_mfma_f32_16x16x32_bf16 v[26:29], v[244:247], v[168:171], v[26:29]
	v_mfma_f32_16x16x32_bf16 v[18:21], v[226:229], v[172:175], v[18:21]
	v_mfma_f32_16x16x32_bf16 v[18:21], v[244:247], v[186:189], v[18:21]
	v_mfma_f32_16x16x32_bf16 v[10:13], v[226:229], v[202:205], v[10:13]
	v_mfma_f32_16x16x32_bf16 v[10:13], v[244:247], v[206:209], v[10:13]
	v_mfma_f32_16x16x32_bf16 v[2:5], v[226:229], v[210:213], v[2:5]
	v_mfma_f32_16x16x32_bf16 v[2:5], v[244:247], v[214:217], v[2:5]
	s_add_i32 s76, s76, 2
	s_add_u32 s30, s30, 0x100
	s_addc_u32 s51, s51, 0
	s_cmp_gt_u32 s76, 5
	s_mov_b64 s[56:57], s[6:7]
	s_barrier
	s_cbranch_scc0 .LBB0_571
	v_lshl_add_u32 v164, s72, 8, v196
	v_ashrrev_i32_e32 v165, 31, v164
	v_lshlrev_b64 v[130:131], 6, v[164:165]
	v_readlane_b32 s76, v255, 26
	s_cmp_gt_i32 s71, 5
	v_lshl_add_u64 v[172:173], s[26:27], 0, v[130:131]
	s_mov_b64 s[6:7], -1
	v_or_b32_e32 v168, 16, v164
	v_or_b32_e32 v166, 32, v164
	v_or_b32_e32 v170, 48, v164
	v_readlane_b32 s77, v255, 27
	s_cbranch_scc0 .LBB0_582
	v_ashrrev_i32_e32 v169, 31, v168
	v_lshlrev_b64 v[130:131], 6, v[168:169]
	v_lshl_add_u64 v[130:131], s[26:27], 0, v[130:131]
	global_load_dwordx4 v[174:177], v[172:173], off offset:48
	global_load_dwordx4 v[186:189], v[172:173], off offset:32
	global_load_dwordx4 v[202:205], v[130:131], off offset:48
	global_load_dwordx4 v[206:209], v[130:131], off offset:32
	v_ashrrev_i32_e32 v167, 31, v166
	v_lshlrev_b64 v[130:131], 6, v[166:167]
	v_lshl_add_u64 v[130:131], s[26:27], 0, v[130:131]
	v_ashrrev_i32_e32 v171, 31, v170
	global_load_dwordx4 v[134:137], v[130:131], off offset:48
	global_load_dwordx4 v[138:141], v[130:131], off offset:32
	v_lshlrev_b64 v[130:131], 6, v[170:171]
	v_lshl_add_u64 v[142:143], s[26:27], 0, v[130:131]
	global_load_dwordx4 v[130:133], v[142:143], off offset:48
	s_nop 0
	global_load_dwordx4 v[142:145], v[142:143], off offset:32
	s_mov_b32 s6, 0x3727c5ac
	s_add_i32 s28, s71, -6
	s_cmp_gt_u32 s28, 3
	s_cselect_b64 s[56:57], -1, 0
	s_cmp_lt_u32 s28, 4
	v_lshl_or_b32 v178, s28, 8, v158
	s_waitcnt vmcnt(0)
; __device__ __forceinline__ unsigned cvt_pk_bf16(float lo, float hi) { const f32x2_t v = {lo, hi}; return __builtin_bit_cast(unsigned, __builtin_convertvector(v, bf16x2_t)); }
;     __device__ __forceinline__ void operator()(f32x4 (&acc)[2][2][4][2], const Unit& u, int wr, int wc, int fr, int fq) const {
;     ...
;             for (int m = 0; m < 4; ++m) { const float* sp = SSQ + (size_t)(row0 + ai * HALF + m * 16) * 16 + 8; s0[m] = *(const f32x4*)sp; s1[m] = *(const f32x4*)(sp + 4); }
; #pragma unroll
;             for (int m = 0; m < 4; ++m) rstd[m] = rsqrtf(((s0[m][0] + s0[m][1]) + (s0[m][2] + s0[m][3]) + (s1[m][0] + s1[m][1]) + (s1[m][2] + s1[m][3])) * (1.0f / 512.0f) + EPS);
;             if (u.pn < 4) {
; #pragma unroll
;                 for (int m = 0; m < 4; ++m)
; #pragma unroll
;                     for (int bj = 0; bj < 2; ++bj) { const int c0 = u.pn * BM + bj * HALF + wc * 32 + 8 * fq; const f32x4 v0 = acc[ai][bj][m][0] * rstd[m], v1 = acc[ai][bj][m][1] * rstd[m];
;                         u32x4 w; w.x = cvt_pk_bf16(v0[0], v0[1]); w.y = cvt_pk_bf16(v0[2], v0[3]); w.z = cvt_pk_bf16(v1[0], v1[1]); w.w = cvt_pk_bf16(v1[2], v1[3]);
;                         *(u32x4*)(KM + (size_t)(row0 + ai * HALF + m * 16) * 1536 + (c0 >> 7) * 192 + (c0 & 127)) = w; }
;             } else {
; #pragma unroll
;                 for (int m = 0; m < 4; ++m)
; #pragma unroll
;                     for (int bj = 0; bj < 2; ++bj) { const int c0 = u.pn * BM + bj * HALF + wc * 32 + 8 * fq; const f32x4 v0 = acc[ai][bj][m][0] * rstd[m], v1 = acc[ai][bj][m][1] * rstd[m];
;                         u32x4 w; w.x = cvt_pk_bf16(v0[0], v0[1]); w.y = cvt_pk_bf16(v0[2], v0[3]); w.z = cvt_pk_bf16(v1[0], v1[1]); w.w = cvt_pk_bf16(v1[2], v1[3]);
;                         *(u32x4*)(VM + (size_t)(row0 + ai * HALF + m * 16) * 1024 + (c0 - 1024)) = w; }
	v_mov_b32_e32 v184, v176
	v_mov_b32_e32 v182, v187
	v_mov_b32_e32 v183, v188
	v_mov_b32_e32 v187, v189
	v_mov_b32_e32 v185, v174
	v_mov_b32_e32 v174, v177
	v_mov_b32_e32 v176, v207
	v_mov_b32_e32 v177, v208
	v_mov_b32_e32 v207, v209
	v_pk_add_f32 v[182:183], v[182:183], v[186:187]
	v_pk_add_f32 v[174:175], v[184:185], v[174:175]
	v_pk_add_f32 v[176:177], v[176:177], v[206:207]
	v_mov_b32_e32 v184, v204
	v_mov_b32_e32 v185, v202
	v_mov_b32_e32 v202, v205
	v_pk_add_f32 v[184:185], v[184:185], v[202:203]
	v_mov_b32_e32 v186, v176
	v_mov_b32_e32 v187, v182
	v_mov_b32_e32 v182, v177
	v_pk_add_f32 v[176:177], v[186:187], v[182:183]
	v_mov_b32_e32 v182, v185
	v_mov_b32_e32 v183, v175
	v_pk_add_f32 v[176:177], v[176:177], v[182:183]
	v_mov_b32_e32 v185, v174
	v_pk_add_f32 v[174:175], v[184:185], v[176:177]
	v_mov_b64_e32 v[186:187], s[6:7]
	v_pk_fma_f32 v[176:177], v[174:175], s[42:43], v[186:187] op_sel_hi:[1,0,0]
	v_mov_b32_e32 v182, v139
	v_mul_f32_e32 v174, 0x4b800000, v177
	v_cmp_gt_f32_e64 s[6:7], s85, v177
	v_mov_b32_e32 v183, v140
	v_mov_b32_e32 v139, v141
	v_mov_b32_e32 v140, v136
	v_mov_b32_e32 v141, v134
	v_mov_b32_e32 v134, v137
	v_mov_b32_e32 v136, v143
	v_mov_b32_e32 v137, v144
	v_mov_b32_e32 v143, v145
	v_cndmask_b32_e64 v174, v177, v174, s[6:7]
	v_pk_add_f32 v[138:139], v[182:183], v[138:139]
	v_pk_add_f32 v[134:135], v[140:141], v[134:135]
	v_pk_add_f32 v[136:137], v[136:137], v[142:143]
	v_mov_b32_e32 v140, v132
	v_mov_b32_e32 v141, v130
	v_mov_b32_e32 v130, v133
	v_rsq_f32_e32 v174, v174
	v_pk_add_f32 v[130:131], v[140:141], v[130:131]
	v_mov_b32_e32 v132, v136
	v_mov_b32_e32 v133, v138
	v_mov_b32_e32 v138, v137
	v_pk_add_f32 v[132:133], v[132:133], v[138:139]
	v_mov_b32_e32 v136, v131
	v_mov_b32_e32 v137, v135
	v_pk_add_f32 v[132:133], v[132:133], v[136:137]
	v_mov_b32_e32 v131, v134
	v_pk_add_f32 v[130:131], v[130:131], v[132:133]
	v_mul_f32_e32 v175, 0x45800000, v174
	v_pk_fma_f32 v[130:131], v[130:131], s[42:43], v[186:187] op_sel_hi:[1,0,0]
	v_cmp_gt_f32_e32 vcc, s85, v176
	v_cndmask_b32_e64 v174, v174, v175, s[6:7]
	v_mul_f32_e32 v175, 0x4b800000, v176
	v_mul_f32_e32 v132, 0x4b800000, v131
	v_cmp_gt_f32_e64 s[6:7], s85, v131
	v_cndmask_b32_e32 v175, v176, v175, vcc
	v_rsq_f32_e32 v175, v175
	v_cndmask_b32_e64 v131, v131, v132, s[6:7]
	v_rsq_f32_e32 v131, v131
	v_mul_f32_e32 v176, 0x45800000, v175
	v_cndmask_b32_e32 v176, v175, v176, vcc
	v_mul_f32_e32 v132, 0x45800000, v131
	v_cmp_gt_f32_e32 vcc, s85, v130
	v_cndmask_b32_e64 v138, v131, v132, s[6:7]
	v_mul_f32_e32 v131, 0x4b800000, v130
	v_cndmask_b32_e32 v130, v130, v131, vcc
	v_rsq_f32_e32 v130, v130
	v_pk_mul_f32 v[132:133], v[128:129], v[174:175] op_sel_hi:[1,0]
	v_pk_mul_f32 v[134:135], v[124:125], v[174:175] op_sel_hi:[1,0]
	v_pk_mul_f32 v[136:137], v[122:123], v[174:175] op_sel_hi:[1,0]
	v_mul_f32_e32 v131, 0x45800000, v130
	v_cndmask_b32_e32 v140, v130, v131, vcc
	v_pk_mul_f32 v[130:131], v[126:127], v[174:175] op_sel_hi:[1,0]
	v_pk_mul_f32 v[142:143], v[92:93], v[174:175] op_sel_hi:[1,0]
	v_cvt_pk_bf16_f32 v130, v130, v131
	v_cvt_pk_bf16_f32 v131, v132, v133
	v_cvt_pk_bf16_f32 v132, v136, v137
	v_cvt_pk_bf16_f32 v133, v134, v135
	v_pk_mul_f32 v[136:137], v[96:97], v[174:175] op_sel_hi:[1,0]
	v_pk_mul_f32 v[134:135], v[94:95], v[174:175] op_sel_hi:[1,0]
	v_pk_mul_f32 v[144:145], v[90:91], v[174:175] op_sel_hi:[1,0]
	v_cvt_pk_bf16_f32 v134, v134, v135
	v_cvt_pk_bf16_f32 v135, v136, v137
	v_cvt_pk_bf16_f32 v136, v144, v145
	v_cvt_pk_bf16_f32 v137, v142, v143
	s_mov_b64 s[6:7], -1
	s_cbranch_scc1 .LBB0_575
; __device__ __forceinline__ unsigned cvt_pk_bf16(float lo, float hi) { const f32x2_t v = {lo, hi}; return __builtin_bit_cast(unsigned, __builtin_convertvector(v, bf16x2_t)); }
;     __device__ __forceinline__ void operator()(f32x4 (&acc)[2][2][4][2], const Unit& u, int wr, int wc, int fr, int fq) const {
;     ...
;             } else {
; #pragma unroll
;                 for (int m = 0; m < 4; ++m)
; #pragma unroll
;                     for (int bj = 0; bj < 2; ++bj) { const int c0 = u.pn * BM + bj * HALF + wc * 32 + 8 * fq; const f32x4 v0 = acc[ai][bj][m][0] * rstd[m], v1 = acc[ai][bj][m][1] * rstd[m];
;                         u32x4 w; w.x = cvt_pk_bf16(v0[0], v0[1]); w.y = cvt_pk_bf16(v0[2], v0[3]); w.z = cvt_pk_bf16(v1[0], v1[1]); w.w = cvt_pk_bf16(v1[2], v1[3]);
;                         *(u32x4*)(VM + (size_t)(row0 + ai * HALF + m * 16) * 1024 + (c0 - 1024)) = w; }
;             }
	v_lshlrev_b64 v[142:143], 11, v[164:165]
	v_lshl_add_u64 v[142:143], s[24:25], 0, v[142:143]
	v_lshlrev_b64 v[174:175], 1, v[178:179]
	v_lshl_add_u64 v[142:143], v[142:143], 0, v[174:175]
	v_lshlrev_b64 v[182:183], 11, v[168:169]
	global_store_dwordx4 v[142:143], v[130:133], off offset:-2048
	global_store_dwordx4 v[142:143], v[134:137], off offset:-1792
	v_pk_mul_f32 v[144:145], v[120:121], v[176:177] op_sel_hi:[1,0]
	v_pk_mul_f32 v[142:143], v[118:119], v[176:177] op_sel_hi:[1,0]
	v_pk_mul_f32 v[184:185], v[116:117], v[176:177] op_sel_hi:[1,0]
	v_pk_mul_f32 v[186:187], v[114:115], v[176:177] op_sel_hi:[1,0]
	v_lshl_add_u64 v[182:183], s[24:25], 0, v[182:183]
	v_cvt_pk_bf16_f32 v142, v142, v143
	v_cvt_pk_bf16_f32 v143, v144, v145
	v_cvt_pk_bf16_f32 v144, v186, v187
	v_cvt_pk_bf16_f32 v145, v184, v185
	v_lshl_add_u64 v[182:183], v[182:183], 0, v[174:175]
	global_store_dwordx4 v[182:183], v[142:145], off offset:-2048
	v_pk_mul_f32 v[184:185], v[84:85], v[176:177] op_sel_hi:[1,0]
	v_pk_mul_f32 v[186:187], v[82:83], v[176:177] op_sel_hi:[1,0]
	v_pk_mul_f32 v[144:145], v[88:89], v[176:177] op_sel_hi:[1,0]
	v_pk_mul_f32 v[142:143], v[86:87], v[176:177] op_sel_hi:[1,0]
	s_mov_b64 s[6:7], 0
	v_cvt_pk_bf16_f32 v142, v142, v143
	v_cvt_pk_bf16_f32 v143, v144, v145
	v_cvt_pk_bf16_f32 v144, v186, v187
	v_cvt_pk_bf16_f32 v145, v184, v185
	global_store_dwordx4 v[182:183], v[142:145], off offset:-1792
	v_lshlrev_b64 v[182:183], 11, v[166:167]
	v_pk_mul_f32 v[184:185], v[108:109], v[138:139] op_sel_hi:[1,0]
	v_pk_mul_f32 v[144:145], v[112:113], v[138:139] op_sel_hi:[1,0]
	v_pk_mul_f32 v[142:143], v[110:111], v[138:139] op_sel_hi:[1,0]
	v_pk_mul_f32 v[186:187], v[106:107], v[138:139] op_sel_hi:[1,0]
	v_lshl_add_u64 v[182:183], s[24:25], 0, v[182:183]
	v_cvt_pk_bf16_f32 v142, v142, v143
	v_cvt_pk_bf16_f32 v143, v144, v145
	v_cvt_pk_bf16_f32 v144, v186, v187
	v_cvt_pk_bf16_f32 v145, v184, v185
	v_lshl_add_u64 v[182:183], v[182:183], 0, v[174:175]
	global_store_dwordx4 v[182:183], v[142:145], off offset:-2048
	v_pk_mul_f32 v[184:185], v[76:77], v[138:139] op_sel_hi:[1,0]
	v_pk_mul_f32 v[186:187], v[74:75], v[138:139] op_sel_hi:[1,0]
	v_pk_mul_f32 v[144:145], v[80:81], v[138:139] op_sel_hi:[1,0]
	v_pk_mul_f32 v[142:143], v[78:79], v[138:139] op_sel_hi:[1,0]
	s_nop 0
	v_cvt_pk_bf16_f32 v142, v142, v143
	v_cvt_pk_bf16_f32 v143, v144, v145
	v_cvt_pk_bf16_f32 v144, v186, v187
	v_cvt_pk_bf16_f32 v145, v184, v185
	global_store_dwordx4 v[182:183], v[142:145], off offset:-1792
	v_lshlrev_b64 v[182:183], 11, v[170:171]
	v_pk_mul_f32 v[184:185], v[100:101], v[140:141] op_sel_hi:[1,0]
	v_pk_mul_f32 v[144:145], v[104:105], v[140:141] op_sel_hi:[1,0]
	v_pk_mul_f32 v[142:143], v[102:103], v[140:141] op_sel_hi:[1,0]
	v_pk_mul_f32 v[186:187], v[98:99], v[140:141] op_sel_hi:[1,0]
	v_lshl_add_u64 v[182:183], s[24:25], 0, v[182:183]
	v_cvt_pk_bf16_f32 v142, v142, v143
	v_cvt_pk_bf16_f32 v143, v144, v145
	v_cvt_pk_bf16_f32 v144, v186, v187
	v_cvt_pk_bf16_f32 v145, v184, v185
	v_lshl_add_u64 v[174:175], v[182:183], 0, v[174:175]
	global_store_dwordx4 v[174:175], v[142:145], off offset:-2048
	v_pk_mul_f32 v[182:183], v[68:69], v[140:141] op_sel_hi:[1,0]
	v_pk_mul_f32 v[184:185], v[66:67], v[140:141] op_sel_hi:[1,0]
	v_pk_mul_f32 v[144:145], v[72:73], v[140:141] op_sel_hi:[1,0]
	v_pk_mul_f32 v[142:143], v[70:71], v[140:141] op_sel_hi:[1,0]
	s_nop 0
	v_cvt_pk_bf16_f32 v142, v142, v143
	v_cvt_pk_bf16_f32 v143, v144, v145
	v_cvt_pk_bf16_f32 v144, v184, v185
	v_cvt_pk_bf16_f32 v145, v182, v183
	global_store_dwordx4 v[174:175], v[142:145], off offset:-1792

; #define PG8_STAGE(bufoff, gbase, voff) do { _Pragma("unroll") for (int _i = 0; _i < 2; ++_i) \
;         __builtin_amdgcn_global_load_lds((const unsigned*)((const char*)(gbase) + (voff)[_i]), (LAS unsigned*)(lds + (bufoff) + ldsw + _i * 8192), 16, 0, 0); } while (0)
; #define PG8_LDA(dst, b, h) do { _Pragma("unroll") for (int m = 0; m < 4; ++m) _Pragma("unroll") for (int k = 0; k < 2; ++k) dst[m][k] = *(const LAS bf16x8*)(lds + PG8_SA(b, h) + aoff + m * 2048 + k * 1024); } while (0)
; #define PG8_LDB(dst, b, h) do { _Pragma("unroll") for (int n = 0; n < 2; ++n) _Pragma("unroll") for (int k = 0; k < 2; ++k) dst[n][k] = *(const LAS bf16x8*)(lds + PG8_SB(b, h) + boff + n * 2048 + k * 1024); } while (0)
; #define PG8_MMA(ai, bj, At, Bt) do { __builtin_amdgcn_s_setprio(1); _Pragma("unroll") for (int m = 0; m < 4; ++m) _Pragma("unroll") for (int n = 0; n < 2; ++n) _Pragma("unroll") for (int k = 0; k < 2; ++k) \
;         acc[ai][bj][m][n] = __builtin_amdgcn_mfma_f32_16x16x32_bf16(Bt[n][k], At[m][k], acc[ai][bj][m][n], 0, 0, 0); __builtin_amdgcn_s_setprio(0); } while (0)
; #define PG8_WAIT_V(n) asm volatile("s_waitcnt vmcnt(" #n ")" ::: "memory")
; #define PG8_BAR __builtin_amdgcn_s_barrier()
; template <class Epi, class Sched>
; __device__ __forceinline__ void gemm_phase(LAS unsigned char* lds, const Gemm g, const Sched& S, const Epi& E) {
;     ...
;         for (int t = 0; t < ntu; t += 2) {
;             const bool last = (t == ntu - 2);
;             const char* a1 = cA + (size_t)(t + 1) * kstep;
;             const char* a2 = last ? nA : cA + (size_t)(t + 2) * kstep; const char* b2 = last ? nB : cB + (size_t)(t + 2) * kstep;
;             const char* a3 = a2 + kstep; const char* b3 = b2 + kstep;
;             if (last && has_next) S.a_ready(nxt);
;             PG8_LDB(B0, 0, 0); PG8_SCHED; PG8_LDA(At, 0, 0); PG8_STAGE(PG8_SA(1, 1), a1 + hstepA, voffA);
;             PG8_WAIT_L(8); PG8_BAR; PG8_WAIT_L(0); PG8_MMA(0, 0, At, B0); PG8_BAR; PG8_SCHED;
;             PG8_LDB(B1, 0, 1); PG8_STAGE(PG8_SB(0, 0), b2, voffB);
;             PG8_BAR; PG8_WAIT_L(0); PG8_MMA(0, 1, At, B1); PG8_BAR;
;             PG8_LDA(At, 0, 1); PG8_STAGE(PG8_SA(0, 0), a2, voffA);
;             PG8_BAR; PG8_WAIT_L(0); PG8_MMA(1, 0, At, B0); PG8_BAR; PG8_SCHED;
;             PG8_STAGE(PG8_SB(0, 1), b2 + hstepB, voffB);
;             PG8_WAIT_V(6); PG8_BAR; PG8_MMA(1, 1, At, B1); PG8_BAR;
.LBB0_871:
	s_add_i32 s63, s28, 2
	s_add_u32 s6, s68, 0xfffc0080
	s_addc_u32 s7, s69, -1
	s_add_i32 s35, 0, 0x10000
	v_add_u32_e32 v1, s35, v207
	ds_read_b128 v[130:133], v1
	ds_read_b128 v[134:137], v1 offset:1024
	ds_read_b128 v[138:141], v1 offset:2048
	ds_read_b128 v[142:145], v1 offset:3072
	s_cmp_eq_u32 s23, s28
	s_cselect_b32 s28, s24, s6
	s_cselect_b32 s29, s25, s7
	s_cselect_b32 s27, s13, s59
	s_cselect_b32 s26, s21, s55
	ds_read_b128 v[146:149], v209
	ds_read_b128 v[150:153], v209 offset:1024
	ds_read_b128 v[154:157], v209 offset:2048
	ds_read_b128 v[158:161], v209 offset:3072
	ds_read_b128 v[162:165], v209 offset:4096
	ds_read_b128 v[182:185], v209 offset:5120
	ds_read_b128 v[192:195], v209 offset:6144
	ds_read_b128 v[196:199], v209 offset:7168
	s_mov_b32 s98, 0xfffc0000
	s_mov_b32 s99, -1
	v_lshl_add_u64 v[232:233], s[68:69], 0, v[188:189]
	v_lshl_add_u64 v[232:233], v[232:233], 0, s[98:99]
	s_mov_b32 m0, s76
	s_nop 0
	global_load_lds_dwordx4 v[232:233], off
	v_lshl_add_u64 v[232:233], s[68:69], 0, v[190:191]
	v_lshl_add_u64 v[232:233], v[232:233], 0, s[98:99]
	s_mov_b32 m0, s77
	s_nop 0
	global_load_lds_dwordx4 v[232:233], off
	v_lshl_add_u64 v[232:233], s[68:69], 0, v[188:189]
	s_add_i32 m0, s79, 0xc000
	s_nop 0
	global_load_lds_dwordx4 v[232:233], off
	v_lshl_add_u64 v[232:233], s[68:69], 0, v[190:191]
	s_add_i32 m0, s79, 0xe000
	s_nop 0
	global_load_lds_dwordx4 v[232:233], off
	s_add_i32 s37, 0, 0x14000
	v_add_u32_e32 v1, s37, v207
	ds_read_b128 v[200:203], v1
	ds_read_b128 v[210:213], v1 offset:1024
	ds_read_b128 v[214:217], v1 offset:2048
	ds_read_b128 v[218:221], v1 offset:3072
	s_waitcnt lgkmcnt(0)
	s_barrier
	v_mfma_f32_16x16x32_bf16 v[126:129], v[130:133], v[146:149], v[126:129]
	v_mfma_f32_16x16x32_bf16 v[126:129], v[134:137], v[150:153], v[126:129]
	v_mfma_f32_16x16x32_bf16 v[118:121], v[130:133], v[154:157], v[118:121]
	v_mfma_f32_16x16x32_bf16 v[118:121], v[134:137], v[158:161], v[118:121]
	v_mfma_f32_16x16x32_bf16 v[110:113], v[130:133], v[162:165], v[110:113]
	v_mfma_f32_16x16x32_bf16 v[110:113], v[134:137], v[182:185], v[110:113]
	v_mfma_f32_16x16x32_bf16 v[102:105], v[130:133], v[192:195], v[102:105]
	v_mfma_f32_16x16x32_bf16 v[102:105], v[134:137], v[196:199], v[102:105]
	v_mfma_f32_16x16x32_bf16 v[122:125], v[138:141], v[146:149], v[122:125]
	v_mfma_f32_16x16x32_bf16 v[122:125], v[142:145], v[150:153], v[122:125]
	v_mfma_f32_16x16x32_bf16 v[114:117], v[138:141], v[154:157], v[114:117]
	v_mfma_f32_16x16x32_bf16 v[114:117], v[142:145], v[158:161], v[114:117]
	v_mfma_f32_16x16x32_bf16 v[106:109], v[138:141], v[162:165], v[106:109]
	v_mfma_f32_16x16x32_bf16 v[106:109], v[142:145], v[182:185], v[106:109]
	v_mfma_f32_16x16x32_bf16 v[98:101], v[138:141], v[192:195], v[98:101]
	v_mfma_f32_16x16x32_bf16 v[98:101], v[142:145], v[196:199], v[98:101]
	v_mfma_f32_16x16x32_bf16 v[94:97], v[200:203], v[146:149], v[94:97]
	v_mfma_f32_16x16x32_bf16 v[94:97], v[210:213], v[150:153], v[94:97]
	v_mfma_f32_16x16x32_bf16 v[86:89], v[200:203], v[154:157], v[86:89]
	v_mfma_f32_16x16x32_bf16 v[86:89], v[210:213], v[158:161], v[86:89]
	v_mfma_f32_16x16x32_bf16 v[78:81], v[200:203], v[162:165], v[78:81]
	v_mfma_f32_16x16x32_bf16 v[78:81], v[210:213], v[182:185], v[78:81]
	v_mfma_f32_16x16x32_bf16 v[70:73], v[200:203], v[192:195], v[70:73]
	v_mfma_f32_16x16x32_bf16 v[70:73], v[210:213], v[196:199], v[70:73]
	v_mfma_f32_16x16x32_bf16 v[90:93], v[214:217], v[146:149], v[90:93]
	v_mfma_f32_16x16x32_bf16 v[90:93], v[218:221], v[150:153], v[90:93]
	v_mfma_f32_16x16x32_bf16 v[82:85], v[214:217], v[154:157], v[82:85]
	v_mfma_f32_16x16x32_bf16 v[82:85], v[218:221], v[158:161], v[82:85]
	v_mfma_f32_16x16x32_bf16 v[74:77], v[214:217], v[162:165], v[74:77]
	v_mfma_f32_16x16x32_bf16 v[74:77], v[218:221], v[182:185], v[74:77]
	v_mfma_f32_16x16x32_bf16 v[66:69], v[214:217], v[192:195], v[66:69]
	v_mfma_f32_16x16x32_bf16 v[66:69], v[218:221], v[196:199], v[66:69]
	s_barrier
	ds_read_b128 v[146:149], v209 offset:16384
	ds_read_b128 v[150:153], v209 offset:17408
	ds_read_b128 v[154:157], v209 offset:18432
	ds_read_b128 v[158:161], v209 offset:19456
	ds_read_b128 v[162:165], v209 offset:20480
	ds_read_b128 v[182:185], v209 offset:21504
	ds_read_b128 v[192:195], v209 offset:22528
	ds_read_b128 v[196:199], v209 offset:23552
	s_add_i32 s6, s35, s89
	v_lshl_add_u64 v[204:205], s[26:27], 0, v[178:179]
	s_mov_b32 m0, s6
	s_nop 0
	global_load_lds_dwordx4 v[204:205], off
	v_lshl_add_u64 v[222:223], s[26:27], 0, v[172:173]
	s_add_i32 m0, s6, 0x2000
	s_nop 0
	global_load_lds_dwordx4 v[222:223], off
	s_add_u32 s6, s26, 0x40000
	s_addc_u32 s7, s27, 0
	s_add_i32 s35, s37, s89
	v_lshl_add_u64 v[234:235], s[6:7], 0, v[178:179]
	s_mov_b32 m0, s35
	s_nop 0
	global_load_lds_dwordx4 v[234:235], off
	v_lshl_add_u64 v[234:235], s[6:7], 0, v[172:173]
	s_add_i32 m0, s35, 0x2000
	s_nop 0
	global_load_lds_dwordx4 v[234:235], off
	s_waitcnt vmcnt(4)
	s_waitcnt lgkmcnt(0)
	s_barrier
; #define PG8_STAGE(bufoff, gbase, voff) do { _Pragma("unroll") for (int _i = 0; _i < 2; ++_i) \
;         __builtin_amdgcn_global_load_lds((const unsigned*)((const char*)(gbase) + (voff)[_i]), (LAS unsigned*)(lds + (bufoff) + ldsw + _i * 8192), 16, 0, 0); } while (0)
; #define PG8_LDA(dst, b, h) do { _Pragma("unroll") for (int m = 0; m < 4; ++m) _Pragma("unroll") for (int k = 0; k < 2; ++k) dst[m][k] = *(const LAS bf16x8*)(lds + PG8_SA(b, h) + aoff + m * 2048 + k * 1024); } while (0)
; #define PG8_LDB(dst, b, h) do { _Pragma("unroll") for (int n = 0; n < 2; ++n) _Pragma("unroll") for (int k = 0; k < 2; ++k) dst[n][k] = *(const LAS bf16x8*)(lds + PG8_SB(b, h) + boff + n * 2048 + k * 1024); } while (0)
; #define PG8_MMA(ai, bj, At, Bt) do { __builtin_amdgcn_s_setprio(1); _Pragma("unroll") for (int m = 0; m < 4; ++m) _Pragma("unroll") for (int n = 0; n < 2; ++n) _Pragma("unroll") for (int k = 0; k < 2; ++k) \
;         acc[ai][bj][m][n] = __builtin_amdgcn_mfma_f32_16x16x32_bf16(Bt[n][k], At[m][k], acc[ai][bj][m][n], 0, 0, 0); __builtin_amdgcn_s_setprio(0); } while (0)
; #define PG8_WAIT_V(n) asm volatile("s_waitcnt vmcnt(" #n ")" ::: "memory")
; #define PG8_WAIT_L(n) asm volatile("s_waitcnt lgkmcnt(" #n ")" ::: "memory")
; #define PG8_BAR __builtin_amdgcn_s_barrier()
; #define PG8_SCHED __builtin_amdgcn_sched_barrier(0)
; template <class Epi, class Sched>
; __device__ __forceinline__ void gemm_phase(LAS unsigned char* lds, const Gemm g, const Sched& S, const Epi& E) {
;     ...
;             PG8_BAR; PG8_WAIT_L(0); PG8_MMA(1, 0, At, B0); PG8_BAR; PG8_SCHED;
;             PG8_STAGE(PG8_SB(0, 1), b2 + hstepB, voffB);
;             PG8_WAIT_V(6); PG8_BAR; PG8_MMA(1, 1, At, B1); PG8_BAR;
;             PG8_LDB(B0, 1, 0); PG8_SCHED; PG8_LDA(At, 1, 0); PG8_STAGE(PG8_SA(0, 1), a2 + hstepA, voffA);
;             PG8_WAIT_L(8); PG8_BAR; PG8_WAIT_L(0); PG8_MMA(0, 0, At, B0); PG8_BAR; PG8_SCHED;
;             PG8_LDB(B1, 1, 1); PG8_STAGE(PG8_SB(1, 0), b3, voffB);
;             PG8_BAR; PG8_WAIT_L(0); PG8_MMA(0, 1, At, B1); PG8_BAR;
	v_mfma_f32_16x16x32_bf16 v[62:65], v[130:133], v[146:149], v[62:65]
	v_mfma_f32_16x16x32_bf16 v[62:65], v[134:137], v[150:153], v[62:65]
	v_mfma_f32_16x16x32_bf16 v[54:57], v[130:133], v[154:157], v[54:57]
	v_mfma_f32_16x16x32_bf16 v[54:57], v[134:137], v[158:161], v[54:57]
	v_mfma_f32_16x16x32_bf16 v[46:49], v[130:133], v[162:165], v[46:49]
	v_mfma_f32_16x16x32_bf16 v[46:49], v[134:137], v[182:185], v[46:49]
	v_mfma_f32_16x16x32_bf16 v[38:41], v[130:133], v[192:195], v[38:41]
	v_mfma_f32_16x16x32_bf16 v[38:41], v[134:137], v[196:199], v[38:41]
	v_mfma_f32_16x16x32_bf16 v[58:61], v[138:141], v[146:149], v[58:61]
	v_mfma_f32_16x16x32_bf16 v[58:61], v[142:145], v[150:153], v[58:61]
	v_mfma_f32_16x16x32_bf16 v[50:53], v[138:141], v[154:157], v[50:53]
	v_mfma_f32_16x16x32_bf16 v[50:53], v[142:145], v[158:161], v[50:53]
	v_mfma_f32_16x16x32_bf16 v[42:45], v[138:141], v[162:165], v[42:45]
	v_mfma_f32_16x16x32_bf16 v[42:45], v[142:145], v[182:185], v[42:45]
	v_mfma_f32_16x16x32_bf16 v[34:37], v[138:141], v[192:195], v[34:37]
	v_mfma_f32_16x16x32_bf16 v[34:37], v[142:145], v[196:199], v[34:37]
	v_mfma_f32_16x16x32_bf16 v[30:33], v[200:203], v[146:149], v[30:33]
	v_mfma_f32_16x16x32_bf16 v[30:33], v[210:213], v[150:153], v[30:33]
	v_mfma_f32_16x16x32_bf16 v[22:25], v[200:203], v[154:157], v[22:25]
	v_mfma_f32_16x16x32_bf16 v[22:25], v[210:213], v[158:161], v[22:25]
	v_mfma_f32_16x16x32_bf16 v[14:17], v[200:203], v[162:165], v[14:17]
	v_mfma_f32_16x16x32_bf16 v[14:17], v[210:213], v[182:185], v[14:17]
	v_mfma_f32_16x16x32_bf16 v[6:9], v[200:203], v[192:195], v[6:9]
	v_mfma_f32_16x16x32_bf16 v[6:9], v[210:213], v[196:199], v[6:9]
	v_mfma_f32_16x16x32_bf16 v[26:29], v[214:217], v[146:149], v[26:29]
	v_mfma_f32_16x16x32_bf16 v[26:29], v[218:221], v[150:153], v[26:29]
	v_mfma_f32_16x16x32_bf16 v[18:21], v[214:217], v[154:157], v[18:21]
	v_mfma_f32_16x16x32_bf16 v[18:21], v[218:221], v[158:161], v[18:21]
	v_mfma_f32_16x16x32_bf16 v[10:13], v[214:217], v[162:165], v[10:13]
	v_mfma_f32_16x16x32_bf16 v[10:13], v[218:221], v[182:185], v[10:13]
	v_mfma_f32_16x16x32_bf16 v[2:5], v[214:217], v[192:195], v[2:5]
	v_mfma_f32_16x16x32_bf16 v[2:5], v[218:221], v[196:199], v[2:5]
	s_add_i32 s35, 0, 0x18000
	v_add_u32_e32 v1, s35, v207
	s_barrier
	ds_read_b128 v[130:133], v1
	ds_read_b128 v[134:137], v1 offset:1024
	ds_read_b128 v[138:141], v1 offset:2048
	ds_read_b128 v[142:145], v1 offset:3072
	ds_read_b128 v[146:149], v209 offset:32768
	ds_read_b128 v[150:153], v209 offset:33792
	ds_read_b128 v[154:157], v209 offset:34816
	ds_read_b128 v[158:161], v209 offset:35840
	ds_read_b128 v[162:165], v209 offset:36864
	ds_read_b128 v[182:185], v209 offset:37888
	ds_read_b128 v[192:195], v209 offset:38912
	ds_read_b128 v[196:199], v209 offset:39936
	s_mov_b32 m0, s79
	v_lshl_add_u64 v[224:225], s[28:29], 0, v[168:169]
	global_load_lds_dwordx4 v[224:225], off
	v_lshl_add_u64 v[226:227], s[28:29], 0, v[170:171]
	s_mov_b32 m0, s46
	s_nop 0
	global_load_lds_dwordx4 v[226:227], off
	s_add_u32 s6, s28, 0x40000
	s_addc_u32 s7, s29, 0
	s_mov_b32 m0, s33
	v_lshl_add_u64 v[236:237], s[6:7], 0, v[168:169]
	global_load_lds_dwordx4 v[236:237], off
	v_lshl_add_u64 v[236:237], s[6:7], 0, v[170:171]
	s_mov_b32 m0, s83
	s_nop 0
	global_load_lds_dwordx4 v[236:237], off
	s_add_i32 s28, 0, 0x1c000
	v_add_u32_e32 v1, s28, v207
	ds_read_b128 v[200:203], v1
	ds_read_b128 v[210:213], v1 offset:1024
	ds_read_b128 v[214:217], v1 offset:2048
	ds_read_b128 v[218:221], v1 offset:3072
	s_waitcnt lgkmcnt(0)
	s_barrier
	v_mfma_f32_16x16x32_bf16 v[126:129], v[130:133], v[146:149], v[126:129]
	v_mfma_f32_16x16x32_bf16 v[126:129], v[134:137], v[150:153], v[126:129]
	v_mfma_f32_16x16x32_bf16 v[118:121], v[130:133], v[154:157], v[118:121]
	v_mfma_f32_16x16x32_bf16 v[118:121], v[134:137], v[158:161], v[118:121]
	v_mfma_f32_16x16x32_bf16 v[110:113], v[130:133], v[162:165], v[110:113]
	v_mfma_f32_16x16x32_bf16 v[110:113], v[134:137], v[182:185], v[110:113]
	v_mfma_f32_16x16x32_bf16 v[102:105], v[130:133], v[192:195], v[102:105]
	v_mfma_f32_16x16x32_bf16 v[102:105], v[134:137], v[196:199], v[102:105]
	v_mfma_f32_16x16x32_bf16 v[122:125], v[138:141], v[146:149], v[122:125]
	v_mfma_f32_16x16x32_bf16 v[122:125], v[142:145], v[150:153], v[122:125]
	v_mfma_f32_16x16x32_bf16 v[114:117], v[138:141], v[154:157], v[114:117]
	v_mfma_f32_16x16x32_bf16 v[114:117], v[142:145], v[158:161], v[114:117]
	v_mfma_f32_16x16x32_bf16 v[106:109], v[138:141], v[162:165], v[106:109]
	v_mfma_f32_16x16x32_bf16 v[106:109], v[142:145], v[182:185], v[106:109]
	v_mfma_f32_16x16x32_bf16 v[98:101], v[138:141], v[192:195], v[98:101]
	v_mfma_f32_16x16x32_bf16 v[98:101], v[142:145], v[196:199], v[98:101]
	v_mfma_f32_16x16x32_bf16 v[94:97], v[200:203], v[146:149], v[94:97]
	v_mfma_f32_16x16x32_bf16 v[94:97], v[210:213], v[150:153], v[94:97]
	v_mfma_f32_16x16x32_bf16 v[86:89], v[200:203], v[154:157], v[86:89]
	v_mfma_f32_16x16x32_bf16 v[86:89], v[210:213], v[158:161], v[86:89]
	v_mfma_f32_16x16x32_bf16 v[78:81], v[200:203], v[162:165], v[78:81]
	v_mfma_f32_16x16x32_bf16 v[78:81], v[210:213], v[182:185], v[78:81]
	v_mfma_f32_16x16x32_bf16 v[70:73], v[200:203], v[192:195], v[70:73]
	v_mfma_f32_16x16x32_bf16 v[70:73], v[210:213], v[196:199], v[70:73]
	v_mfma_f32_16x16x32_bf16 v[90:93], v[214:217], v[146:149], v[90:93]
	v_mfma_f32_16x16x32_bf16 v[90:93], v[218:221], v[150:153], v[90:93]
	v_mfma_f32_16x16x32_bf16 v[82:85], v[214:217], v[154:157], v[82:85]
	v_mfma_f32_16x16x32_bf16 v[82:85], v[218:221], v[158:161], v[82:85]
	v_mfma_f32_16x16x32_bf16 v[74:77], v[214:217], v[162:165], v[74:77]
	v_mfma_f32_16x16x32_bf16 v[74:77], v[218:221], v[182:185], v[74:77]
	v_mfma_f32_16x16x32_bf16 v[66:69], v[214:217], v[192:195], v[66:69]
	v_mfma_f32_16x16x32_bf16 v[66:69], v[218:221], v[196:199], v[66:69]
	s_barrier
; #define PG8_STAGE(bufoff, gbase, voff) do { _Pragma("unroll") for (int _i = 0; _i < 2; ++_i) \
;         __builtin_amdgcn_global_load_lds((const unsigned*)((const char*)(gbase) + (voff)[_i]), (LAS unsigned*)(lds + (bufoff) + ldsw + _i * 8192), 16, 0, 0); } while (0)
; #define PG8_LDA(dst, b, h) do { _Pragma("unroll") for (int m = 0; m < 4; ++m) _Pragma("unroll") for (int k = 0; k < 2; ++k) dst[m][k] = *(const LAS bf16x8*)(lds + PG8_SA(b, h) + aoff + m * 2048 + k * 1024); } while (0)
; #define PG8_LDB(dst, b, h) do { _Pragma("unroll") for (int n = 0; n < 2; ++n) _Pragma("unroll") for (int k = 0; k < 2; ++k) dst[n][k] = *(const LAS bf16x8*)(lds + PG8_SB(b, h) + boff + n * 2048 + k * 1024); } while (0)
; #define PG8_WAIT_V(n) asm volatile("s_waitcnt vmcnt(" #n ")" ::: "memory")
; #define PG8_WAIT_L(n) asm volatile("s_waitcnt lgkmcnt(" #n ")" ::: "memory")
; #define PG8_BAR __builtin_amdgcn_s_barrier()
;     __device__ __forceinline__ void operator()(f32x4 (&acc)[2][2][4][2], const Unit& u, int wr, int wc, int fr, int fq) const {
;     ...
;         if (u.nt) {
;             const int tile = (u.pm - 64) * 8 + u.pn, w = wr * 4 + wc;
;             const auto rsrc = __builtin_amdgcn_make_buffer_rsrc((void*)PM, 0, 96 * 131072, 0x00020000);
;             const unsigned pbase = (unsigned)(tile * 3) * 131072u + (unsigned)((w * 16 * 64 + fq * 16 + fr) * 16);
; #pragma unroll
;             for (int ai = 0; ai < 2; ++ai) {
;                 u32x4 ra[4][2];
; #pragma unroll
;                 for (int m = 0; m < 4; ++m)
; #pragma unroll
;                     for (int bj = 0; bj < 2; ++bj) ra[m][bj] = *(const u32x4*)(gl + (size_t)u.seg * 8 * 65536 + ((ai * 4 + m) * 2 + bj) * 512);
; template <class Epi, class Sched>
; __device__ __forceinline__ void gemm_phase(LAS unsigned char* lds, const Gemm g, const Sched& S, const Epi& E) {
;     ...
;             PG8_WAIT_L(8); PG8_BAR; PG8_WAIT_L(0); PG8_MMA(0, 0, At, B0); PG8_BAR; PG8_SCHED;
;             PG8_LDB(B1, 1, 1); PG8_STAGE(PG8_SB(1, 0), b3, voffB);
;             PG8_BAR; PG8_WAIT_L(0); PG8_MMA(0, 1, At, B1); PG8_BAR;
;             PG8_LDA(At, 1, 1); PG8_STAGE(PG8_SA(1, 0), a3, voffA);
;             PG8_BAR; PG8_WAIT_L(0); PG8_MMA(1, 0, At, B0); PG8_BAR; PG8_SCHED;
;             PG8_STAGE(PG8_SB(1, 1), b3 + hstepB, voffB);
;             PG8_WAIT_V(6); PG8_BAR; PG8_MMA(1, 1, At, B1); PG8_BAR;
;         }
	ds_read_b128 v[146:149], v209 offset:49152
	ds_read_b128 v[150:153], v209 offset:50176
	ds_read_b128 v[154:157], v209 offset:51200
	ds_read_b128 v[158:161], v209 offset:52224
	ds_read_b128 v[162:165], v209 offset:53248
	ds_read_b128 v[182:185], v209 offset:54272
	ds_read_b128 v[192:195], v209 offset:55296
	ds_read_b128 v[196:199], v209 offset:56320
	s_add_i32 s6, s35, s89
	v_lshl_add_u64 v[204:205], v[204:205], 0, s[92:93]
	s_mov_b32 m0, s6
	s_nop 0
	global_load_lds_dwordx4 v[204:205], off
	v_lshl_add_u64 v[204:205], v[222:223], 0, s[92:93]
	s_add_i32 m0, s6, 0x2000
	s_nop 0
	global_load_lds_dwordx4 v[204:205], off
	s_add_u32 s6, s26, 0x40080
	s_addc_u32 s7, s27, 0
	s_add_i32 s26, s28, s89
	v_lshl_add_u64 v[238:239], s[6:7], 0, v[178:179]
	s_mov_b32 m0, s26
	s_nop 0
	global_load_lds_dwordx4 v[238:239], off
	v_lshl_add_u64 v[238:239], s[6:7], 0, v[172:173]
	s_add_i32 m0, s26, 0x2000
	s_nop 0
	global_load_lds_dwordx4 v[238:239], off
	s_waitcnt vmcnt(4)
	s_waitcnt lgkmcnt(0)
	s_barrier
	v_mfma_f32_16x16x32_bf16 v[62:65], v[130:133], v[146:149], v[62:65]
	v_mfma_f32_16x16x32_bf16 v[62:65], v[134:137], v[150:153], v[62:65]
	v_mfma_f32_16x16x32_bf16 v[54:57], v[130:133], v[154:157], v[54:57]
	v_mfma_f32_16x16x32_bf16 v[54:57], v[134:137], v[158:161], v[54:57]
	v_mfma_f32_16x16x32_bf16 v[46:49], v[130:133], v[162:165], v[46:49]
	v_mfma_f32_16x16x32_bf16 v[46:49], v[134:137], v[182:185], v[46:49]
	v_mfma_f32_16x16x32_bf16 v[38:41], v[130:133], v[192:195], v[38:41]
	v_mfma_f32_16x16x32_bf16 v[38:41], v[134:137], v[196:199], v[38:41]
	v_mfma_f32_16x16x32_bf16 v[58:61], v[138:141], v[146:149], v[58:61]
	v_mfma_f32_16x16x32_bf16 v[58:61], v[142:145], v[150:153], v[58:61]
	v_mfma_f32_16x16x32_bf16 v[50:53], v[138:141], v[154:157], v[50:53]
	v_mfma_f32_16x16x32_bf16 v[50:53], v[142:145], v[158:161], v[50:53]
	v_mfma_f32_16x16x32_bf16 v[42:45], v[138:141], v[162:165], v[42:45]
	v_mfma_f32_16x16x32_bf16 v[42:45], v[142:145], v[182:185], v[42:45]
	v_mfma_f32_16x16x32_bf16 v[34:37], v[138:141], v[192:195], v[34:37]
	v_mfma_f32_16x16x32_bf16 v[34:37], v[142:145], v[196:199], v[34:37]
	v_mfma_f32_16x16x32_bf16 v[30:33], v[200:203], v[146:149], v[30:33]
	v_mfma_f32_16x16x32_bf16 v[30:33], v[210:213], v[150:153], v[30:33]
	v_mfma_f32_16x16x32_bf16 v[22:25], v[200:203], v[154:157], v[22:25]
	v_mfma_f32_16x16x32_bf16 v[22:25], v[210:213], v[158:161], v[22:25]
	v_mfma_f32_16x16x32_bf16 v[14:17], v[200:203], v[162:165], v[14:17]
	v_mfma_f32_16x16x32_bf16 v[14:17], v[210:213], v[182:185], v[14:17]
	v_mfma_f32_16x16x32_bf16 v[6:9], v[200:203], v[192:195], v[6:9]
	v_mfma_f32_16x16x32_bf16 v[6:9], v[210:213], v[196:199], v[6:9]
	v_mfma_f32_16x16x32_bf16 v[26:29], v[214:217], v[146:149], v[26:29]
	v_mfma_f32_16x16x32_bf16 v[26:29], v[218:221], v[150:153], v[26:29]
	v_mfma_f32_16x16x32_bf16 v[18:21], v[214:217], v[154:157], v[18:21]
	v_mfma_f32_16x16x32_bf16 v[18:21], v[218:221], v[158:161], v[18:21]
	v_mfma_f32_16x16x32_bf16 v[10:13], v[214:217], v[162:165], v[10:13]
	v_mfma_f32_16x16x32_bf16 v[10:13], v[218:221], v[182:185], v[10:13]
	v_mfma_f32_16x16x32_bf16 v[2:5], v[214:217], v[192:195], v[2:5]
	v_mfma_f32_16x16x32_bf16 v[2:5], v[218:221], v[196:199], v[2:5]
	s_add_u32 s68, s68, 0x100
	s_addc_u32 s69, s69, 0
	s_add_u32 s55, s55, 0x100
	s_addc_u32 s59, s59, 0
	s_cmp_ge_i32 s63, s1
	s_mov_b32 s28, s63
	s_barrier
	s_cbranch_scc0 .LBB0_871
	s_lshl_b64 s[6:7], s[66:67], 17
	v_lshl_add_u32 v210, s20, 8, v206
	v_lshl_or_b32 v194, s12, 8, v167
	v_lshl_add_u64 v[192:193], v[176:177], 0, s[6:7]
	s_andn2_b64 vcc, exec, vcc
	s_mov_b64 s[26:27], -1
	s_cbranch_vccnz .LBB0_880
	s_ashr_i32 s23, s22, 31
	s_lshl_b64 s[6:7], s[22:23], 20
	v_lshl_add_u64 v[158:159], v[192:193], 0, s[6:7]
	global_load_dwordx4 v[162:165], v[158:159], off
	global_load_dwordx4 v[154:157], v[158:159], off offset:1024
	global_load_dwordx4 v[150:153], v[158:159], off offset:2048
	global_load_dwordx4 v[146:149], v[158:159], off offset:3072
	v_add_co_u32_e32 v130, vcc, s48, v158
	s_movk_i32 s6, 0x2000
	s_nop 0
	v_addc_co_u32_e32 v131, vcc, 0, v159, vcc
	v_add_co_u32_e32 v160, vcc, s6, v158
	s_lshl_b32 s1, s20, 3
	s_nop 0
	v_addc_co_u32_e32 v161, vcc, 0, v159, vcc
	global_load_dwordx4 v[142:145], v[160:161], off offset:-4096
	global_load_dwordx4 v[138:141], v[130:131], off offset:1024
	global_load_dwordx4 v[134:137], v[130:131], off offset:2048
	s_nop 0
	global_load_dwordx4 v[130:133], v[130:131], off offset:3072
	s_add_i32 s1, s12, s1
	s_addk_i32 s1, 0xfe00
	s_mul_i32 s12, s1, 0x60000
	s_lshl_b32 s6, s22, 17
	s_add_i32 s12, s12, s6
	s_movk_i32 s6, 0x3000
	s_waitcnt vmcnt(0)
; __device__ __forceinline__ unsigned cvt_pk_bf16(float lo, float hi) { const f32x2_t v = {lo, hi}; return __builtin_bit_cast(unsigned, __builtin_convertvector(v, bf16x2_t)); }
;     __device__ __forceinline__ void operator()(f32x4 (&acc)[2][2][4][2], const Unit& u, int wr, int wc, int fr, int fq) const {
;     ...
; #pragma unroll
;             for (int ai = 0; ai < 2; ++ai) {
;                 u32x4 ra[4][2];
; #pragma unroll
;                 for (int m = 0; m < 4; ++m)
; #pragma unroll
;                     for (int bj = 0; bj < 2; ++bj) ra[m][bj] = *(const u32x4*)(gl + (size_t)u.seg * 8 * 65536 + ((ai * 4 + m) * 2 + bj) * 512);
; #pragma unroll
;                 for (int m = 0; m < 4; ++m)
; #pragma unroll
;                     for (int bj = 0; bj < 2; ++bj) { float f[8]; unpack8(ra[m][bj], f);
;                         const f32x4 v0 = acc[ai][bj][m][0], v1 = acc[ai][bj][m][1];
;                         u32x4 wv; wv.x = cvt_pk_bf16(v0[0] * f[0], v0[1] * f[1]); wv.y = cvt_pk_bf16(v0[2] * f[2], v0[3] * f[3]); wv.z = cvt_pk_bf16(v1[0] * f[4], v1[1] * f[5]); wv.w = cvt_pk_bf16(v1[2] * f[6], v1[3] * f[7]);
;                         __builtin_amdgcn_raw_buffer_store_b128(wv, rsrc, pbase + (unsigned)u.seg * 131072u + (unsigned)(((ai * 4 + m) * 2 + bj) * 1024), 0,   16); }
;             }
	v_lshlrev_b32_e32 v182, 16, v162
	v_and_b32_e32 v183, 0xffff0000, v162
	v_lshlrev_b32_e32 v162, 16, v163
	v_and_b32_e32 v163, 0xffff0000, v163
	v_pk_mul_f32 v[182:183], v[126:127], v[182:183]
	v_pk_mul_f32 v[162:163], v[128:129], v[162:163]
	v_cvt_pk_bf16_f32 v182, v182, v183
	v_cvt_pk_bf16_f32 v183, v162, v163
	v_lshlrev_b32_e32 v162, 16, v164
	v_and_b32_e32 v163, 0xffff0000, v164
	v_pk_mul_f32 v[162:163], v[122:123], v[162:163]
	v_lshlrev_b32_e32 v164, 16, v154
	v_cvt_pk_bf16_f32 v184, v162, v163
	v_lshlrev_b32_e32 v162, 16, v165
	v_and_b32_e32 v163, 0xffff0000, v165
	v_and_b32_e32 v165, 0xffff0000, v154
	v_pk_mul_f32 v[164:165], v[94:95], v[164:165]
	v_pk_mul_f32 v[162:163], v[124:125], v[162:163]
	v_cvt_pk_bf16_f32 v154, v164, v165
	v_lshlrev_b32_e32 v164, 16, v155
	v_and_b32_e32 v165, 0xffff0000, v155
	v_pk_mul_f32 v[164:165], v[96:97], v[164:165]
	v_cvt_pk_bf16_f32 v185, v162, v163
	v_cvt_pk_bf16_f32 v155, v164, v165
	v_lshlrev_b32_e32 v164, 16, v156
	v_and_b32_e32 v165, 0xffff0000, v156
	v_pk_mul_f32 v[164:165], v[90:91], v[164:165]
	v_add_u32_e32 v162, s12, v208
	v_cvt_pk_bf16_f32 v156, v164, v165
	v_lshlrev_b32_e32 v164, 16, v157
	v_and_b32_e32 v165, 0xffff0000, v157
	v_pk_mul_f32 v[164:165], v[92:93], v[164:165]
	v_add_u32_e32 v1, 0x1000, v162
	v_cvt_pk_bf16_f32 v157, v164, v165
	buffer_store_dwordx4 v[154:157], v162, s[16:19], 0 offen offset:1024 sc1
	buffer_store_dwordx4 v[182:185], v162, s[16:19], 0 offen sc1
	s_nop 0
	v_lshlrev_b32_e32 v154, 16, v150
	v_and_b32_e32 v155, 0xffff0000, v150
	v_pk_mul_f32 v[154:155], v[118:119], v[154:155]
	s_nop 0
	v_cvt_pk_bf16_f32 v150, v154, v155
	v_lshlrev_b32_e32 v154, 16, v151
	v_and_b32_e32 v155, 0xffff0000, v151
	v_pk_mul_f32 v[154:155], v[120:121], v[154:155]
	s_nop 0
	v_cvt_pk_bf16_f32 v151, v154, v155
	v_lshlrev_b32_e32 v154, 16, v152
	v_and_b32_e32 v155, 0xffff0000, v152
	v_pk_mul_f32 v[154:155], v[114:115], v[154:155]
	s_nop 0
	v_cvt_pk_bf16_f32 v152, v154, v155
	v_lshlrev_b32_e32 v154, 16, v153
	v_and_b32_e32 v155, 0xffff0000, v153
	v_pk_mul_f32 v[154:155], v[116:117], v[154:155]
	s_nop 0
	v_cvt_pk_bf16_f32 v153, v154, v155
	buffer_store_dwordx4 v[150:153], v162, s[16:19], 0 offen offset:2048 sc1
	s_nop 1
	v_lshlrev_b32_e32 v150, 16, v146
	v_and_b32_e32 v151, 0xffff0000, v146
	v_pk_mul_f32 v[150:151], v[86:87], v[150:151]
	s_nop 0
	v_cvt_pk_bf16_f32 v146, v150, v151
	v_lshlrev_b32_e32 v150, 16, v147
	v_and_b32_e32 v151, 0xffff0000, v147
	v_pk_mul_f32 v[150:151], v[88:89], v[150:151]
	s_nop 0
	v_cvt_pk_bf16_f32 v147, v150, v151
	v_lshlrev_b32_e32 v150, 16, v148
	v_and_b32_e32 v151, 0xffff0000, v148
	v_pk_mul_f32 v[150:151], v[82:83], v[150:151]
	s_nop 0
	v_cvt_pk_bf16_f32 v148, v150, v151
	v_lshlrev_b32_e32 v150, 16, v149
	v_and_b32_e32 v151, 0xffff0000, v149
	v_pk_mul_f32 v[150:151], v[84:85], v[150:151]
	s_nop 0
	v_cvt_pk_bf16_f32 v149, v150, v151
	buffer_store_dwordx4 v[146:149], v162, s[16:19], 0 offen offset:3072 sc1
	s_nop 1
	v_lshlrev_b32_e32 v146, 16, v142
	v_and_b32_e32 v147, 0xffff0000, v142
	v_pk_mul_f32 v[146:147], v[110:111], v[146:147]
	s_nop 0
	v_cvt_pk_bf16_f32 v142, v146, v147
	v_lshlrev_b32_e32 v146, 16, v143
	v_and_b32_e32 v147, 0xffff0000, v143
	v_pk_mul_f32 v[146:147], v[112:113], v[146:147]
	s_nop 0
	v_cvt_pk_bf16_f32 v143, v146, v147
	v_lshlrev_b32_e32 v146, 16, v144
	v_and_b32_e32 v147, 0xffff0000, v144
	v_pk_mul_f32 v[146:147], v[106:107], v[146:147]
	s_nop 0
	v_cvt_pk_bf16_f32 v144, v146, v147
	v_lshlrev_b32_e32 v146, 16, v145
	v_and_b32_e32 v147, 0xffff0000, v145
	v_pk_mul_f32 v[146:147], v[108:109], v[146:147]
	s_nop 0
	v_cvt_pk_bf16_f32 v145, v146, v147
	buffer_store_dwordx4 v[142:145], v1, s[16:19], 0 offen sc1
	s_nop 1
	v_lshlrev_b32_e32 v142, 16, v138
	v_and_b32_e32 v143, 0xffff0000, v138
	v_pk_mul_f32 v[142:143], v[78:79], v[142:143]
	s_nop 0
	v_cvt_pk_bf16_f32 v138, v142, v143
	v_lshlrev_b32_e32 v142, 16, v139
	v_and_b32_e32 v143, 0xffff0000, v139
	v_pk_mul_f32 v[142:143], v[80:81], v[142:143]
	s_nop 0
	v_cvt_pk_bf16_f32 v139, v142, v143
	v_lshlrev_b32_e32 v142, 16, v140
	v_and_b32_e32 v143, 0xffff0000, v140
	v_pk_mul_f32 v[142:143], v[74:75], v[142:143]
	s_nop 0
	v_cvt_pk_bf16_f32 v140, v142, v143
	v_lshlrev_b32_e32 v142, 16, v141
	v_and_b32_e32 v143, 0xffff0000, v141
	v_pk_mul_f32 v[142:143], v[76:77], v[142:143]
	s_nop 0
	v_cvt_pk_bf16_f32 v141, v142, v143
	buffer_store_dwordx4 v[138:141], v1, s[16:19], 0 offen offset:1024 sc1
	s_nop 1
	v_lshlrev_b32_e32 v138, 16, v134
	v_and_b32_e32 v139, 0xffff0000, v134
	v_pk_mul_f32 v[138:139], v[102:103], v[138:139]
	s_nop 0
	v_cvt_pk_bf16_f32 v134, v138, v139
	v_lshlrev_b32_e32 v138, 16, v135
	v_and_b32_e32 v139, 0xffff0000, v135
	v_pk_mul_f32 v[138:139], v[104:105], v[138:139]
	s_nop 0
	v_cvt_pk_bf16_f32 v135, v138, v139
	v_lshlrev_b32_e32 v138, 16, v136
	v_and_b32_e32 v139, 0xffff0000, v136
	v_pk_mul_f32 v[138:139], v[98:99], v[138:139]
	s_nop 0
	v_cvt_pk_bf16_f32 v136, v138, v139
	v_lshlrev_b32_e32 v138, 16, v137
	v_and_b32_e32 v139, 0xffff0000, v137
	v_pk_mul_f32 v[138:139], v[100:101], v[138:139]
	s_nop 0
	v_cvt_pk_bf16_f32 v137, v138, v139
	buffer_store_dwordx4 v[134:137], v1, s[16:19], 0 offen offset:2048 sc1
	s_nop 1
	v_lshlrev_b32_e32 v134, 16, v130
	v_and_b32_e32 v135, 0xffff0000, v130
	v_pk_mul_f32 v[134:135], v[70:71], v[134:135]
	s_nop 0
	v_cvt_pk_bf16_f32 v130, v134, v135
	v_lshlrev_b32_e32 v134, 16, v131
	v_and_b32_e32 v135, 0xffff0000, v131
	v_pk_mul_f32 v[134:135], v[72:73], v[134:135]
	s_nop 0
	v_cvt_pk_bf16_f32 v131, v134, v135
	v_lshlrev_b32_e32 v134, 16, v132
	v_and_b32_e32 v135, 0xffff0000, v132
	v_pk_mul_f32 v[134:135], v[66:67], v[134:135]
	s_nop 0
	v_cvt_pk_bf16_f32 v132, v134, v135
	v_lshlrev_b32_e32 v134, 16, v133
	v_and_b32_e32 v135, 0xffff0000, v133
	v_pk_mul_f32 v[134:135], v[68:69], v[134:135]
	s_nop 0
	v_cvt_pk_bf16_f32 v133, v134, v135
	buffer_store_dwordx4 v[130:133], v1, s[16:19], 0 offen offset:3072 sc1
	global_load_dwordx4 v[134:137], v[160:161], off
	global_load_dwordx4 v[138:141], v[160:161], off offset:1024
	global_load_dwordx4 v[142:145], v[160:161], off offset:2048
	global_load_dwordx4 v[146:149], v[160:161], off offset:3072
	v_add_co_u32_e32 v130, vcc, s6, v158
	v_add_u32_e32 v1, 0x2000, v162
	s_nop 0
	v_addc_co_u32_e32 v131, vcc, 0, v159, vcc
	global_load_dwordx4 v[150:153], v[130:131], off
	global_load_dwordx4 v[154:157], v[130:131], off offset:1024
	global_load_dwordx4 v[158:161], v[130:131], off offset:2048
	s_nop 0
	global_load_dwordx4 v[130:133], v[130:131], off offset:3072
	s_waitcnt vmcnt(0)
; __device__ __forceinline__ unsigned cvt_pk_bf16(float lo, float hi) { const f32x2_t v = {lo, hi}; return __builtin_bit_cast(unsigned, __builtin_convertvector(v, bf16x2_t)); }
;     __device__ __forceinline__ void operator()(f32x4 (&acc)[2][2][4][2], const Unit& u, int wr, int wc, int fr, int fq) const {
;     ...
; #pragma unroll
;                 for (int m = 0; m < 4; ++m)
; #pragma unroll
;                     for (int bj = 0; bj < 2; ++bj) { float f[8]; unpack8(ra[m][bj], f);
;                         const f32x4 v0 = acc[ai][bj][m][0], v1 = acc[ai][bj][m][1];
;                         u32x4 wv; wv.x = cvt_pk_bf16(v0[0] * f[0], v0[1] * f[1]); wv.y = cvt_pk_bf16(v0[2] * f[2], v0[3] * f[3]); wv.z = cvt_pk_bf16(v1[0] * f[4], v1[1] * f[5]); wv.w = cvt_pk_bf16(v1[2] * f[6], v1[3] * f[7]);
;                         __builtin_amdgcn_raw_buffer_store_b128(wv, rsrc, pbase + (unsigned)u.seg * 131072u + (unsigned)(((ai * 4 + m) * 2 + bj) * 1024), 0,   16); }
;             }
;             asm volatile("s_waitcnt vmcnt(0)" ::: "memory");
;             unsigned old = 0; if ((fq | fr) == 0) old = __hip_atomic_fetch_add(cnt + tile * 8 + w, 1u, __ATOMIC_RELAXED, __HIP_MEMORY_SCOPE_AGENT);
;             old = (unsigned)__builtin_amdgcn_readfirstlane((int)old);
	v_lshlrev_b32_e32 v164, 16, v134
	v_and_b32_e32 v165, 0xffff0000, v134
	v_pk_mul_f32 v[164:165], v[62:63], v[164:165]
	s_nop 0
	v_cvt_pk_bf16_f32 v134, v164, v165
	v_lshlrev_b32_e32 v164, 16, v135
	v_and_b32_e32 v165, 0xffff0000, v135
	v_pk_mul_f32 v[164:165], v[64:65], v[164:165]
	s_nop 0
	v_cvt_pk_bf16_f32 v135, v164, v165
	v_lshlrev_b32_e32 v164, 16, v136
	v_and_b32_e32 v165, 0xffff0000, v136
	v_pk_mul_f32 v[164:165], v[58:59], v[164:165]
	s_nop 0
	v_cvt_pk_bf16_f32 v136, v164, v165
	v_lshlrev_b32_e32 v164, 16, v137
	v_and_b32_e32 v165, 0xffff0000, v137
	v_pk_mul_f32 v[164:165], v[60:61], v[164:165]
	s_nop 0
	v_cvt_pk_bf16_f32 v137, v164, v165
	buffer_store_dwordx4 v[134:137], v1, s[16:19], 0 offen sc1
	s_nop 1
	v_lshlrev_b32_e32 v134, 16, v138
	v_and_b32_e32 v135, 0xffff0000, v138
	v_lshlrev_b32_e32 v136, 16, v139
	v_and_b32_e32 v137, 0xffff0000, v139
	v_pk_mul_f32 v[134:135], v[30:31], v[134:135]
	v_pk_mul_f32 v[136:137], v[32:33], v[136:137]
	v_cvt_pk_bf16_f32 v134, v134, v135
	v_cvt_pk_bf16_f32 v135, v136, v137
	v_lshlrev_b32_e32 v136, 16, v140
	v_and_b32_e32 v137, 0xffff0000, v140
	v_lshlrev_b32_e32 v138, 16, v141
	v_and_b32_e32 v139, 0xffff0000, v141
	v_pk_mul_f32 v[136:137], v[26:27], v[136:137]
	v_pk_mul_f32 v[138:139], v[28:29], v[138:139]
	v_cvt_pk_bf16_f32 v136, v136, v137
	v_cvt_pk_bf16_f32 v137, v138, v139
	buffer_store_dwordx4 v[134:137], v1, s[16:19], 0 offen offset:1024 sc1
	v_lshlrev_b32_e32 v138, 16, v145
	v_and_b32_e32 v139, 0xffff0000, v145
	v_lshlrev_b32_e32 v134, 16, v142
	v_and_b32_e32 v135, 0xffff0000, v142
	v_lshlrev_b32_e32 v136, 16, v143
	v_and_b32_e32 v137, 0xffff0000, v143
	v_pk_mul_f32 v[134:135], v[54:55], v[134:135]
	v_pk_mul_f32 v[136:137], v[56:57], v[136:137]
	v_cvt_pk_bf16_f32 v134, v134, v135
	v_cvt_pk_bf16_f32 v135, v136, v137
	v_lshlrev_b32_e32 v136, 16, v144
	v_and_b32_e32 v137, 0xffff0000, v144
	v_pk_mul_f32 v[136:137], v[50:51], v[136:137]
	v_pk_mul_f32 v[138:139], v[52:53], v[138:139]
	v_cvt_pk_bf16_f32 v136, v136, v137
	v_cvt_pk_bf16_f32 v137, v138, v139
	buffer_store_dwordx4 v[134:137], v1, s[16:19], 0 offen offset:2048 sc1
	v_lshlrev_b32_e32 v138, 16, v149
	v_and_b32_e32 v139, 0xffff0000, v149
	v_lshlrev_b32_e32 v134, 16, v146
	v_and_b32_e32 v135, 0xffff0000, v146
	v_lshlrev_b32_e32 v136, 16, v147
	v_and_b32_e32 v137, 0xffff0000, v147
	v_pk_mul_f32 v[134:135], v[22:23], v[134:135]
	v_pk_mul_f32 v[136:137], v[24:25], v[136:137]
	v_cvt_pk_bf16_f32 v134, v134, v135
	v_cvt_pk_bf16_f32 v135, v136, v137
	v_lshlrev_b32_e32 v136, 16, v148
	v_and_b32_e32 v137, 0xffff0000, v148
	v_pk_mul_f32 v[136:137], v[18:19], v[136:137]
	v_pk_mul_f32 v[138:139], v[20:21], v[138:139]
	v_cvt_pk_bf16_f32 v136, v136, v137
	v_cvt_pk_bf16_f32 v137, v138, v139
	buffer_store_dwordx4 v[134:137], v1, s[16:19], 0 offen offset:3072 sc1
	v_lshlrev_b32_e32 v138, 16, v153
	v_and_b32_e32 v139, 0xffff0000, v153
	v_lshlrev_b32_e32 v134, 16, v150
	v_and_b32_e32 v135, 0xffff0000, v150
	v_lshlrev_b32_e32 v136, 16, v151
	v_and_b32_e32 v137, 0xffff0000, v151
	v_pk_mul_f32 v[134:135], v[46:47], v[134:135]
	v_pk_mul_f32 v[136:137], v[48:49], v[136:137]
	v_cvt_pk_bf16_f32 v134, v134, v135
	v_cvt_pk_bf16_f32 v135, v136, v137
	v_lshlrev_b32_e32 v136, 16, v152
	v_and_b32_e32 v137, 0xffff0000, v152
	v_pk_mul_f32 v[136:137], v[42:43], v[136:137]
	v_pk_mul_f32 v[138:139], v[44:45], v[138:139]
	v_cvt_pk_bf16_f32 v136, v136, v137
	v_cvt_pk_bf16_f32 v137, v138, v139
	v_add_u32_e32 v1, 0x3000, v162
	buffer_store_dwordx4 v[134:137], v1, s[16:19], 0 offen sc1
	v_lshlrev_b32_e32 v138, 16, v157
	v_and_b32_e32 v139, 0xffff0000, v157
	v_lshlrev_b32_e32 v134, 16, v154
	v_and_b32_e32 v135, 0xffff0000, v154
	v_lshlrev_b32_e32 v136, 16, v155
	v_and_b32_e32 v137, 0xffff0000, v155
	v_pk_mul_f32 v[134:135], v[14:15], v[134:135]
	v_pk_mul_f32 v[136:137], v[16:17], v[136:137]
	v_cvt_pk_bf16_f32 v134, v134, v135
	v_cvt_pk_bf16_f32 v135, v136, v137
	v_lshlrev_b32_e32 v136, 16, v156
	v_and_b32_e32 v137, 0xffff0000, v156
	v_pk_mul_f32 v[136:137], v[10:11], v[136:137]
	v_pk_mul_f32 v[138:139], v[12:13], v[138:139]
	v_cvt_pk_bf16_f32 v136, v136, v137
	v_cvt_pk_bf16_f32 v137, v138, v139
	buffer_store_dwordx4 v[134:137], v1, s[16:19], 0 offen offset:1024 sc1
	v_lshlrev_b32_e32 v138, 16, v161
	v_and_b32_e32 v139, 0xffff0000, v161
	v_lshlrev_b32_e32 v134, 16, v158
	v_and_b32_e32 v135, 0xffff0000, v158
	v_lshlrev_b32_e32 v136, 16, v159
	v_and_b32_e32 v137, 0xffff0000, v159
	v_pk_mul_f32 v[134:135], v[38:39], v[134:135]
	v_pk_mul_f32 v[136:137], v[40:41], v[136:137]
	v_cvt_pk_bf16_f32 v134, v134, v135
	v_cvt_pk_bf16_f32 v135, v136, v137
	v_lshlrev_b32_e32 v136, 16, v160
	v_and_b32_e32 v137, 0xffff0000, v160
	v_pk_mul_f32 v[136:137], v[34:35], v[136:137]
	v_pk_mul_f32 v[138:139], v[36:37], v[138:139]
	v_cvt_pk_bf16_f32 v136, v136, v137
	v_cvt_pk_bf16_f32 v137, v138, v139
	buffer_store_dwordx4 v[134:137], v1, s[16:19], 0 offen offset:2048 sc1
	s_nop 1
	v_lshlrev_b32_e32 v134, 16, v130
	v_and_b32_e32 v135, 0xffff0000, v130
	v_pk_mul_f32 v[134:135], v[6:7], v[134:135]
	s_nop 0
	v_cvt_pk_bf16_f32 v130, v134, v135
	v_lshlrev_b32_e32 v134, 16, v131
	v_and_b32_e32 v135, 0xffff0000, v131
	v_pk_mul_f32 v[134:135], v[8:9], v[134:135]
	s_nop 0
	v_cvt_pk_bf16_f32 v131, v134, v135
	v_lshlrev_b32_e32 v134, 16, v132
	v_and_b32_e32 v135, 0xffff0000, v132
	v_pk_mul_f32 v[134:135], v[2:3], v[134:135]
	s_nop 0
	v_cvt_pk_bf16_f32 v132, v134, v135
	v_lshlrev_b32_e32 v134, 16, v133
	v_and_b32_e32 v135, 0xffff0000, v133
	v_pk_mul_f32 v[134:135], v[4:5], v[134:135]
	s_nop 0
	v_cvt_pk_bf16_f32 v133, v134, v135
	buffer_store_dwordx4 v[130:133], v1, s[16:19], 0 offen offset:3072 sc1
	s_waitcnt vmcnt(0)
	s_nop 1
	v_mov_b32_e32 v130, 0
	s_and_saveexec_b64 s[12:13], s[4:5]
	s_cbranch_execz .LBB0_877
	s_mov_b64 s[26:27], exec
	v_mbcnt_lo_u32_b32 v1, s26, 0
	v_mbcnt_hi_u32_b32 v130, s27, v1
	v_cmp_eq_u32_e32 vcc, 0, v130
	s_and_saveexec_b64 s[20:21], vcc
	s_cbranch_execz .LBB0_876
	s_lshl_b32 s6, s1, 3
	s_ashr_i32 s7, s6, 31
	s_lshl_b64 s[6:7], s[6:7], 2
	v_readlane_b32 s23, v255, 36
	s_add_u32 s6, s23, s6
	v_readlane_b32 s23, v255, 37
	s_addc_u32 s7, s23, s7
	s_bcnt1_i32_b64 s23, s[26:27]
	v_mov_b32_e32 v1, s23
	global_atomic_add v131, v179, v1, s[6:7] sc0

; #define PG8_STAGE(bufoff, gbase, voff) do { _Pragma("unroll") for (int _i = 0; _i < 2; ++_i) \
;         __builtin_amdgcn_global_load_lds((const unsigned*)((const char*)(gbase) + (voff)[_i]), (LAS unsigned*)(lds + (bufoff) + ldsw + _i * 8192), 16, 0, 0); } while (0)
; #define PG8_LDA(dst, b, h) do { _Pragma("unroll") for (int m = 0; m < 4; ++m) _Pragma("unroll") for (int k = 0; k < 2; ++k) dst[m][k] = *(const LAS bf16x8*)(lds + PG8_SA(b, h) + aoff + m * 2048 + k * 1024); } while (0)
; #define PG8_LDB(dst, b, h) do { _Pragma("unroll") for (int n = 0; n < 2; ++n) _Pragma("unroll") for (int k = 0; k < 2; ++k) dst[n][k] = *(const LAS bf16x8*)(lds + PG8_SB(b, h) + boff + n * 2048 + k * 1024); } while (0)
; #define PG8_MMA(ai, bj, At, Bt) do { __builtin_amdgcn_s_setprio(1); _Pragma("unroll") for (int m = 0; m < 4; ++m) _Pragma("unroll") for (int n = 0; n < 2; ++n) _Pragma("unroll") for (int k = 0; k < 2; ++k) \
;         acc[ai][bj][m][n] = __builtin_amdgcn_mfma_f32_16x16x32_bf16(Bt[n][k], At[m][k], acc[ai][bj][m][n], 0, 0, 0); __builtin_amdgcn_s_setprio(0); } while (0)
; #define PG8_WAIT_V(n) asm volatile("s_waitcnt vmcnt(" #n ")" ::: "memory")
; #define PG8_BAR __builtin_amdgcn_s_barrier()
; template <class Epi, class Sched>
; __device__ __forceinline__ void gemm_phase(LAS unsigned char* lds, const Gemm g, const Sched& S, const Epi& E) {
;     ...
;         for (int t = 0; t < ntu; t += 2) {
;             const bool last = (t == ntu - 2);
;             const char* a1 = cA + (size_t)(t + 1) * kstep;
;             const char* a2 = last ? nA : cA + (size_t)(t + 2) * kstep; const char* b2 = last ? nB : cB + (size_t)(t + 2) * kstep;
;             const char* a3 = a2 + kstep; const char* b3 = b2 + kstep;
;             if (last && has_next) S.a_ready(nxt);
;             PG8_LDB(B0, 0, 0); PG8_SCHED; PG8_LDA(At, 0, 0); PG8_STAGE(PG8_SA(1, 1), a1 + hstepA, voffA);
;             PG8_WAIT_L(8); PG8_BAR; PG8_WAIT_L(0); PG8_MMA(0, 0, At, B0); PG8_BAR; PG8_SCHED;
;             PG8_LDB(B1, 0, 1); PG8_STAGE(PG8_SB(0, 0), b2, voffB);
;             PG8_BAR; PG8_WAIT_L(0); PG8_MMA(0, 1, At, B1); PG8_BAR;
;             PG8_LDA(At, 0, 1); PG8_STAGE(PG8_SA(0, 0), a2, voffA);
;             PG8_BAR; PG8_WAIT_L(0); PG8_MMA(1, 0, At, B0); PG8_BAR; PG8_SCHED;
;             PG8_STAGE(PG8_SB(0, 1), b2 + hstepB, voffB);
;             PG8_WAIT_V(6); PG8_BAR; PG8_MMA(1, 1, At, B1); PG8_BAR;
.LBB0_985:
	s_add_i32 s72, s28, 2
	s_add_u32 s54, s52, 0x100
	s_addc_u32 s55, s53, 0
	s_add_i32 s35, 0, 0x10000
	v_add_u32_e32 v1, s35, v141
	ds_read_b128 v[144:147], v1
	ds_read_b128 v[148:151], v1 offset:1024
	ds_read_b128 v[152:155], v1 offset:2048
	ds_read_b128 v[156:159], v1 offset:3072
	s_cmp_eq_u32 s21, s28
	s_cselect_b32 s28, s24, s54
	s_cselect_b32 s29, s25, s55
	s_cselect_b32 s57, s27, s71
	s_cselect_b32 s56, s26, s70
	ds_read_b128 v[160:163], v143
	ds_read_b128 v[164:167], v143 offset:1024
	ds_read_b128 v[168:171], v143 offset:2048
	ds_read_b128 v[172:175], v143 offset:3072
	ds_read_b128 v[182:185], v143 offset:4096
	ds_read_b128 v[186:189], v143 offset:5120
	ds_read_b128 v[190:193], v143 offset:6144
	ds_read_b128 v[194:197], v143 offset:7168
	s_mov_b32 s98, 0xfff7c000
	s_mov_b32 s99, -1
	v_lshl_add_u64 v[232:233], s[52:53], 0, v[136:137]
	v_lshl_add_u64 v[232:233], v[232:233], 0, s[98:99]
	s_mov_b32 m0, s62
	s_nop 0
	global_load_lds_dwordx4 v[232:233], off
	v_lshl_add_u64 v[232:233], s[52:53], 0, v[138:139]
	v_lshl_add_u64 v[232:233], v[232:233], 0, s[98:99]
	s_mov_b32 m0, s63
	s_nop 0
	global_load_lds_dwordx4 v[232:233], off
	v_lshl_add_u64 v[232:233], s[52:53], 0, v[136:137]
	s_add_i32 m0, s9, 0xc000
	s_nop 0
	global_load_lds_dwordx4 v[232:233], off
	v_lshl_add_u64 v[232:233], s[52:53], 0, v[138:139]
	s_add_i32 m0, s9, 0xe000
	s_nop 0
	global_load_lds_dwordx4 v[232:233], off
	s_add_i32 s76, 0, 0x14000
	v_add_u32_e32 v1, s76, v141
	ds_read_b128 v[198:201], v1
	ds_read_b128 v[202:205], v1 offset:1024
	ds_read_b128 v[206:209], v1 offset:2048
	ds_read_b128 v[210:213], v1 offset:3072
	s_waitcnt lgkmcnt(0)
	s_barrier
	v_mfma_f32_16x16x32_bf16 v[126:129], v[144:147], v[160:163], v[126:129]
	v_mfma_f32_16x16x32_bf16 v[126:129], v[148:151], v[164:167], v[126:129]
	v_mfma_f32_16x16x32_bf16 v[110:113], v[144:147], v[168:171], v[110:113]
	v_mfma_f32_16x16x32_bf16 v[110:113], v[148:151], v[172:175], v[110:113]
	v_mfma_f32_16x16x32_bf16 v[94:97], v[144:147], v[182:185], v[94:97]
	v_mfma_f32_16x16x32_bf16 v[94:97], v[148:151], v[186:189], v[94:97]
	v_mfma_f32_16x16x32_bf16 v[78:81], v[144:147], v[190:193], v[78:81]
	v_mfma_f32_16x16x32_bf16 v[78:81], v[148:151], v[194:197], v[78:81]
	v_mfma_f32_16x16x32_bf16 v[122:125], v[152:155], v[160:163], v[122:125]
	v_mfma_f32_16x16x32_bf16 v[122:125], v[156:159], v[164:167], v[122:125]
	v_mfma_f32_16x16x32_bf16 v[106:109], v[152:155], v[168:171], v[106:109]
	v_mfma_f32_16x16x32_bf16 v[106:109], v[156:159], v[172:175], v[106:109]
	v_mfma_f32_16x16x32_bf16 v[90:93], v[152:155], v[182:185], v[90:93]
	v_mfma_f32_16x16x32_bf16 v[90:93], v[156:159], v[186:189], v[90:93]
	v_mfma_f32_16x16x32_bf16 v[74:77], v[152:155], v[190:193], v[74:77]
	v_mfma_f32_16x16x32_bf16 v[74:77], v[156:159], v[194:197], v[74:77]
	v_mfma_f32_16x16x32_bf16 v[118:121], v[198:201], v[160:163], v[118:121]
	v_mfma_f32_16x16x32_bf16 v[118:121], v[202:205], v[164:167], v[118:121]
	v_mfma_f32_16x16x32_bf16 v[102:105], v[198:201], v[168:171], v[102:105]
	v_mfma_f32_16x16x32_bf16 v[102:105], v[202:205], v[172:175], v[102:105]
	v_mfma_f32_16x16x32_bf16 v[86:89], v[198:201], v[182:185], v[86:89]
	v_mfma_f32_16x16x32_bf16 v[86:89], v[202:205], v[186:189], v[86:89]
	v_mfma_f32_16x16x32_bf16 v[70:73], v[198:201], v[190:193], v[70:73]
	v_mfma_f32_16x16x32_bf16 v[70:73], v[202:205], v[194:197], v[70:73]
	v_mfma_f32_16x16x32_bf16 v[114:117], v[206:209], v[160:163], v[114:117]
	v_mfma_f32_16x16x32_bf16 v[114:117], v[210:213], v[164:167], v[114:117]
	v_mfma_f32_16x16x32_bf16 v[98:101], v[206:209], v[168:171], v[98:101]
	v_mfma_f32_16x16x32_bf16 v[98:101], v[210:213], v[172:175], v[98:101]
	v_mfma_f32_16x16x32_bf16 v[82:85], v[206:209], v[182:185], v[82:85]
	v_mfma_f32_16x16x32_bf16 v[82:85], v[210:213], v[186:189], v[82:85]
	v_mfma_f32_16x16x32_bf16 v[66:69], v[206:209], v[190:193], v[66:69]
	v_mfma_f32_16x16x32_bf16 v[66:69], v[210:213], v[194:197], v[66:69]
	s_barrier
	ds_read_b128 v[160:163], v143 offset:16384
	ds_read_b128 v[164:167], v143 offset:17408
	ds_read_b128 v[168:171], v143 offset:18432
	ds_read_b128 v[172:175], v143 offset:19456
	ds_read_b128 v[182:185], v143 offset:20480
	ds_read_b128 v[186:189], v143 offset:21504
	ds_read_b128 v[190:193], v143 offset:22528
	ds_read_b128 v[194:197], v143 offset:23552
	s_add_i32 s35, s35, s46
	v_lshl_add_u64 v[176:177], s[56:57], 0, v[178:179]
	s_mov_b32 m0, s35
	s_nop 0
	global_load_lds_dwordx4 v[176:177], off
	v_lshl_add_u64 v[214:215], s[56:57], 0, v[134:135]
	s_add_i32 m0, s35, 0x2000
	s_nop 0
	global_load_lds_dwordx4 v[214:215], off
	s_add_u32 s52, s56, 0x80000
	s_addc_u32 s53, s57, 0
	s_add_i32 s35, s76, s46
	v_lshl_add_u64 v[234:235], s[52:53], 0, v[178:179]
	s_mov_b32 m0, s35
	s_nop 0
	global_load_lds_dwordx4 v[234:235], off
	v_lshl_add_u64 v[234:235], s[52:53], 0, v[134:135]
	s_add_i32 m0, s35, 0x2000
	s_nop 0
	global_load_lds_dwordx4 v[234:235], off
	s_waitcnt vmcnt(4)
	s_waitcnt lgkmcnt(0)
	s_barrier
; #define PG8_STAGE(bufoff, gbase, voff) do { _Pragma("unroll") for (int _i = 0; _i < 2; ++_i) \
;         __builtin_amdgcn_global_load_lds((const unsigned*)((const char*)(gbase) + (voff)[_i]), (LAS unsigned*)(lds + (bufoff) + ldsw + _i * 8192), 16, 0, 0); } while (0)
; #define PG8_LDA(dst, b, h) do { _Pragma("unroll") for (int m = 0; m < 4; ++m) _Pragma("unroll") for (int k = 0; k < 2; ++k) dst[m][k] = *(const LAS bf16x8*)(lds + PG8_SA(b, h) + aoff + m * 2048 + k * 1024); } while (0)
; #define PG8_LDB(dst, b, h) do { _Pragma("unroll") for (int n = 0; n < 2; ++n) _Pragma("unroll") for (int k = 0; k < 2; ++k) dst[n][k] = *(const LAS bf16x8*)(lds + PG8_SB(b, h) + boff + n * 2048 + k * 1024); } while (0)
; #define PG8_MMA(ai, bj, At, Bt) do { __builtin_amdgcn_s_setprio(1); _Pragma("unroll") for (int m = 0; m < 4; ++m) _Pragma("unroll") for (int n = 0; n < 2; ++n) _Pragma("unroll") for (int k = 0; k < 2; ++k) \
;         acc[ai][bj][m][n] = __builtin_amdgcn_mfma_f32_16x16x32_bf16(Bt[n][k], At[m][k], acc[ai][bj][m][n], 0, 0, 0); __builtin_amdgcn_s_setprio(0); } while (0)
; #define PG8_WAIT_V(n) asm volatile("s_waitcnt vmcnt(" #n ")" ::: "memory")
; #define PG8_WAIT_L(n) asm volatile("s_waitcnt lgkmcnt(" #n ")" ::: "memory")
; #define PG8_BAR __builtin_amdgcn_s_barrier()
; #define PG8_SCHED __builtin_amdgcn_sched_barrier(0)
; template <class Epi, class Sched>
; __device__ __forceinline__ void gemm_phase(LAS unsigned char* lds, const Gemm g, const Sched& S, const Epi& E) {
;     ...
;             PG8_BAR; PG8_WAIT_L(0); PG8_MMA(1, 0, At, B0); PG8_BAR; PG8_SCHED;
;             PG8_STAGE(PG8_SB(0, 1), b2 + hstepB, voffB);
;             PG8_WAIT_V(6); PG8_BAR; PG8_MMA(1, 1, At, B1); PG8_BAR;
;             PG8_LDB(B0, 1, 0); PG8_SCHED; PG8_LDA(At, 1, 0); PG8_STAGE(PG8_SA(0, 1), a2 + hstepA, voffA);
;             PG8_WAIT_L(8); PG8_BAR; PG8_WAIT_L(0); PG8_MMA(0, 0, At, B0); PG8_BAR; PG8_SCHED;
;             PG8_LDB(B1, 1, 1); PG8_STAGE(PG8_SB(1, 0), b3, voffB);
;             PG8_BAR; PG8_WAIT_L(0); PG8_MMA(0, 1, At, B1); PG8_BAR;
	v_mfma_f32_16x16x32_bf16 v[62:65], v[144:147], v[160:163], v[62:65]
	v_mfma_f32_16x16x32_bf16 v[62:65], v[148:151], v[164:167], v[62:65]
	v_mfma_f32_16x16x32_bf16 v[46:49], v[144:147], v[168:171], v[46:49]
	v_mfma_f32_16x16x32_bf16 v[46:49], v[148:151], v[172:175], v[46:49]
	v_mfma_f32_16x16x32_bf16 v[30:33], v[144:147], v[182:185], v[30:33]
	v_mfma_f32_16x16x32_bf16 v[30:33], v[148:151], v[186:189], v[30:33]
	v_mfma_f32_16x16x32_bf16 v[14:17], v[144:147], v[190:193], v[14:17]
	v_mfma_f32_16x16x32_bf16 v[14:17], v[148:151], v[194:197], v[14:17]
	v_mfma_f32_16x16x32_bf16 v[58:61], v[152:155], v[160:163], v[58:61]
	v_mfma_f32_16x16x32_bf16 v[58:61], v[156:159], v[164:167], v[58:61]
	v_mfma_f32_16x16x32_bf16 v[42:45], v[152:155], v[168:171], v[42:45]
	v_mfma_f32_16x16x32_bf16 v[42:45], v[156:159], v[172:175], v[42:45]
	v_mfma_f32_16x16x32_bf16 v[26:29], v[152:155], v[182:185], v[26:29]
	v_mfma_f32_16x16x32_bf16 v[26:29], v[156:159], v[186:189], v[26:29]
	v_mfma_f32_16x16x32_bf16 v[10:13], v[152:155], v[190:193], v[10:13]
	v_mfma_f32_16x16x32_bf16 v[10:13], v[156:159], v[194:197], v[10:13]
	v_mfma_f32_16x16x32_bf16 v[54:57], v[198:201], v[160:163], v[54:57]
	v_mfma_f32_16x16x32_bf16 v[54:57], v[202:205], v[164:167], v[54:57]
	v_mfma_f32_16x16x32_bf16 v[38:41], v[198:201], v[168:171], v[38:41]
	v_mfma_f32_16x16x32_bf16 v[38:41], v[202:205], v[172:175], v[38:41]
	v_mfma_f32_16x16x32_bf16 v[22:25], v[198:201], v[182:185], v[22:25]
	v_mfma_f32_16x16x32_bf16 v[22:25], v[202:205], v[186:189], v[22:25]
	v_mfma_f32_16x16x32_bf16 v[6:9], v[198:201], v[190:193], v[6:9]
	v_mfma_f32_16x16x32_bf16 v[6:9], v[202:205], v[194:197], v[6:9]
	v_mfma_f32_16x16x32_bf16 v[50:53], v[206:209], v[160:163], v[50:53]
	v_mfma_f32_16x16x32_bf16 v[50:53], v[210:213], v[164:167], v[50:53]
	v_mfma_f32_16x16x32_bf16 v[34:37], v[206:209], v[168:171], v[34:37]
	v_mfma_f32_16x16x32_bf16 v[34:37], v[210:213], v[172:175], v[34:37]
	v_mfma_f32_16x16x32_bf16 v[18:21], v[206:209], v[182:185], v[18:21]
	v_mfma_f32_16x16x32_bf16 v[18:21], v[210:213], v[186:189], v[18:21]
	v_mfma_f32_16x16x32_bf16 v[2:5], v[206:209], v[190:193], v[2:5]
	v_mfma_f32_16x16x32_bf16 v[2:5], v[210:213], v[194:197], v[2:5]
	s_add_i32 s35, 0, 0x18000
	v_add_u32_e32 v1, s35, v141
	s_barrier
	ds_read_b128 v[144:147], v1
	ds_read_b128 v[148:151], v1 offset:1024
	ds_read_b128 v[152:155], v1 offset:2048
	ds_read_b128 v[156:159], v1 offset:3072
	ds_read_b128 v[160:163], v143 offset:32768
	ds_read_b128 v[164:167], v143 offset:33792
	ds_read_b128 v[168:171], v143 offset:34816
	ds_read_b128 v[172:175], v143 offset:35840
	ds_read_b128 v[182:185], v143 offset:36864
	ds_read_b128 v[186:189], v143 offset:37888
	ds_read_b128 v[190:193], v143 offset:38912
	ds_read_b128 v[194:197], v143 offset:39936
	s_mov_b32 m0, s9
	v_lshl_add_u64 v[216:217], s[28:29], 0, v[130:131]
	global_load_lds_dwordx4 v[216:217], off
	v_lshl_add_u64 v[218:219], s[28:29], 0, v[132:133]
	s_mov_b32 m0, s11
	s_nop 0
	global_load_lds_dwordx4 v[218:219], off
	s_add_u32 s28, s28, 0x84000
	s_addc_u32 s29, s29, 0
	s_mov_b32 m0, s58
	v_lshl_add_u64 v[236:237], s[28:29], 0, v[130:131]
	global_load_lds_dwordx4 v[236:237], off
	v_lshl_add_u64 v[236:237], s[28:29], 0, v[132:133]
	s_mov_b32 m0, s59
	s_nop 0
	global_load_lds_dwordx4 v[236:237], off
	s_add_i32 s52, 0, 0x1c000
	v_add_u32_e32 v1, s52, v141
	ds_read_b128 v[198:201], v1
	ds_read_b128 v[202:205], v1 offset:1024
	ds_read_b128 v[206:209], v1 offset:2048
	ds_read_b128 v[210:213], v1 offset:3072
	s_waitcnt lgkmcnt(0)
	s_barrier
	v_mfma_f32_16x16x32_bf16 v[126:129], v[144:147], v[160:163], v[126:129]
	v_mfma_f32_16x16x32_bf16 v[126:129], v[148:151], v[164:167], v[126:129]
	v_mfma_f32_16x16x32_bf16 v[110:113], v[144:147], v[168:171], v[110:113]
	v_mfma_f32_16x16x32_bf16 v[110:113], v[148:151], v[172:175], v[110:113]
	v_mfma_f32_16x16x32_bf16 v[94:97], v[144:147], v[182:185], v[94:97]
	v_mfma_f32_16x16x32_bf16 v[94:97], v[148:151], v[186:189], v[94:97]
	v_mfma_f32_16x16x32_bf16 v[78:81], v[144:147], v[190:193], v[78:81]
	v_mfma_f32_16x16x32_bf16 v[78:81], v[148:151], v[194:197], v[78:81]
	v_mfma_f32_16x16x32_bf16 v[122:125], v[152:155], v[160:163], v[122:125]
	v_mfma_f32_16x16x32_bf16 v[122:125], v[156:159], v[164:167], v[122:125]
	v_mfma_f32_16x16x32_bf16 v[106:109], v[152:155], v[168:171], v[106:109]
	v_mfma_f32_16x16x32_bf16 v[106:109], v[156:159], v[172:175], v[106:109]
	v_mfma_f32_16x16x32_bf16 v[90:93], v[152:155], v[182:185], v[90:93]
	v_mfma_f32_16x16x32_bf16 v[90:93], v[156:159], v[186:189], v[90:93]
	v_mfma_f32_16x16x32_bf16 v[74:77], v[152:155], v[190:193], v[74:77]
	v_mfma_f32_16x16x32_bf16 v[74:77], v[156:159], v[194:197], v[74:77]
	v_mfma_f32_16x16x32_bf16 v[118:121], v[198:201], v[160:163], v[118:121]
	v_mfma_f32_16x16x32_bf16 v[118:121], v[202:205], v[164:167], v[118:121]
	v_mfma_f32_16x16x32_bf16 v[102:105], v[198:201], v[168:171], v[102:105]
	v_mfma_f32_16x16x32_bf16 v[102:105], v[202:205], v[172:175], v[102:105]
	v_mfma_f32_16x16x32_bf16 v[86:89], v[198:201], v[182:185], v[86:89]
	v_mfma_f32_16x16x32_bf16 v[86:89], v[202:205], v[186:189], v[86:89]
	v_mfma_f32_16x16x32_bf16 v[70:73], v[198:201], v[190:193], v[70:73]
	v_mfma_f32_16x16x32_bf16 v[70:73], v[202:205], v[194:197], v[70:73]
	v_mfma_f32_16x16x32_bf16 v[114:117], v[206:209], v[160:163], v[114:117]
	v_mfma_f32_16x16x32_bf16 v[114:117], v[210:213], v[164:167], v[114:117]
	v_mfma_f32_16x16x32_bf16 v[98:101], v[206:209], v[168:171], v[98:101]
	v_mfma_f32_16x16x32_bf16 v[98:101], v[210:213], v[172:175], v[98:101]
	v_mfma_f32_16x16x32_bf16 v[82:85], v[206:209], v[182:185], v[82:85]
	v_mfma_f32_16x16x32_bf16 v[82:85], v[210:213], v[186:189], v[82:85]
	v_mfma_f32_16x16x32_bf16 v[66:69], v[206:209], v[190:193], v[66:69]
	v_mfma_f32_16x16x32_bf16 v[66:69], v[210:213], v[194:197], v[66:69]
	s_barrier
; #define PG8_STAGE(bufoff, gbase, voff) do { _Pragma("unroll") for (int _i = 0; _i < 2; ++_i) \
;         __builtin_amdgcn_global_load_lds((const unsigned*)((const char*)(gbase) + (voff)[_i]), (LAS unsigned*)(lds + (bufoff) + ldsw + _i * 8192), 16, 0, 0); } while (0)
; #define PG8_LDA(dst, b, h) do { _Pragma("unroll") for (int m = 0; m < 4; ++m) _Pragma("unroll") for (int k = 0; k < 2; ++k) dst[m][k] = *(const LAS bf16x8*)(lds + PG8_SA(b, h) + aoff + m * 2048 + k * 1024); } while (0)
; #define PG8_MMA(ai, bj, At, Bt) do { __builtin_amdgcn_s_setprio(1); _Pragma("unroll") for (int m = 0; m < 4; ++m) _Pragma("unroll") for (int n = 0; n < 2; ++n) _Pragma("unroll") for (int k = 0; k < 2; ++k) \
;         acc[ai][bj][m][n] = __builtin_amdgcn_mfma_f32_16x16x32_bf16(Bt[n][k], At[m][k], acc[ai][bj][m][n], 0, 0, 0); __builtin_amdgcn_s_setprio(0); } while (0)
; #define PG8_WAIT_V(n) asm volatile("s_waitcnt vmcnt(" #n ")" ::: "memory")
; #define PG8_WAIT_L(n) asm volatile("s_waitcnt lgkmcnt(" #n ")" ::: "memory")
; #define PG8_BAR __builtin_amdgcn_s_barrier()
; #define PG8_SCHED __builtin_amdgcn_sched_barrier(0)
; template <class Epi, class Sched>
; __device__ __forceinline__ void gemm_phase(LAS unsigned char* lds, const Gemm g, const Sched& S, const Epi& E) {
;     ...
;             PG8_LDA(At, 1, 1); PG8_STAGE(PG8_SA(1, 0), a3, voffA);
;             PG8_BAR; PG8_WAIT_L(0); PG8_MMA(1, 0, At, B0); PG8_BAR; PG8_SCHED;
;             PG8_STAGE(PG8_SB(1, 1), b3 + hstepB, voffB);
;             PG8_WAIT_V(6); PG8_BAR; PG8_MMA(1, 1, At, B1); PG8_BAR;
;         }
	ds_read_b128 v[160:163], v143 offset:49152
	ds_read_b128 v[164:167], v143 offset:50176
	ds_read_b128 v[168:171], v143 offset:51200
	ds_read_b128 v[172:175], v143 offset:52224
	ds_read_b128 v[182:185], v143 offset:53248
	ds_read_b128 v[186:189], v143 offset:54272
	ds_read_b128 v[190:193], v143 offset:55296
	ds_read_b128 v[194:197], v143 offset:56320
	s_add_i32 s28, s35, s46
	v_lshl_add_u64 v[176:177], v[176:177], 0, s[92:93]
	s_mov_b32 m0, s28
	s_nop 0
	global_load_lds_dwordx4 v[176:177], off
	v_lshl_add_u64 v[176:177], v[214:215], 0, s[92:93]
	s_add_i32 m0, s28, 0x2000
	s_nop 0
	global_load_lds_dwordx4 v[176:177], off
	s_add_u32 s28, s56, 0x80080
	s_addc_u32 s29, s57, 0
	s_add_i32 s35, s52, s46
	v_lshl_add_u64 v[238:239], s[28:29], 0, v[178:179]
	s_mov_b32 m0, s35
	s_nop 0
	global_load_lds_dwordx4 v[238:239], off
	v_lshl_add_u64 v[238:239], s[28:29], 0, v[134:135]
	s_add_i32 m0, s35, 0x2000
	s_nop 0
	global_load_lds_dwordx4 v[238:239], off
	s_waitcnt vmcnt(4)
	s_waitcnt lgkmcnt(0)
	s_barrier
	v_mfma_f32_16x16x32_bf16 v[62:65], v[144:147], v[160:163], v[62:65]
	v_mfma_f32_16x16x32_bf16 v[62:65], v[148:151], v[164:167], v[62:65]
	v_mfma_f32_16x16x32_bf16 v[46:49], v[144:147], v[168:171], v[46:49]
	v_mfma_f32_16x16x32_bf16 v[46:49], v[148:151], v[172:175], v[46:49]
	v_mfma_f32_16x16x32_bf16 v[30:33], v[144:147], v[182:185], v[30:33]
	v_mfma_f32_16x16x32_bf16 v[30:33], v[148:151], v[186:189], v[30:33]
	v_mfma_f32_16x16x32_bf16 v[14:17], v[144:147], v[190:193], v[14:17]
	v_mfma_f32_16x16x32_bf16 v[14:17], v[148:151], v[194:197], v[14:17]
	v_mfma_f32_16x16x32_bf16 v[58:61], v[152:155], v[160:163], v[58:61]
	v_mfma_f32_16x16x32_bf16 v[58:61], v[156:159], v[164:167], v[58:61]
	v_mfma_f32_16x16x32_bf16 v[42:45], v[152:155], v[168:171], v[42:45]
	v_mfma_f32_16x16x32_bf16 v[42:45], v[156:159], v[172:175], v[42:45]
	v_mfma_f32_16x16x32_bf16 v[26:29], v[152:155], v[182:185], v[26:29]
	v_mfma_f32_16x16x32_bf16 v[26:29], v[156:159], v[186:189], v[26:29]
	v_mfma_f32_16x16x32_bf16 v[10:13], v[152:155], v[190:193], v[10:13]
	v_mfma_f32_16x16x32_bf16 v[10:13], v[156:159], v[194:197], v[10:13]
	v_mfma_f32_16x16x32_bf16 v[54:57], v[198:201], v[160:163], v[54:57]
	v_mfma_f32_16x16x32_bf16 v[54:57], v[202:205], v[164:167], v[54:57]
	v_mfma_f32_16x16x32_bf16 v[38:41], v[198:201], v[168:171], v[38:41]
	v_mfma_f32_16x16x32_bf16 v[38:41], v[202:205], v[172:175], v[38:41]
	v_mfma_f32_16x16x32_bf16 v[22:25], v[198:201], v[182:185], v[22:25]
	v_mfma_f32_16x16x32_bf16 v[22:25], v[202:205], v[186:189], v[22:25]
	v_mfma_f32_16x16x32_bf16 v[6:9], v[198:201], v[190:193], v[6:9]
	v_mfma_f32_16x16x32_bf16 v[6:9], v[202:205], v[194:197], v[6:9]
	v_mfma_f32_16x16x32_bf16 v[50:53], v[206:209], v[160:163], v[50:53]
	v_mfma_f32_16x16x32_bf16 v[50:53], v[210:213], v[164:167], v[50:53]
	v_mfma_f32_16x16x32_bf16 v[34:37], v[206:209], v[168:171], v[34:37]
	v_mfma_f32_16x16x32_bf16 v[34:37], v[210:213], v[172:175], v[34:37]
	v_mfma_f32_16x16x32_bf16 v[18:21], v[206:209], v[182:185], v[18:21]
	v_mfma_f32_16x16x32_bf16 v[18:21], v[210:213], v[186:189], v[18:21]
	v_mfma_f32_16x16x32_bf16 v[2:5], v[206:209], v[190:193], v[2:5]
	v_mfma_f32_16x16x32_bf16 v[2:5], v[210:213], v[194:197], v[2:5]
	s_add_u32 s70, s70, 0x100
	s_addc_u32 s71, s71, 0
	s_cmp_ge_i32 s72, s17
	s_mov_b64 s[52:53], s[54:55]
	s_mov_b32 s28, s72
	s_barrier
	s_cbranch_scc0 .LBB0_985
	v_readlane_b32 s70, v255, 24
	v_readlane_b32 s76, v255, 26
	v_readlane_b32 s71, v255, 25
	v_readlane_b32 s77, v255, 27
	s_andn2_b64 vcc, exec, s[50:51]
	s_mov_b64 s[28:29], s[12:13]
	s_cbranch_vccnz .LBB0_967
	s_branch .LBB0_966

; #define PG8_STAGE(bufoff, gbase, voff) do { _Pragma("unroll") for (int _i = 0; _i < 2; ++_i) \
;         __builtin_amdgcn_global_load_lds((const unsigned*)((const char*)(gbase) + (voff)[_i]), (LAS unsigned*)(lds + (bufoff) + ldsw + _i * 8192), 16, 0, 0); } while (0)
; #define PG8_LDA(dst, b, h) do { _Pragma("unroll") for (int m = 0; m < 4; ++m) _Pragma("unroll") for (int k = 0; k < 2; ++k) dst[m][k] = *(const LAS bf16x8*)(lds + PG8_SA(b, h) + aoff + m * 2048 + k * 1024); } while (0)
; #define PG8_LDB(dst, b, h) do { _Pragma("unroll") for (int n = 0; n < 2; ++n) _Pragma("unroll") for (int k = 0; k < 2; ++k) dst[n][k] = *(const LAS bf16x8*)(lds + PG8_SB(b, h) + boff + n * 2048 + k * 1024); } while (0)
; #define PG8_MMA(ai, bj, At, Bt) do { __builtin_amdgcn_s_setprio(1); _Pragma("unroll") for (int m = 0; m < 4; ++m) _Pragma("unroll") for (int n = 0; n < 2; ++n) _Pragma("unroll") for (int k = 0; k < 2; ++k) \
;         acc[ai][bj][m][n] = __builtin_amdgcn_mfma_f32_16x16x32_bf16(Bt[n][k], At[m][k], acc[ai][bj][m][n], 0, 0, 0); __builtin_amdgcn_s_setprio(0); } while (0)
; #define PG8_WAIT_V(n) asm volatile("s_waitcnt vmcnt(" #n ")" ::: "memory")
; #define PG8_BAR __builtin_amdgcn_s_barrier()
; template <class Epi, class Sched>
; __device__ __forceinline__ void gemm_phase(LAS unsigned char* lds, const Gemm g, const Sched& S, const Epi& E) {
;     ...
;         for (int t = 0; t < ntu; t += 2) {
;             const bool last = (t == ntu - 2);
;             const char* a1 = cA + (size_t)(t + 1) * kstep;
;             const char* a2 = last ? nA : cA + (size_t)(t + 2) * kstep; const char* b2 = last ? nB : cB + (size_t)(t + 2) * kstep;
;             const char* a3 = a2 + kstep; const char* b3 = b2 + kstep;
;             if (last && has_next) S.a_ready(nxt);
;             PG8_LDB(B0, 0, 0); PG8_SCHED; PG8_LDA(At, 0, 0); PG8_STAGE(PG8_SA(1, 1), a1 + hstepA, voffA);
;             PG8_WAIT_L(8); PG8_BAR; PG8_WAIT_L(0); PG8_MMA(0, 0, At, B0); PG8_BAR; PG8_SCHED;
;             PG8_LDB(B1, 0, 1); PG8_STAGE(PG8_SB(0, 0), b2, voffB);
;             PG8_BAR; PG8_WAIT_L(0); PG8_MMA(0, 1, At, B1); PG8_BAR;
;             PG8_LDA(At, 0, 1); PG8_STAGE(PG8_SA(0, 0), a2, voffA);
;             PG8_BAR; PG8_WAIT_L(0); PG8_MMA(1, 0, At, B0); PG8_BAR; PG8_SCHED;
;             PG8_STAGE(PG8_SB(0, 1), b2 + hstepB, voffB);
;             PG8_WAIT_V(6); PG8_BAR; PG8_MMA(1, 1, At, B1); PG8_BAR;
.LBB0_1140:
	s_add_u32 s28, s26, 0xfff80080
	s_addc_u32 s29, s27, -1
	s_add_i32 s35, 0, 0x10000
	v_add_u32_e32 v1, s35, v143
	ds_read_b128 v[146:149], v1
	ds_read_b128 v[150:153], v1 offset:1024
	ds_read_b128 v[154:157], v1 offset:2048
	ds_read_b128 v[158:161], v1 offset:3072
	s_cmp_eq_u32 s63, 28
	s_cselect_b32 s29, s13, s29
	s_cselect_b32 s28, s57, s28
	s_cselect_b32 s51, s11, s62
	s_cselect_b32 s50, s58, s59
	ds_read_b128 v[162:165], v145
	ds_read_b128 v[166:169], v145 offset:1024
	ds_read_b128 v[170:173], v145 offset:2048
	ds_read_b128 v[174:177], v145 offset:3072
	ds_read_b128 v[182:185], v145 offset:4096
	ds_read_b128 v[186:189], v145 offset:5120
	ds_read_b128 v[190:193], v145 offset:6144
	ds_read_b128 v[194:197], v145 offset:7168
	s_mov_b32 s98, 0xfff80000
	s_mov_b32 s99, -1
	v_lshl_add_u64 v[232:233], s[26:27], 0, v[136:137]
	v_lshl_add_u64 v[232:233], v[232:233], 0, s[98:99]
	s_mov_b32 m0, s54
	s_nop 0
	global_load_lds_dwordx4 v[232:233], off
	v_lshl_add_u64 v[232:233], s[26:27], 0, v[138:139]
	v_lshl_add_u64 v[232:233], v[232:233], 0, s[98:99]
	s_mov_b32 m0, s55
	s_nop 0
	global_load_lds_dwordx4 v[232:233], off
	v_lshl_add_u64 v[232:233], s[26:27], 0, v[136:137]
	s_add_i32 m0, s23, 0xc000
	s_nop 0
	global_load_lds_dwordx4 v[232:233], off
	v_lshl_add_u64 v[232:233], s[26:27], 0, v[138:139]
	s_add_i32 m0, s23, 0xe000
	s_nop 0
	global_load_lds_dwordx4 v[232:233], off
	s_add_i32 s66, 0, 0x14000
	v_add_u32_e32 v1, s66, v143
	ds_read_b128 v[198:201], v1
	ds_read_b128 v[202:205], v1 offset:1024
	ds_read_b128 v[206:209], v1 offset:2048
	ds_read_b128 v[210:213], v1 offset:3072
	s_waitcnt lgkmcnt(0)
	s_barrier
	v_mfma_f32_16x16x32_bf16 v[126:129], v[146:149], v[162:165], v[126:129]
	v_mfma_f32_16x16x32_bf16 v[126:129], v[150:153], v[166:169], v[126:129]
	v_mfma_f32_16x16x32_bf16 v[110:113], v[146:149], v[170:173], v[110:113]
	v_mfma_f32_16x16x32_bf16 v[110:113], v[150:153], v[174:177], v[110:113]
	v_mfma_f32_16x16x32_bf16 v[94:97], v[146:149], v[182:185], v[94:97]
	v_mfma_f32_16x16x32_bf16 v[94:97], v[150:153], v[186:189], v[94:97]
	v_mfma_f32_16x16x32_bf16 v[78:81], v[146:149], v[190:193], v[78:81]
	v_mfma_f32_16x16x32_bf16 v[78:81], v[150:153], v[194:197], v[78:81]
	v_mfma_f32_16x16x32_bf16 v[118:121], v[154:157], v[162:165], v[118:121]
	v_mfma_f32_16x16x32_bf16 v[118:121], v[158:161], v[166:169], v[118:121]
	v_mfma_f32_16x16x32_bf16 v[102:105], v[154:157], v[170:173], v[102:105]
	v_mfma_f32_16x16x32_bf16 v[102:105], v[158:161], v[174:177], v[102:105]
	v_mfma_f32_16x16x32_bf16 v[86:89], v[154:157], v[182:185], v[86:89]
	v_mfma_f32_16x16x32_bf16 v[86:89], v[158:161], v[186:189], v[86:89]
	v_mfma_f32_16x16x32_bf16 v[70:73], v[154:157], v[190:193], v[70:73]
	v_mfma_f32_16x16x32_bf16 v[70:73], v[158:161], v[194:197], v[70:73]
	v_mfma_f32_16x16x32_bf16 v[122:125], v[198:201], v[162:165], v[122:125]
	v_mfma_f32_16x16x32_bf16 v[122:125], v[202:205], v[166:169], v[122:125]
	v_mfma_f32_16x16x32_bf16 v[106:109], v[198:201], v[170:173], v[106:109]
	v_mfma_f32_16x16x32_bf16 v[106:109], v[202:205], v[174:177], v[106:109]
	v_mfma_f32_16x16x32_bf16 v[90:93], v[198:201], v[182:185], v[90:93]
	v_mfma_f32_16x16x32_bf16 v[90:93], v[202:205], v[186:189], v[90:93]
	v_mfma_f32_16x16x32_bf16 v[74:77], v[198:201], v[190:193], v[74:77]
	v_mfma_f32_16x16x32_bf16 v[74:77], v[202:205], v[194:197], v[74:77]
	v_mfma_f32_16x16x32_bf16 v[114:117], v[206:209], v[162:165], v[114:117]
	v_mfma_f32_16x16x32_bf16 v[114:117], v[210:213], v[166:169], v[114:117]
	v_mfma_f32_16x16x32_bf16 v[98:101], v[206:209], v[170:173], v[98:101]
	v_mfma_f32_16x16x32_bf16 v[98:101], v[210:213], v[174:177], v[98:101]
	v_mfma_f32_16x16x32_bf16 v[82:85], v[206:209], v[182:185], v[82:85]
	v_mfma_f32_16x16x32_bf16 v[82:85], v[210:213], v[186:189], v[82:85]
	v_mfma_f32_16x16x32_bf16 v[66:69], v[206:209], v[190:193], v[66:69]
	v_mfma_f32_16x16x32_bf16 v[66:69], v[210:213], v[194:197], v[66:69]
	s_barrier
	ds_read_b128 v[162:165], v145 offset:16384
	ds_read_b128 v[166:169], v145 offset:17408
	ds_read_b128 v[170:173], v145 offset:18432
	ds_read_b128 v[174:177], v145 offset:19456
	ds_read_b128 v[182:185], v145 offset:20480
	ds_read_b128 v[186:189], v145 offset:21504
	ds_read_b128 v[190:193], v145 offset:22528
	ds_read_b128 v[194:197], v145 offset:23552
	s_add_i32 s35, s35, s46
	v_lshl_add_u64 v[140:141], s[50:51], 0, v[178:179]
	s_mov_b32 m0, s35
	s_nop 0
	global_load_lds_dwordx4 v[140:141], off
	v_lshl_add_u64 v[214:215], s[50:51], 0, v[134:135]
	s_add_i32 m0, s35, 0x2000
	s_nop 0
	global_load_lds_dwordx4 v[214:215], off
	s_add_u32 s64, s50, 0x80000
	s_addc_u32 s65, s51, 0
	s_add_i32 s35, s66, s46
	v_lshl_add_u64 v[234:235], s[64:65], 0, v[178:179]
	s_mov_b32 m0, s35
	s_nop 0
	global_load_lds_dwordx4 v[234:235], off
	v_lshl_add_u64 v[234:235], s[64:65], 0, v[134:135]
	s_add_i32 m0, s35, 0x2000
	s_nop 0
	global_load_lds_dwordx4 v[234:235], off
	s_waitcnt vmcnt(4)
	s_waitcnt lgkmcnt(0)
	s_barrier
; #define PG8_STAGE(bufoff, gbase, voff) do { _Pragma("unroll") for (int _i = 0; _i < 2; ++_i) \
;         __builtin_amdgcn_global_load_lds((const unsigned*)((const char*)(gbase) + (voff)[_i]), (LAS unsigned*)(lds + (bufoff) + ldsw + _i * 8192), 16, 0, 0); } while (0)
; #define PG8_LDA(dst, b, h) do { _Pragma("unroll") for (int m = 0; m < 4; ++m) _Pragma("unroll") for (int k = 0; k < 2; ++k) dst[m][k] = *(const LAS bf16x8*)(lds + PG8_SA(b, h) + aoff + m * 2048 + k * 1024); } while (0)
; #define PG8_LDB(dst, b, h) do { _Pragma("unroll") for (int n = 0; n < 2; ++n) _Pragma("unroll") for (int k = 0; k < 2; ++k) dst[n][k] = *(const LAS bf16x8*)(lds + PG8_SB(b, h) + boff + n * 2048 + k * 1024); } while (0)
; #define PG8_WAIT_V(n) asm volatile("s_waitcnt vmcnt(" #n ")" ::: "memory")
; #define PG8_WAIT_L(n) asm volatile("s_waitcnt lgkmcnt(" #n ")" ::: "memory")
; #define PG8_BAR __builtin_amdgcn_s_barrier()
; #define PG8_SCHED __builtin_amdgcn_sched_barrier(0)
; template <class Epi, class Sched>
; __device__ __forceinline__ void gemm_phase(LAS unsigned char* lds, const Gemm g, const Sched& S, const Epi& E) {
;     ...
;             PG8_LDB(B0, 0, 0); PG8_SCHED; PG8_LDA(At, 0, 0); PG8_STAGE(PG8_SA(1, 1), a1 + hstepA, voffA);
;             PG8_WAIT_L(8); PG8_BAR; PG8_WAIT_L(0); PG8_MMA(0, 0, At, B0); PG8_BAR; PG8_SCHED;
;             PG8_LDB(B1, 0, 1); PG8_STAGE(PG8_SB(0, 0), b2, voffB);
;             PG8_BAR; PG8_WAIT_L(0); PG8_MMA(0, 1, At, B1); PG8_BAR;
;             PG8_LDA(At, 0, 1); PG8_STAGE(PG8_SA(0, 0), a2, voffA);
;             PG8_BAR; PG8_WAIT_L(0); PG8_MMA(1, 0, At, B0); PG8_BAR; PG8_SCHED;
;             PG8_STAGE(PG8_SB(0, 1), b2 + hstepB, voffB);
;             PG8_WAIT_V(6); PG8_BAR; PG8_MMA(1, 1, At, B1); PG8_BAR;
;             PG8_LDB(B0, 1, 0); PG8_SCHED; PG8_LDA(At, 1, 0); PG8_STAGE(PG8_SA(0, 1), a2 + hstepA, voffA);
;             PG8_WAIT_L(8); PG8_BAR; PG8_WAIT_L(0); PG8_MMA(0, 0, At, B0); PG8_BAR; PG8_SCHED;
;             PG8_LDB(B1, 1, 1); PG8_STAGE(PG8_SB(1, 0), b3, voffB);
;             PG8_BAR; PG8_WAIT_L(0); PG8_MMA(0, 1, At, B1); PG8_BAR;
;             PG8_LDA(At, 1, 1); PG8_STAGE(PG8_SA(1, 0), a3, voffA);
;             PG8_BAR; PG8_WAIT_L(0); PG8_MMA(1, 0, At, B0); PG8_BAR; PG8_SCHED;
;             PG8_STAGE(PG8_SB(1, 1), b3 + hstepB, voffB);
;             PG8_WAIT_V(6); PG8_BAR; PG8_MMA(1, 1, At, B1); PG8_BAR;
	v_mfma_f32_16x16x32_bf16 v[62:65], v[146:149], v[162:165], v[62:65]
	v_mfma_f32_16x16x32_bf16 v[62:65], v[150:153], v[166:169], v[62:65]
	v_mfma_f32_16x16x32_bf16 v[46:49], v[146:149], v[170:173], v[46:49]
	v_mfma_f32_16x16x32_bf16 v[46:49], v[150:153], v[174:177], v[46:49]
	v_mfma_f32_16x16x32_bf16 v[30:33], v[146:149], v[182:185], v[30:33]
	v_mfma_f32_16x16x32_bf16 v[30:33], v[150:153], v[186:189], v[30:33]
	v_mfma_f32_16x16x32_bf16 v[14:17], v[146:149], v[190:193], v[14:17]
	v_mfma_f32_16x16x32_bf16 v[14:17], v[150:153], v[194:197], v[14:17]
	v_mfma_f32_16x16x32_bf16 v[54:57], v[154:157], v[162:165], v[54:57]
	v_mfma_f32_16x16x32_bf16 v[54:57], v[158:161], v[166:169], v[54:57]
	v_mfma_f32_16x16x32_bf16 v[38:41], v[154:157], v[170:173], v[38:41]
	v_mfma_f32_16x16x32_bf16 v[38:41], v[158:161], v[174:177], v[38:41]
	v_mfma_f32_16x16x32_bf16 v[22:25], v[154:157], v[182:185], v[22:25]
	v_mfma_f32_16x16x32_bf16 v[22:25], v[158:161], v[186:189], v[22:25]
	v_mfma_f32_16x16x32_bf16 v[6:9], v[154:157], v[190:193], v[6:9]
	v_mfma_f32_16x16x32_bf16 v[6:9], v[158:161], v[194:197], v[6:9]
	v_mfma_f32_16x16x32_bf16 v[58:61], v[198:201], v[162:165], v[58:61]
	v_mfma_f32_16x16x32_bf16 v[58:61], v[202:205], v[166:169], v[58:61]
	v_mfma_f32_16x16x32_bf16 v[42:45], v[198:201], v[170:173], v[42:45]
	v_mfma_f32_16x16x32_bf16 v[42:45], v[202:205], v[174:177], v[42:45]
	v_mfma_f32_16x16x32_bf16 v[26:29], v[198:201], v[182:185], v[26:29]
	v_mfma_f32_16x16x32_bf16 v[26:29], v[202:205], v[186:189], v[26:29]
	v_mfma_f32_16x16x32_bf16 v[10:13], v[198:201], v[190:193], v[10:13]
	v_mfma_f32_16x16x32_bf16 v[10:13], v[202:205], v[194:197], v[10:13]
	v_mfma_f32_16x16x32_bf16 v[50:53], v[206:209], v[162:165], v[50:53]
	v_mfma_f32_16x16x32_bf16 v[50:53], v[210:213], v[166:169], v[50:53]
	v_mfma_f32_16x16x32_bf16 v[34:37], v[206:209], v[170:173], v[34:37]
	v_mfma_f32_16x16x32_bf16 v[34:37], v[210:213], v[174:177], v[34:37]
	v_mfma_f32_16x16x32_bf16 v[18:21], v[206:209], v[182:185], v[18:21]
	v_mfma_f32_16x16x32_bf16 v[18:21], v[210:213], v[186:189], v[18:21]
	v_mfma_f32_16x16x32_bf16 v[2:5], v[206:209], v[190:193], v[2:5]
	v_mfma_f32_16x16x32_bf16 v[2:5], v[210:213], v[194:197], v[2:5]
	s_add_i32 s35, 0, 0x18000
	v_add_u32_e32 v1, s35, v143
	s_barrier
	ds_read_b128 v[146:149], v1
	ds_read_b128 v[150:153], v1 offset:1024
	ds_read_b128 v[154:157], v1 offset:2048
	ds_read_b128 v[158:161], v1 offset:3072
	ds_read_b128 v[162:165], v145 offset:32768
	ds_read_b128 v[166:169], v145 offset:33792
	ds_read_b128 v[170:173], v145 offset:34816
	ds_read_b128 v[174:177], v145 offset:35840
	ds_read_b128 v[182:185], v145 offset:36864
	ds_read_b128 v[186:189], v145 offset:37888
	ds_read_b128 v[190:193], v145 offset:38912
	ds_read_b128 v[194:197], v145 offset:39936
	s_mov_b32 m0, s23
	v_lshl_add_u64 v[216:217], s[28:29], 0, v[130:131]
	global_load_lds_dwordx4 v[216:217], off
	v_lshl_add_u64 v[218:219], s[28:29], 0, v[132:133]
	s_mov_b32 m0, s25
	s_nop 0
	global_load_lds_dwordx4 v[218:219], off
	s_add_u32 s28, s28, 0x80000
	s_addc_u32 s29, s29, 0
	s_mov_b32 m0, s52
	v_lshl_add_u64 v[236:237], s[28:29], 0, v[130:131]
	global_load_lds_dwordx4 v[236:237], off
	v_lshl_add_u64 v[236:237], s[28:29], 0, v[132:133]
	s_mov_b32 m0, s53
	s_nop 0
	global_load_lds_dwordx4 v[236:237], off
	s_add_i32 s64, 0, 0x1c000
	v_add_u32_e32 v1, s64, v143
	ds_read_b128 v[198:201], v1
	ds_read_b128 v[202:205], v1 offset:1024
	ds_read_b128 v[206:209], v1 offset:2048
	ds_read_b128 v[210:213], v1 offset:3072
	s_waitcnt lgkmcnt(0)
	s_barrier
	v_mfma_f32_16x16x32_bf16 v[126:129], v[146:149], v[162:165], v[126:129]
	v_mfma_f32_16x16x32_bf16 v[126:129], v[150:153], v[166:169], v[126:129]
	v_mfma_f32_16x16x32_bf16 v[110:113], v[146:149], v[170:173], v[110:113]
	v_mfma_f32_16x16x32_bf16 v[110:113], v[150:153], v[174:177], v[110:113]
	v_mfma_f32_16x16x32_bf16 v[94:97], v[146:149], v[182:185], v[94:97]
	v_mfma_f32_16x16x32_bf16 v[94:97], v[150:153], v[186:189], v[94:97]
	v_mfma_f32_16x16x32_bf16 v[78:81], v[146:149], v[190:193], v[78:81]
	v_mfma_f32_16x16x32_bf16 v[78:81], v[150:153], v[194:197], v[78:81]
	v_mfma_f32_16x16x32_bf16 v[118:121], v[154:157], v[162:165], v[118:121]
	v_mfma_f32_16x16x32_bf16 v[118:121], v[158:161], v[166:169], v[118:121]
	v_mfma_f32_16x16x32_bf16 v[102:105], v[154:157], v[170:173], v[102:105]
	v_mfma_f32_16x16x32_bf16 v[102:105], v[158:161], v[174:177], v[102:105]
	v_mfma_f32_16x16x32_bf16 v[86:89], v[154:157], v[182:185], v[86:89]
	v_mfma_f32_16x16x32_bf16 v[86:89], v[158:161], v[186:189], v[86:89]
	v_mfma_f32_16x16x32_bf16 v[70:73], v[154:157], v[190:193], v[70:73]
	v_mfma_f32_16x16x32_bf16 v[70:73], v[158:161], v[194:197], v[70:73]
	v_mfma_f32_16x16x32_bf16 v[122:125], v[198:201], v[162:165], v[122:125]
	v_mfma_f32_16x16x32_bf16 v[122:125], v[202:205], v[166:169], v[122:125]
	v_mfma_f32_16x16x32_bf16 v[106:109], v[198:201], v[170:173], v[106:109]
	v_mfma_f32_16x16x32_bf16 v[106:109], v[202:205], v[174:177], v[106:109]
	v_mfma_f32_16x16x32_bf16 v[90:93], v[198:201], v[182:185], v[90:93]
	v_mfma_f32_16x16x32_bf16 v[90:93], v[202:205], v[186:189], v[90:93]
	v_mfma_f32_16x16x32_bf16 v[74:77], v[198:201], v[190:193], v[74:77]
	v_mfma_f32_16x16x32_bf16 v[74:77], v[202:205], v[194:197], v[74:77]
	v_mfma_f32_16x16x32_bf16 v[114:117], v[206:209], v[162:165], v[114:117]
	v_mfma_f32_16x16x32_bf16 v[114:117], v[210:213], v[166:169], v[114:117]
	v_mfma_f32_16x16x32_bf16 v[98:101], v[206:209], v[170:173], v[98:101]
	v_mfma_f32_16x16x32_bf16 v[98:101], v[210:213], v[174:177], v[98:101]
	v_mfma_f32_16x16x32_bf16 v[82:85], v[206:209], v[182:185], v[82:85]
	v_mfma_f32_16x16x32_bf16 v[82:85], v[210:213], v[186:189], v[82:85]
	v_mfma_f32_16x16x32_bf16 v[66:69], v[206:209], v[190:193], v[66:69]
	v_mfma_f32_16x16x32_bf16 v[66:69], v[210:213], v[194:197], v[66:69]
	s_barrier
; __device__ __forceinline__ unsigned cvt_pk_bf16(float lo, float hi) { const f32x2_t v = {lo, hi}; return __builtin_bit_cast(unsigned, __builtin_convertvector(v, bf16x2_t)); }
; #define PG8_STAGE(bufoff, gbase, voff) do { _Pragma("unroll") for (int _i = 0; _i < 2; ++_i) \
;         __builtin_amdgcn_global_load_lds((const unsigned*)((const char*)(gbase) + (voff)[_i]), (LAS unsigned*)(lds + (bufoff) + ldsw + _i * 8192), 16, 0, 0); } while (0)
; #define PG8_LDA(dst, b, h) do { _Pragma("unroll") for (int m = 0; m < 4; ++m) _Pragma("unroll") for (int k = 0; k < 2; ++k) dst[m][k] = *(const LAS bf16x8*)(lds + PG8_SA(b, h) + aoff + m * 2048 + k * 1024); } while (0)
; #define PG8_WAIT_V(n) asm volatile("s_waitcnt vmcnt(" #n ")" ::: "memory")
;     __device__ __forceinline__ void operator()(f32x4 (&acc)[2][2][4][2], const Unit& u, int wr, int wc, int fr, int fq) const {
;         const int row0 = u.pm * BM + wr * 64 + fr, col0 = u.pn * HALF + wc * 32 + 8 * fq;
; #pragma unroll
;         for (int ai = 0; ai < 2; ++ai)
; #pragma unroll
;             for (int m = 0; m < 4; ++m) { bf16_t* rowp = O + (size_t)(row0 + ai * HALF + m * 16) * FF + col0;
;                 float h[8];
; #pragma unroll
;                 for (int n = 0; n < 2; ++n)
; #pragma unroll
;                     for (int e = 0; e < 4; ++e) { const float g = acc[ai][0][m][n][e], up = acc[ai][1][m][n][e]; h[n * 4 + e] = g * __builtin_amdgcn_rcpf(1.0f + __builtin_amdgcn_exp2f(-1.4426950408889634f * g)) * up; }
;                 u32x4 w; w.x = cvt_pk_bf16(h[0], h[1]); w.y = cvt_pk_bf16(h[2], h[3]); w.z = cvt_pk_bf16(h[4], h[5]); w.w = cvt_pk_bf16(h[6], h[7]);
;                 __builtin_nontemporal_store(w, (u32x4*)rowp); }
; template <class Epi, class Sched>
; __device__ __forceinline__ void gemm_phase(LAS unsigned char* lds, const Gemm g, const Sched& S, const Epi& E) {
;     ...
;             PG8_WAIT_L(8); PG8_BAR; PG8_WAIT_L(0); PG8_MMA(0, 0, At, B0); PG8_BAR; PG8_SCHED;
;             PG8_LDB(B1, 1, 1); PG8_STAGE(PG8_SB(1, 0), b3, voffB);
;             PG8_BAR; PG8_WAIT_L(0); PG8_MMA(0, 1, At, B1); PG8_BAR;
;             PG8_LDA(At, 1, 1); PG8_STAGE(PG8_SA(1, 0), a3, voffA);
;             PG8_BAR; PG8_WAIT_L(0); PG8_MMA(1, 0, At, B0); PG8_BAR; PG8_SCHED;
;             PG8_STAGE(PG8_SB(1, 1), b3 + hstepB, voffB);
;             PG8_WAIT_V(6); PG8_BAR; PG8_MMA(1, 1, At, B1); PG8_BAR;
;         }
	ds_read_b128 v[162:165], v145 offset:49152
	ds_read_b128 v[166:169], v145 offset:50176
	ds_read_b128 v[170:173], v145 offset:51200
	ds_read_b128 v[174:177], v145 offset:52224
	ds_read_b128 v[182:185], v145 offset:53248
	ds_read_b128 v[186:189], v145 offset:54272
	ds_read_b128 v[190:193], v145 offset:55296
	ds_read_b128 v[194:197], v145 offset:56320
	s_add_i32 s28, s35, s46
	v_lshl_add_u64 v[140:141], v[140:141], 0, s[92:93]
	s_mov_b32 m0, s28
	s_nop 0
	global_load_lds_dwordx4 v[140:141], off
	v_lshl_add_u64 v[140:141], v[214:215], 0, s[92:93]
	s_add_i32 m0, s28, 0x2000
	s_nop 0
	global_load_lds_dwordx4 v[140:141], off
	s_add_u32 s28, s50, 0x80080
	s_addc_u32 s29, s51, 0
	s_add_i32 s35, s64, s46
	v_lshl_add_u64 v[238:239], s[28:29], 0, v[178:179]
	s_mov_b32 m0, s35
	s_nop 0
	global_load_lds_dwordx4 v[238:239], off
	v_lshl_add_u64 v[238:239], s[28:29], 0, v[134:135]
	s_add_i32 m0, s35, 0x2000
	s_nop 0
	global_load_lds_dwordx4 v[238:239], off
	s_waitcnt vmcnt(4)
	s_waitcnt lgkmcnt(0)
	s_barrier
	v_mfma_f32_16x16x32_bf16 v[62:65], v[146:149], v[162:165], v[62:65]
	v_mfma_f32_16x16x32_bf16 v[62:65], v[150:153], v[166:169], v[62:65]
	v_mfma_f32_16x16x32_bf16 v[46:49], v[146:149], v[170:173], v[46:49]
	v_mfma_f32_16x16x32_bf16 v[46:49], v[150:153], v[174:177], v[46:49]
	v_mfma_f32_16x16x32_bf16 v[30:33], v[146:149], v[182:185], v[30:33]
	v_mfma_f32_16x16x32_bf16 v[30:33], v[150:153], v[186:189], v[30:33]
	v_mfma_f32_16x16x32_bf16 v[14:17], v[146:149], v[190:193], v[14:17]
	v_mfma_f32_16x16x32_bf16 v[14:17], v[150:153], v[194:197], v[14:17]
	v_mfma_f32_16x16x32_bf16 v[54:57], v[154:157], v[162:165], v[54:57]
	v_mfma_f32_16x16x32_bf16 v[54:57], v[158:161], v[166:169], v[54:57]
	v_mfma_f32_16x16x32_bf16 v[38:41], v[154:157], v[170:173], v[38:41]
	v_mfma_f32_16x16x32_bf16 v[38:41], v[158:161], v[174:177], v[38:41]
	v_mfma_f32_16x16x32_bf16 v[22:25], v[154:157], v[182:185], v[22:25]
	v_mfma_f32_16x16x32_bf16 v[22:25], v[158:161], v[186:189], v[22:25]
	v_mfma_f32_16x16x32_bf16 v[6:9], v[154:157], v[190:193], v[6:9]
	v_mfma_f32_16x16x32_bf16 v[6:9], v[158:161], v[194:197], v[6:9]
	v_mfma_f32_16x16x32_bf16 v[58:61], v[198:201], v[162:165], v[58:61]
	v_mfma_f32_16x16x32_bf16 v[58:61], v[202:205], v[166:169], v[58:61]
	v_mfma_f32_16x16x32_bf16 v[42:45], v[198:201], v[170:173], v[42:45]
	v_mfma_f32_16x16x32_bf16 v[42:45], v[202:205], v[174:177], v[42:45]
	v_mfma_f32_16x16x32_bf16 v[26:29], v[198:201], v[182:185], v[26:29]
	v_mfma_f32_16x16x32_bf16 v[26:29], v[202:205], v[186:189], v[26:29]
	v_mfma_f32_16x16x32_bf16 v[10:13], v[198:201], v[190:193], v[10:13]
	v_mfma_f32_16x16x32_bf16 v[10:13], v[202:205], v[194:197], v[10:13]
	v_mfma_f32_16x16x32_bf16 v[50:53], v[206:209], v[162:165], v[50:53]
	v_mfma_f32_16x16x32_bf16 v[50:53], v[210:213], v[166:169], v[50:53]
	v_mfma_f32_16x16x32_bf16 v[34:37], v[206:209], v[170:173], v[34:37]
	v_mfma_f32_16x16x32_bf16 v[34:37], v[210:213], v[174:177], v[34:37]
	v_mfma_f32_16x16x32_bf16 v[18:21], v[206:209], v[182:185], v[18:21]
	v_mfma_f32_16x16x32_bf16 v[18:21], v[210:213], v[186:189], v[18:21]
	v_mfma_f32_16x16x32_bf16 v[2:5], v[206:209], v[190:193], v[2:5]
	v_mfma_f32_16x16x32_bf16 v[2:5], v[210:213], v[194:197], v[2:5]
	s_add_i32 s63, s63, 2
	s_add_u32 s26, s26, 0x100
	s_addc_u32 s27, s27, 0
	s_add_u32 s59, s59, 0x100
	s_addc_u32 s62, s62, 0
	s_cmp_gt_u32 s63, 29
	s_barrier
	s_cbranch_scc0 .LBB0_1140
	v_mul_f32_e32 v1, 0xbfb8aa3b, v126
	v_exp_f32_e32 v1, v1
	v_lshl_or_b32 v148, s22, 7, v144
	v_lshl_add_u32 v146, s24, 8, v142
	v_ashrrev_i32_e32 v149, 31, v148
	v_add_f32_e32 v1, 1.0, v1
	v_rcp_f32_e32 v152, v1
	v_mul_f32_e32 v1, 0xbfb8aa3b, v127
	v_exp_f32_e32 v1, v1
	v_mov_b64_e32 v[140:141], s[8:9]
	v_mad_i64_i32 v[150:151], s[26:27], v146, s61, v[140:141]
	v_add_f32_e32 v1, 1.0, v1
	v_rcp_f32_e32 v153, v1
	v_mul_f32_e32 v1, 0xbfb8aa3b, v128
	v_exp_f32_e32 v1, v1
	s_and_b64 vcc, exec, s[6:7]
	v_pk_mul_f32 v[126:127], v[126:127], v[152:153]
	s_mov_b32 s22, s10
	v_add_f32_e32 v1, 1.0, v1
	v_pk_mul_f32 v[122:123], v[126:127], v[122:123]
	v_rcp_f32_e32 v126, v1
	v_mul_f32_e32 v1, 0xbfb8aa3b, v129
	v_exp_f32_e32 v1, v1
	s_mov_b32 s24, s12
	s_mov_b64 s[50:51], s[20:21]
	v_add_f32_e32 v1, 1.0, v1
	v_rcp_f32_e32 v127, v1
	v_mul_f32_e32 v1, 0xbfb8aa3b, v118
	v_exp_f32_e32 v1, v1
	v_pk_mul_f32 v[126:127], v[128:129], v[126:127]
	s_nop 0
	v_pk_mul_f32 v[124:125], v[126:127], v[124:125]
	v_add_f32_e32 v1, 1.0, v1
	v_rcp_f32_e32 v126, v1
	v_mul_f32_e32 v1, 0xbfb8aa3b, v119
	v_exp_f32_e32 v1, v1
	s_nop 0
	v_add_f32_e32 v1, 1.0, v1
	v_rcp_f32_e32 v127, v1
	v_mul_f32_e32 v1, 0xbfb8aa3b, v120
	v_exp_f32_e32 v1, v1
	v_pk_mul_f32 v[118:119], v[118:119], v[126:127]
	s_nop 0
	v_pk_mul_f32 v[118:119], v[118:119], v[114:115]
	v_add_f32_e32 v1, 1.0, v1
	v_rcp_f32_e32 v114, v1
	v_mul_f32_e32 v1, 0xbfb8aa3b, v121
	v_exp_f32_e32 v1, v1
	v_cvt_pk_bf16_f32 v118, v118, v119
	v_add_f32_e32 v1, 1.0, v1
	v_rcp_f32_e32 v115, v1
	v_or_b32_e32 v1, 16, v146
	v_pk_mul_f32 v[114:115], v[120:121], v[114:115]
	s_nop 0
	v_pk_mul_f32 v[120:121], v[114:115], v[116:117]
	v_lshlrev_b64 v[114:115], 1, v[148:149]
	v_lshl_add_u64 v[126:127], v[150:151], 0, v[114:115]
	v_cvt_pk_bf16_f32 v116, v122, v123
	v_cvt_pk_bf16_f32 v117, v124, v125
	v_cvt_pk_bf16_f32 v119, v120, v121
	global_store_dwordx4 v[126:127], v[116:119], off nt
	s_nop 1
	v_mad_i64_i32 v[116:117], s[26:27], v1, s61, v[140:141]
	v_mul_f32_e32 v1, 0xbfb8aa3b, v110
	v_exp_f32_e32 v1, v1
	s_nop 0
	v_add_f32_e32 v1, 1.0, v1
	v_rcp_f32_e32 v118, v1
	v_mul_f32_e32 v1, 0xbfb8aa3b, v111
	v_exp_f32_e32 v1, v1
	s_nop 0
	v_add_f32_e32 v1, 1.0, v1
	v_rcp_f32_e32 v119, v1
	v_mul_f32_e32 v1, 0xbfb8aa3b, v112
; __device__ __forceinline__ unsigned cvt_pk_bf16(float lo, float hi) { const f32x2_t v = {lo, hi}; return __builtin_bit_cast(unsigned, __builtin_convertvector(v, bf16x2_t)); }
;     __device__ __forceinline__ void operator()(f32x4 (&acc)[2][2][4][2], const Unit& u, int wr, int wc, int fr, int fq) const {
;         const int row0 = u.pm * BM + wr * 64 + fr, col0 = u.pn * HALF + wc * 32 + 8 * fq;
; #pragma unroll
;         for (int ai = 0; ai < 2; ++ai)
; #pragma unroll
;             for (int m = 0; m < 4; ++m) { bf16_t* rowp = O + (size_t)(row0 + ai * HALF + m * 16) * FF + col0;
;                 float h[8];
; #pragma unroll
;                 for (int n = 0; n < 2; ++n)
; #pragma unroll
;                     for (int e = 0; e < 4; ++e) { const float g = acc[ai][0][m][n][e], up = acc[ai][1][m][n][e]; h[n * 4 + e] = g * __builtin_amdgcn_rcpf(1.0f + __builtin_amdgcn_exp2f(-1.4426950408889634f * g)) * up; }
;                 u32x4 w; w.x = cvt_pk_bf16(h[0], h[1]); w.y = cvt_pk_bf16(h[2], h[3]); w.z = cvt_pk_bf16(h[4], h[5]); w.w = cvt_pk_bf16(h[6], h[7]);
;                 __builtin_nontemporal_store(w, (u32x4*)rowp); }
	v_exp_f32_e32 v1, v1
	v_pk_mul_f32 v[110:111], v[110:111], v[118:119]
	s_nop 0
	v_pk_mul_f32 v[106:107], v[110:111], v[106:107]
	v_add_f32_e32 v1, 1.0, v1
	v_rcp_f32_e32 v110, v1
	v_mul_f32_e32 v1, 0xbfb8aa3b, v113
	v_exp_f32_e32 v1, v1
	s_nop 0
	v_add_f32_e32 v1, 1.0, v1
	v_rcp_f32_e32 v111, v1
	v_mul_f32_e32 v1, 0xbfb8aa3b, v102
	v_exp_f32_e32 v1, v1
	v_pk_mul_f32 v[110:111], v[112:113], v[110:111]
	s_nop 0
	v_pk_mul_f32 v[108:109], v[110:111], v[108:109]
	v_add_f32_e32 v1, 1.0, v1
	v_rcp_f32_e32 v110, v1
	v_mul_f32_e32 v1, 0xbfb8aa3b, v103
	v_exp_f32_e32 v1, v1
	s_nop 0
	v_add_f32_e32 v1, 1.0, v1
	v_rcp_f32_e32 v111, v1
	v_mul_f32_e32 v1, 0xbfb8aa3b, v104
	v_exp_f32_e32 v1, v1
	v_pk_mul_f32 v[102:103], v[102:103], v[110:111]
	s_nop 0
	v_pk_mul_f32 v[102:103], v[102:103], v[98:99]
	v_add_f32_e32 v1, 1.0, v1
	v_rcp_f32_e32 v98, v1
	v_mul_f32_e32 v1, 0xbfb8aa3b, v105
	v_exp_f32_e32 v1, v1
	v_lshl_add_u64 v[110:111], v[116:117], 0, v[114:115]
	v_add_f32_e32 v1, 1.0, v1
	v_rcp_f32_e32 v99, v1
	v_or_b32_e32 v1, 32, v146
	v_pk_mul_f32 v[98:99], v[104:105], v[98:99]
	s_nop 0
	v_pk_mul_f32 v[104:105], v[98:99], v[100:101]
	v_cvt_pk_bf16_f32 v98, v106, v107
	v_cvt_pk_bf16_f32 v99, v108, v109
	v_cvt_pk_bf16_f32 v100, v102, v103
	v_cvt_pk_bf16_f32 v101, v104, v105
	global_store_dwordx4 v[110:111], v[98:101], off nt
	s_nop 1
	v_mad_i64_i32 v[98:99], s[26:27], v1, s61, v[140:141]
	v_mul_f32_e32 v1, 0xbfb8aa3b, v94
	v_exp_f32_e32 v1, v1
	s_nop 0
	v_add_f32_e32 v1, 1.0, v1
	v_rcp_f32_e32 v100, v1
	v_mul_f32_e32 v1, 0xbfb8aa3b, v95
	v_exp_f32_e32 v1, v1
	s_nop 0
	v_add_f32_e32 v1, 1.0, v1
	v_rcp_f32_e32 v101, v1
	v_mul_f32_e32 v1, 0xbfb8aa3b, v96
	v_exp_f32_e32 v1, v1
	v_pk_mul_f32 v[94:95], v[94:95], v[100:101]
	s_nop 0
	v_pk_mul_f32 v[90:91], v[94:95], v[90:91]
	v_add_f32_e32 v1, 1.0, v1
	v_rcp_f32_e32 v94, v1
	v_mul_f32_e32 v1, 0xbfb8aa3b, v97
	v_exp_f32_e32 v1, v1
	s_nop 0
	v_add_f32_e32 v1, 1.0, v1
	v_rcp_f32_e32 v95, v1
	v_mul_f32_e32 v1, 0xbfb8aa3b, v86
	v_exp_f32_e32 v1, v1
	v_pk_mul_f32 v[94:95], v[96:97], v[94:95]
	s_nop 0
	v_pk_mul_f32 v[92:93], v[94:95], v[92:93]
	v_add_f32_e32 v1, 1.0, v1
	v_rcp_f32_e32 v94, v1
	v_mul_f32_e32 v1, 0xbfb8aa3b, v87
	v_exp_f32_e32 v1, v1
	s_nop 0
	v_add_f32_e32 v1, 1.0, v1
	v_rcp_f32_e32 v95, v1
	v_mul_f32_e32 v1, 0xbfb8aa3b, v88
	v_exp_f32_e32 v1, v1
	v_pk_mul_f32 v[86:87], v[86:87], v[94:95]
	s_nop 0
	v_pk_mul_f32 v[86:87], v[86:87], v[82:83]
	v_add_f32_e32 v1, 1.0, v1
	v_rcp_f32_e32 v82, v1
	v_mul_f32_e32 v1, 0xbfb8aa3b, v89
	v_exp_f32_e32 v1, v1
	v_lshl_add_u64 v[94:95], v[98:99], 0, v[114:115]
	v_add_f32_e32 v1, 1.0, v1
	v_rcp_f32_e32 v83, v1
	v_or_b32_e32 v1, 48, v146
	v_pk_mul_f32 v[82:83], v[88:89], v[82:83]
	s_nop 0
	v_pk_mul_f32 v[88:89], v[82:83], v[84:85]
	v_cvt_pk_bf16_f32 v82, v90, v91
	v_cvt_pk_bf16_f32 v83, v92, v93
	v_cvt_pk_bf16_f32 v84, v86, v87
	v_cvt_pk_bf16_f32 v85, v88, v89
	global_store_dwordx4 v[94:95], v[82:85], off nt
	s_nop 1
	v_mad_i64_i32 v[82:83], s[26:27], v1, s61, v[140:141]
	v_mul_f32_e32 v1, 0xbfb8aa3b, v78
	v_exp_f32_e32 v1, v1
	s_nop 0
	v_add_f32_e32 v1, 1.0, v1
	v_rcp_f32_e32 v84, v1
	v_mul_f32_e32 v1, 0xbfb8aa3b, v79
	v_exp_f32_e32 v1, v1
	s_nop 0
	v_add_f32_e32 v1, 1.0, v1
	v_rcp_f32_e32 v85, v1
	v_mul_f32_e32 v1, 0xbfb8aa3b, v80
	v_exp_f32_e32 v1, v1
	v_pk_mul_f32 v[78:79], v[78:79], v[84:85]
	s_nop 0
	v_pk_mul_f32 v[74:75], v[78:79], v[74:75]
	v_add_f32_e32 v1, 1.0, v1
	v_rcp_f32_e32 v78, v1
	v_mul_f32_e32 v1, 0xbfb8aa3b, v81
	v_exp_f32_e32 v1, v1
	s_nop 0
	v_add_f32_e32 v1, 1.0, v1
	v_rcp_f32_e32 v79, v1
	v_mul_f32_e32 v1, 0xbfb8aa3b, v70
	v_exp_f32_e32 v1, v1
	v_pk_mul_f32 v[78:79], v[80:81], v[78:79]
	s_nop 0
	v_pk_mul_f32 v[76:77], v[78:79], v[76:77]
	v_add_f32_e32 v1, 1.0, v1
	v_rcp_f32_e32 v78, v1
	v_mul_f32_e32 v1, 0xbfb8aa3b, v71
	v_exp_f32_e32 v1, v1
	s_nop 0
	v_add_f32_e32 v1, 1.0, v1
	v_rcp_f32_e32 v79, v1
	v_mul_f32_e32 v1, 0xbfb8aa3b, v72
	v_exp_f32_e32 v1, v1
	v_pk_mul_f32 v[70:71], v[70:71], v[78:79]
	s_nop 0
	v_pk_mul_f32 v[70:71], v[70:71], v[66:67]
	v_add_f32_e32 v1, 1.0, v1
	v_rcp_f32_e32 v66, v1
	v_mul_f32_e32 v1, 0xbfb8aa3b, v73
	v_exp_f32_e32 v1, v1
	v_lshl_add_u64 v[78:79], v[82:83], 0, v[114:115]
	v_add_f32_e32 v1, 1.0, v1
	v_rcp_f32_e32 v67, v1
	v_add_u32_e32 v1, 0x80, v146
	v_pk_mul_f32 v[66:67], v[72:73], v[66:67]
	s_nop 0
	v_pk_mul_f32 v[72:73], v[66:67], v[68:69]
	v_cvt_pk_bf16_f32 v66, v74, v75
	v_cvt_pk_bf16_f32 v67, v76, v77
	v_cvt_pk_bf16_f32 v68, v70, v71
	v_cvt_pk_bf16_f32 v69, v72, v73
	global_store_dwordx4 v[78:79], v[66:69], off nt
	s_nop 1
	v_mad_i64_i32 v[66:67], s[26:27], v1, s61, v[140:141]
	v_mul_f32_e32 v1, 0xbfb8aa3b, v62
	v_exp_f32_e32 v1, v1
	s_nop 0
	v_add_f32_e32 v1, 1.0, v1
	v_rcp_f32_e32 v68, v1
	v_mul_f32_e32 v1, 0xbfb8aa3b, v63
	v_exp_f32_e32 v1, v1
	s_nop 0
	v_add_f32_e32 v1, 1.0, v1
	v_rcp_f32_e32 v69, v1
	v_mul_f32_e32 v1, 0xbfb8aa3b, v64
	v_exp_f32_e32 v1, v1
	v_pk_mul_f32 v[62:63], v[62:63], v[68:69]
	s_nop 0
	v_pk_mul_f32 v[58:59], v[62:63], v[58:59]
	v_add_f32_e32 v1, 1.0, v1
	v_rcp_f32_e32 v62, v1
	v_mul_f32_e32 v1, 0xbfb8aa3b, v65
	v_exp_f32_e32 v1, v1
	s_nop 0
	v_add_f32_e32 v1, 1.0, v1
	v_rcp_f32_e32 v63, v1
	v_mul_f32_e32 v1, 0xbfb8aa3b, v54
	v_exp_f32_e32 v1, v1
	v_pk_mul_f32 v[62:63], v[64:65], v[62:63]
	s_nop 0
	v_pk_mul_f32 v[60:61], v[62:63], v[60:61]
	v_add_f32_e32 v1, 1.0, v1
	v_rcp_f32_e32 v62, v1
	v_mul_f32_e32 v1, 0xbfb8aa3b, v55
	v_exp_f32_e32 v1, v1
	s_nop 0
	v_add_f32_e32 v1, 1.0, v1
	v_rcp_f32_e32 v63, v1
	v_mul_f32_e32 v1, 0xbfb8aa3b, v56
; __device__ __forceinline__ unsigned cvt_pk_bf16(float lo, float hi) { const f32x2_t v = {lo, hi}; return __builtin_bit_cast(unsigned, __builtin_convertvector(v, bf16x2_t)); }
; #define PG8_WAIT_V(n) asm volatile("s_waitcnt vmcnt(" #n ")" ::: "memory")
; #define PG8_BAR __builtin_amdgcn_s_barrier()
;     __device__ __forceinline__ void operator()(f32x4 (&acc)[2][2][4][2], const Unit& u, int wr, int wc, int fr, int fq) const {
;         const int row0 = u.pm * BM + wr * 64 + fr, col0 = u.pn * HALF + wc * 32 + 8 * fq;
; #pragma unroll
;         for (int ai = 0; ai < 2; ++ai)
; #pragma unroll
;             for (int m = 0; m < 4; ++m) { bf16_t* rowp = O + (size_t)(row0 + ai * HALF + m * 16) * FF + col0;
;                 float h[8];
; #pragma unroll
;                 for (int n = 0; n < 2; ++n)
; #pragma unroll
;                     for (int e = 0; e < 4; ++e) { const float g = acc[ai][0][m][n][e], up = acc[ai][1][m][n][e]; h[n * 4 + e] = g * __builtin_amdgcn_rcpf(1.0f + __builtin_amdgcn_exp2f(-1.4426950408889634f * g)) * up; }
;                 u32x4 w; w.x = cvt_pk_bf16(h[0], h[1]); w.y = cvt_pk_bf16(h[2], h[3]); w.z = cvt_pk_bf16(h[4], h[5]); w.w = cvt_pk_bf16(h[6], h[7]);
;                 __builtin_nontemporal_store(w, (u32x4*)rowp); }
; template <class Epi, class Sched>
; __device__ __forceinline__ void gemm_phase(LAS unsigned char* lds, const Gemm g, const Sched& S, const Epi& E) {
;     ...
;         if (!has_next) break;
;         if (!E.keep(cur)) {
; #pragma unroll
;             for (int a = 0; a < 2; ++a)
; #pragma unroll
;                 for (int b = 0; b < 2; ++b)
; #pragma unroll
;                     for (int m = 0; m < 4; ++m)
; #pragma unroll
;                         for (int n = 0; n < 2; ++n) acc[a][b][m][n] = (f32x4){0.f, 0.f, 0.f, 0.f};
;         }
;         cur = nxt; cA = nA; cB = nB; ++ui;
;     }
;     PG8_WAIT_V(0);
;     if (wr == 0) PG8_BAR;
;     PG8_BAR;
	v_exp_f32_e32 v1, v1
	v_pk_mul_f32 v[54:55], v[54:55], v[62:63]
	s_nop 0
	v_pk_mul_f32 v[54:55], v[54:55], v[50:51]
	v_add_f32_e32 v1, 1.0, v1
	v_rcp_f32_e32 v50, v1
	v_mul_f32_e32 v1, 0xbfb8aa3b, v57
	v_exp_f32_e32 v1, v1
	v_lshl_add_u64 v[62:63], v[66:67], 0, v[114:115]
	v_add_f32_e32 v1, 1.0, v1
	v_rcp_f32_e32 v51, v1
	v_add_u32_e32 v1, 0x90, v146
	v_pk_mul_f32 v[50:51], v[56:57], v[50:51]
	s_nop 0
	v_pk_mul_f32 v[56:57], v[50:51], v[52:53]
	v_cvt_pk_bf16_f32 v50, v58, v59
	v_cvt_pk_bf16_f32 v51, v60, v61
	v_cvt_pk_bf16_f32 v52, v54, v55
	v_cvt_pk_bf16_f32 v53, v56, v57
	global_store_dwordx4 v[62:63], v[50:53], off nt
	s_nop 1
	v_mad_i64_i32 v[50:51], s[26:27], v1, s61, v[140:141]
	v_mul_f32_e32 v1, 0xbfb8aa3b, v46
	v_exp_f32_e32 v1, v1
	s_nop 0
	v_add_f32_e32 v1, 1.0, v1
	v_rcp_f32_e32 v52, v1
	v_mul_f32_e32 v1, 0xbfb8aa3b, v47
	v_exp_f32_e32 v1, v1
	s_nop 0
	v_add_f32_e32 v1, 1.0, v1
	v_rcp_f32_e32 v53, v1
	v_mul_f32_e32 v1, 0xbfb8aa3b, v48
	v_exp_f32_e32 v1, v1
	v_pk_mul_f32 v[46:47], v[46:47], v[52:53]
	s_nop 0
	v_pk_mul_f32 v[42:43], v[46:47], v[42:43]
	v_add_f32_e32 v1, 1.0, v1
	v_rcp_f32_e32 v46, v1
	v_mul_f32_e32 v1, 0xbfb8aa3b, v49
	v_exp_f32_e32 v1, v1
	s_nop 0
	v_add_f32_e32 v1, 1.0, v1
	v_rcp_f32_e32 v47, v1
	v_mul_f32_e32 v1, 0xbfb8aa3b, v38
	v_exp_f32_e32 v1, v1
	v_pk_mul_f32 v[46:47], v[48:49], v[46:47]
	s_nop 0
	v_pk_mul_f32 v[44:45], v[46:47], v[44:45]
	v_add_f32_e32 v1, 1.0, v1
	v_rcp_f32_e32 v46, v1
	v_mul_f32_e32 v1, 0xbfb8aa3b, v39
	v_exp_f32_e32 v1, v1
	s_nop 0
	v_add_f32_e32 v1, 1.0, v1
	v_rcp_f32_e32 v47, v1
	v_mul_f32_e32 v1, 0xbfb8aa3b, v40
	v_exp_f32_e32 v1, v1
	v_pk_mul_f32 v[38:39], v[38:39], v[46:47]
	s_nop 0
	v_pk_mul_f32 v[38:39], v[38:39], v[34:35]
	v_add_f32_e32 v1, 1.0, v1
	v_rcp_f32_e32 v34, v1
	v_mul_f32_e32 v1, 0xbfb8aa3b, v41
	v_exp_f32_e32 v1, v1
	v_lshl_add_u64 v[46:47], v[50:51], 0, v[114:115]
	v_add_f32_e32 v1, 1.0, v1
	v_rcp_f32_e32 v35, v1
	v_add_u32_e32 v1, 0xa0, v146
	v_pk_mul_f32 v[34:35], v[40:41], v[34:35]
	s_nop 0
	v_pk_mul_f32 v[40:41], v[34:35], v[36:37]
	v_cvt_pk_bf16_f32 v34, v42, v43
	v_cvt_pk_bf16_f32 v35, v44, v45
	v_cvt_pk_bf16_f32 v36, v38, v39
	v_cvt_pk_bf16_f32 v37, v40, v41
	global_store_dwordx4 v[46:47], v[34:37], off nt
	s_nop 1
	v_mad_i64_i32 v[34:35], s[26:27], v1, s61, v[140:141]
	v_mul_f32_e32 v1, 0xbfb8aa3b, v30
	v_exp_f32_e32 v1, v1
	s_nop 0
	v_add_f32_e32 v1, 1.0, v1
	v_rcp_f32_e32 v36, v1
	v_mul_f32_e32 v1, 0xbfb8aa3b, v31
	v_exp_f32_e32 v1, v1
	s_nop 0
	v_add_f32_e32 v1, 1.0, v1
	v_rcp_f32_e32 v37, v1
	v_mul_f32_e32 v1, 0xbfb8aa3b, v32
	v_exp_f32_e32 v1, v1
	v_pk_mul_f32 v[30:31], v[30:31], v[36:37]
	s_nop 0
	v_pk_mul_f32 v[26:27], v[30:31], v[26:27]
	v_add_f32_e32 v1, 1.0, v1
	v_rcp_f32_e32 v30, v1
	v_mul_f32_e32 v1, 0xbfb8aa3b, v33
	v_exp_f32_e32 v1, v1
	s_nop 0
	v_add_f32_e32 v1, 1.0, v1
	v_rcp_f32_e32 v31, v1
	v_mul_f32_e32 v1, 0xbfb8aa3b, v22
	v_exp_f32_e32 v1, v1
	v_pk_mul_f32 v[30:31], v[32:33], v[30:31]
	s_nop 0
	v_pk_mul_f32 v[28:29], v[30:31], v[28:29]
	v_add_f32_e32 v1, 1.0, v1
	v_rcp_f32_e32 v30, v1
	v_mul_f32_e32 v1, 0xbfb8aa3b, v23
	v_exp_f32_e32 v1, v1
	s_nop 0
	v_add_f32_e32 v1, 1.0, v1
	v_rcp_f32_e32 v31, v1
	v_mul_f32_e32 v1, 0xbfb8aa3b, v24
	v_exp_f32_e32 v1, v1
	v_pk_mul_f32 v[22:23], v[22:23], v[30:31]
	s_nop 0
	v_pk_mul_f32 v[22:23], v[22:23], v[18:19]
	v_add_f32_e32 v1, 1.0, v1
	v_rcp_f32_e32 v18, v1
	v_mul_f32_e32 v1, 0xbfb8aa3b, v25
	v_exp_f32_e32 v1, v1
	v_lshl_add_u64 v[30:31], v[34:35], 0, v[114:115]
	v_add_f32_e32 v1, 1.0, v1
	v_rcp_f32_e32 v19, v1
	v_add_u32_e32 v1, 0xb0, v146
	v_pk_mul_f32 v[18:19], v[24:25], v[18:19]
	s_nop 0
	v_pk_mul_f32 v[24:25], v[18:19], v[20:21]
	v_cvt_pk_bf16_f32 v18, v26, v27
	v_cvt_pk_bf16_f32 v19, v28, v29
	v_cvt_pk_bf16_f32 v20, v22, v23
	v_cvt_pk_bf16_f32 v21, v24, v25
	global_store_dwordx4 v[30:31], v[18:21], off nt
	s_nop 1
	v_mad_i64_i32 v[18:19], s[26:27], v1, s61, v[140:141]
	v_mul_f32_e32 v1, 0xbfb8aa3b, v14
	v_exp_f32_e32 v1, v1
	s_mov_b64 s[26:27], s[16:17]
	v_add_f32_e32 v1, 1.0, v1
	v_rcp_f32_e32 v20, v1
	v_mul_f32_e32 v1, 0xbfb8aa3b, v15
	v_exp_f32_e32 v1, v1
	s_nop 0
	v_add_f32_e32 v1, 1.0, v1
	v_rcp_f32_e32 v21, v1
	v_mul_f32_e32 v1, 0xbfb8aa3b, v16
	v_exp_f32_e32 v1, v1
	v_pk_mul_f32 v[14:15], v[14:15], v[20:21]
	s_nop 0
	v_pk_mul_f32 v[10:11], v[14:15], v[10:11]
	v_add_f32_e32 v1, 1.0, v1
	v_rcp_f32_e32 v14, v1
	v_mul_f32_e32 v1, 0xbfb8aa3b, v17
	v_exp_f32_e32 v1, v1
	s_nop 0
	v_add_f32_e32 v1, 1.0, v1
	v_rcp_f32_e32 v15, v1
	v_mul_f32_e32 v1, 0xbfb8aa3b, v6
	v_exp_f32_e32 v1, v1
	v_pk_mul_f32 v[14:15], v[16:17], v[14:15]
	s_nop 0
	v_pk_mul_f32 v[12:13], v[14:15], v[12:13]
	v_add_f32_e32 v1, 1.0, v1
	v_rcp_f32_e32 v14, v1
	v_mul_f32_e32 v1, 0xbfb8aa3b, v7
	v_exp_f32_e32 v1, v1
	s_nop 0
	v_add_f32_e32 v1, 1.0, v1
	v_rcp_f32_e32 v15, v1
	v_mul_f32_e32 v1, 0xbfb8aa3b, v8
	v_exp_f32_e32 v1, v1
	v_pk_mul_f32 v[6:7], v[6:7], v[14:15]
	s_nop 0
	v_pk_mul_f32 v[6:7], v[6:7], v[2:3]
	v_add_f32_e32 v1, 1.0, v1
	v_rcp_f32_e32 v2, v1
	v_mul_f32_e32 v1, 0xbfb8aa3b, v9
	v_exp_f32_e32 v1, v1
	v_lshl_add_u64 v[14:15], v[18:19], 0, v[114:115]
	v_add_f32_e32 v1, 1.0, v1
	v_rcp_f32_e32 v3, v1
	s_nop 0
	v_pk_mul_f32 v[2:3], v[8:9], v[2:3]
	s_nop 0
	v_pk_mul_f32 v[8:9], v[2:3], v[4:5]
	v_cvt_pk_bf16_f32 v2, v10, v11
	v_cvt_pk_bf16_f32 v3, v12, v13
	v_cvt_pk_bf16_f32 v4, v6, v7
	v_cvt_pk_bf16_f32 v5, v8, v9
	global_store_dwordx4 v[14:15], v[2:5], off nt
	s_cbranch_vccz .LBB0_1136
	s_waitcnt vmcnt(0)
	s_cmpk_gt_u32 s1, 0xff
	s_cbranch_scc1 .LBB0_1144
	s_barrier

; #define PG8_STAGE(bufoff, gbase, voff) do { _Pragma("unroll") for (int _i = 0; _i < 2; ++_i) \
;         __builtin_amdgcn_global_load_lds((const unsigned*)((const char*)(gbase) + (voff)[_i]), (LAS unsigned*)(lds + (bufoff) + ldsw + _i * 8192), 16, 0, 0); } while (0)
; #define PG8_LDA(dst, b, h) do { _Pragma("unroll") for (int m = 0; m < 4; ++m) _Pragma("unroll") for (int k = 0; k < 2; ++k) dst[m][k] = *(const LAS bf16x8*)(lds + PG8_SA(b, h) + aoff + m * 2048 + k * 1024); } while (0)
; #define PG8_WAIT_V(n) asm volatile("s_waitcnt vmcnt(" #n ")" ::: "memory")
; template <class Epi, class Sched>
; __device__ __forceinline__ void gemm_phase(LAS unsigned char* lds, const Gemm g, const Sched& S, const Epi& E) {
;     ...
;         for (int t = 0; t < ntu; t += 2) {
;             const bool last = (t == ntu - 2);
;             const char* a1 = cA + (size_t)(t + 1) * kstep;
;             const char* a2 = last ? nA : cA + (size_t)(t + 2) * kstep; const char* b2 = last ? nB : cB + (size_t)(t + 2) * kstep;
;             const char* a3 = a2 + kstep; const char* b3 = b2 + kstep;
;             if (last && has_next) S.a_ready(nxt);
;             PG8_LDB(B0, 0, 0); PG8_SCHED; PG8_LDA(At, 0, 0); PG8_STAGE(PG8_SA(1, 1), a1 + hstepA, voffA);
;             PG8_WAIT_L(8); PG8_BAR; PG8_WAIT_L(0); PG8_MMA(0, 0, At, B0); PG8_BAR; PG8_SCHED;
;             PG8_LDB(B1, 0, 1); PG8_STAGE(PG8_SB(0, 0), b2, voffB);
;             PG8_BAR; PG8_WAIT_L(0); PG8_MMA(0, 1, At, B1); PG8_BAR;
;             PG8_LDA(At, 0, 1); PG8_STAGE(PG8_SA(0, 0), a2, voffA);
;             PG8_BAR; PG8_WAIT_L(0); PG8_MMA(1, 0, At, B0); PG8_BAR; PG8_SCHED;
;             PG8_STAGE(PG8_SB(0, 1), b2 + hstepB, voffB);
;             PG8_WAIT_V(6); PG8_BAR; PG8_MMA(1, 1, At, B1); PG8_BAR;
;             PG8_LDB(B0, 1, 0); PG8_SCHED; PG8_LDA(At, 1, 0); PG8_STAGE(PG8_SA(0, 1), a2 + hstepA, voffA);
;             PG8_WAIT_L(8); PG8_BAR; PG8_WAIT_L(0); PG8_MMA(0, 0, At, B0); PG8_BAR; PG8_SCHED;
;             PG8_LDB(B1, 1, 1); PG8_STAGE(PG8_SB(1, 0), b3, voffB);
;             PG8_BAR; PG8_WAIT_L(0); PG8_MMA(0, 1, At, B1); PG8_BAR;
;             PG8_LDA(At, 1, 1); PG8_STAGE(PG8_SA(1, 0), a3, voffA);
;             PG8_BAR; PG8_WAIT_L(0); PG8_MMA(1, 0, At, B0); PG8_BAR; PG8_SCHED;
;             PG8_STAGE(PG8_SB(1, 1), b3 + hstepB, voffB);
;             PG8_WAIT_V(6); PG8_BAR; PG8_MMA(1, 1, At, B1); PG8_BAR;
.LBB0_1238:
	s_add_i32 s72, s26, 2
	s_add_u32 s24, s22, 0x100
	s_addc_u32 s25, s23, 0
	s_add_i32 s35, 0, 0x10000
	v_add_u32_e32 v1, s35, v141
	ds_read_b128 v[144:147], v1
	ds_read_b128 v[148:151], v1 offset:1024
	ds_read_b128 v[152:155], v1 offset:2048
	ds_read_b128 v[156:159], v1 offset:3072
	s_cmp_eq_u32 s69, s26
	s_cselect_b32 s26, s16, s70
	s_cselect_b32 s29, s13, s25
	s_cselect_b32 s28, s12, s24
	s_cselect_b32 s27, s17, s71
	ds_read_b128 v[160:163], v143
	ds_read_b128 v[164:167], v143 offset:1024
	ds_read_b128 v[168:171], v143 offset:2048
	ds_read_b128 v[172:175], v143 offset:3072
	ds_read_b128 v[182:185], v143 offset:4096
	ds_read_b128 v[186:189], v143 offset:5120
	ds_read_b128 v[190:193], v143 offset:6144
	ds_read_b128 v[194:197], v143 offset:7168
	s_mov_b32 s98, 0xffea0000
	s_mov_b32 s99, -1
	v_lshl_add_u64 v[232:233], s[22:23], 0, v[136:137]
	v_lshl_add_u64 v[232:233], v[232:233], 0, s[98:99]
	s_mov_b32 m0, s56
	s_nop 0
	global_load_lds_dwordx4 v[232:233], off
	v_lshl_add_u64 v[232:233], s[22:23], 0, v[138:139]
	v_lshl_add_u64 v[232:233], v[232:233], 0, s[98:99]
	s_mov_b32 m0, s57
	s_nop 0
	global_load_lds_dwordx4 v[232:233], off
	v_lshl_add_u64 v[232:233], s[22:23], 0, v[136:137]
	s_add_i32 m0, s52, 0xc000
	s_nop 0
	global_load_lds_dwordx4 v[232:233], off
	v_lshl_add_u64 v[232:233], s[22:23], 0, v[138:139]
	s_add_i32 m0, s52, 0xe000
	s_nop 0
	global_load_lds_dwordx4 v[232:233], off
	s_add_i32 s76, 0, 0x14000
	v_add_u32_e32 v1, s76, v141
	ds_read_b128 v[198:201], v1
	ds_read_b128 v[202:205], v1 offset:1024
	ds_read_b128 v[206:209], v1 offset:2048
	ds_read_b128 v[210:213], v1 offset:3072
	s_waitcnt lgkmcnt(0)
	s_barrier
	v_mfma_f32_16x16x32_bf16 v[126:129], v[144:147], v[160:163], v[126:129]
	v_mfma_f32_16x16x32_bf16 v[126:129], v[148:151], v[164:167], v[126:129]
	v_mfma_f32_16x16x32_bf16 v[110:113], v[144:147], v[168:171], v[110:113]
	v_mfma_f32_16x16x32_bf16 v[110:113], v[148:151], v[172:175], v[110:113]
	v_mfma_f32_16x16x32_bf16 v[94:97], v[144:147], v[182:185], v[94:97]
	v_mfma_f32_16x16x32_bf16 v[94:97], v[148:151], v[186:189], v[94:97]
	v_mfma_f32_16x16x32_bf16 v[78:81], v[144:147], v[190:193], v[78:81]
	v_mfma_f32_16x16x32_bf16 v[78:81], v[148:151], v[194:197], v[78:81]
	v_mfma_f32_16x16x32_bf16 v[122:125], v[152:155], v[160:163], v[122:125]
	v_mfma_f32_16x16x32_bf16 v[122:125], v[156:159], v[164:167], v[122:125]
	v_mfma_f32_16x16x32_bf16 v[106:109], v[152:155], v[168:171], v[106:109]
	v_mfma_f32_16x16x32_bf16 v[106:109], v[156:159], v[172:175], v[106:109]
	v_mfma_f32_16x16x32_bf16 v[90:93], v[152:155], v[182:185], v[90:93]
	v_mfma_f32_16x16x32_bf16 v[90:93], v[156:159], v[186:189], v[90:93]
	v_mfma_f32_16x16x32_bf16 v[74:77], v[152:155], v[190:193], v[74:77]
	v_mfma_f32_16x16x32_bf16 v[74:77], v[156:159], v[194:197], v[74:77]
	v_mfma_f32_16x16x32_bf16 v[118:121], v[198:201], v[160:163], v[118:121]
	v_mfma_f32_16x16x32_bf16 v[118:121], v[202:205], v[164:167], v[118:121]
	v_mfma_f32_16x16x32_bf16 v[102:105], v[198:201], v[168:171], v[102:105]
	v_mfma_f32_16x16x32_bf16 v[102:105], v[202:205], v[172:175], v[102:105]
	v_mfma_f32_16x16x32_bf16 v[86:89], v[198:201], v[182:185], v[86:89]
	v_mfma_f32_16x16x32_bf16 v[86:89], v[202:205], v[186:189], v[86:89]
	v_mfma_f32_16x16x32_bf16 v[70:73], v[198:201], v[190:193], v[70:73]
	v_mfma_f32_16x16x32_bf16 v[70:73], v[202:205], v[194:197], v[70:73]
	v_mfma_f32_16x16x32_bf16 v[114:117], v[206:209], v[160:163], v[114:117]
	v_mfma_f32_16x16x32_bf16 v[114:117], v[210:213], v[164:167], v[114:117]
	v_mfma_f32_16x16x32_bf16 v[98:101], v[206:209], v[168:171], v[98:101]
	v_mfma_f32_16x16x32_bf16 v[98:101], v[210:213], v[172:175], v[98:101]
	v_mfma_f32_16x16x32_bf16 v[82:85], v[206:209], v[182:185], v[82:85]
	v_mfma_f32_16x16x32_bf16 v[82:85], v[210:213], v[186:189], v[82:85]
	v_mfma_f32_16x16x32_bf16 v[66:69], v[206:209], v[190:193], v[66:69]
	v_mfma_f32_16x16x32_bf16 v[66:69], v[210:213], v[194:197], v[66:69]
	s_barrier
	ds_read_b128 v[160:163], v143 offset:16384
	ds_read_b128 v[164:167], v143 offset:17408
	ds_read_b128 v[168:171], v143 offset:18432
	ds_read_b128 v[172:175], v143 offset:19456
	ds_read_b128 v[182:185], v143 offset:20480
	ds_read_b128 v[186:189], v143 offset:21504
	ds_read_b128 v[190:193], v143 offset:22528
	ds_read_b128 v[194:197], v143 offset:23552
	s_add_i32 s22, s35, s50
	v_lshl_add_u64 v[176:177], s[26:27], 0, v[178:179]
	s_mov_b32 m0, s22
	s_nop 0
	global_load_lds_dwordx4 v[176:177], off
	v_lshl_add_u64 v[214:215], s[26:27], 0, v[134:135]
	s_add_i32 m0, s22, 0x2000
	s_nop 0
	global_load_lds_dwordx4 v[214:215], off
	s_add_u32 s22, s26, 0x160000
	s_addc_u32 s23, s27, 0
	s_add_i32 s35, s76, s50
	v_lshl_add_u64 v[234:235], s[22:23], 0, v[178:179]
	s_mov_b32 m0, s35
	s_nop 0
	global_load_lds_dwordx4 v[234:235], off
	v_lshl_add_u64 v[234:235], s[22:23], 0, v[134:135]
	s_add_i32 m0, s35, 0x2000
	s_nop 0
	global_load_lds_dwordx4 v[234:235], off
	s_waitcnt vmcnt(4)
	s_waitcnt lgkmcnt(0)
	s_barrier
; #define PG8_STAGE(bufoff, gbase, voff) do { _Pragma("unroll") for (int _i = 0; _i < 2; ++_i) \
;         __builtin_amdgcn_global_load_lds((const unsigned*)((const char*)(gbase) + (voff)[_i]), (LAS unsigned*)(lds + (bufoff) + ldsw + _i * 8192), 16, 0, 0); } while (0)
; #define PG8_LDA(dst, b, h) do { _Pragma("unroll") for (int m = 0; m < 4; ++m) _Pragma("unroll") for (int k = 0; k < 2; ++k) dst[m][k] = *(const LAS bf16x8*)(lds + PG8_SA(b, h) + aoff + m * 2048 + k * 1024); } while (0)
; #define PG8_LDB(dst, b, h) do { _Pragma("unroll") for (int n = 0; n < 2; ++n) _Pragma("unroll") for (int k = 0; k < 2; ++k) dst[n][k] = *(const LAS bf16x8*)(lds + PG8_SB(b, h) + boff + n * 2048 + k * 1024); } while (0)
; #define PG8_WAIT_V(n) asm volatile("s_waitcnt vmcnt(" #n ")" ::: "memory")
; #define PG8_WAIT_L(n) asm volatile("s_waitcnt lgkmcnt(" #n ")" ::: "memory")
; #define PG8_BAR __builtin_amdgcn_s_barrier()
; #define PG8_SCHED __builtin_amdgcn_sched_barrier(0)
; template <class Epi, class Sched>
; __device__ __forceinline__ void gemm_phase(LAS unsigned char* lds, const Gemm g, const Sched& S, const Epi& E) {
;     ...
;             PG8_LDB(B0, 0, 0); PG8_SCHED; PG8_LDA(At, 0, 0); PG8_STAGE(PG8_SA(1, 1), a1 + hstepA, voffA);
;             PG8_WAIT_L(8); PG8_BAR; PG8_WAIT_L(0); PG8_MMA(0, 0, At, B0); PG8_BAR; PG8_SCHED;
;             PG8_LDB(B1, 0, 1); PG8_STAGE(PG8_SB(0, 0), b2, voffB);
;             PG8_BAR; PG8_WAIT_L(0); PG8_MMA(0, 1, At, B1); PG8_BAR;
;             PG8_LDA(At, 0, 1); PG8_STAGE(PG8_SA(0, 0), a2, voffA);
;             PG8_BAR; PG8_WAIT_L(0); PG8_MMA(1, 0, At, B0); PG8_BAR; PG8_SCHED;
;             PG8_STAGE(PG8_SB(0, 1), b2 + hstepB, voffB);
;             PG8_WAIT_V(6); PG8_BAR; PG8_MMA(1, 1, At, B1); PG8_BAR;
;             PG8_LDB(B0, 1, 0); PG8_SCHED; PG8_LDA(At, 1, 0); PG8_STAGE(PG8_SA(0, 1), a2 + hstepA, voffA);
;             PG8_WAIT_L(8); PG8_BAR; PG8_WAIT_L(0); PG8_MMA(0, 0, At, B0); PG8_BAR; PG8_SCHED;
;             PG8_LDB(B1, 1, 1); PG8_STAGE(PG8_SB(1, 0), b3, voffB);
;             PG8_BAR; PG8_WAIT_L(0); PG8_MMA(0, 1, At, B1); PG8_BAR;
;             PG8_LDA(At, 1, 1); PG8_STAGE(PG8_SA(1, 0), a3, voffA);
;             PG8_BAR; PG8_WAIT_L(0); PG8_MMA(1, 0, At, B0); PG8_BAR; PG8_SCHED;
;             PG8_STAGE(PG8_SB(1, 1), b3 + hstepB, voffB);
;             PG8_WAIT_V(6); PG8_BAR; PG8_MMA(1, 1, At, B1); PG8_BAR;
	v_mfma_f32_16x16x32_bf16 v[62:65], v[144:147], v[160:163], v[62:65]
	v_mfma_f32_16x16x32_bf16 v[62:65], v[148:151], v[164:167], v[62:65]
	v_mfma_f32_16x16x32_bf16 v[46:49], v[144:147], v[168:171], v[46:49]
	v_mfma_f32_16x16x32_bf16 v[46:49], v[148:151], v[172:175], v[46:49]
	v_mfma_f32_16x16x32_bf16 v[30:33], v[144:147], v[182:185], v[30:33]
	v_mfma_f32_16x16x32_bf16 v[30:33], v[148:151], v[186:189], v[30:33]
	v_mfma_f32_16x16x32_bf16 v[14:17], v[144:147], v[190:193], v[14:17]
	v_mfma_f32_16x16x32_bf16 v[14:17], v[148:151], v[194:197], v[14:17]
	v_mfma_f32_16x16x32_bf16 v[58:61], v[152:155], v[160:163], v[58:61]
	v_mfma_f32_16x16x32_bf16 v[58:61], v[156:159], v[164:167], v[58:61]
	v_mfma_f32_16x16x32_bf16 v[42:45], v[152:155], v[168:171], v[42:45]
	v_mfma_f32_16x16x32_bf16 v[42:45], v[156:159], v[172:175], v[42:45]
	v_mfma_f32_16x16x32_bf16 v[26:29], v[152:155], v[182:185], v[26:29]
	v_mfma_f32_16x16x32_bf16 v[26:29], v[156:159], v[186:189], v[26:29]
	v_mfma_f32_16x16x32_bf16 v[10:13], v[152:155], v[190:193], v[10:13]
	v_mfma_f32_16x16x32_bf16 v[10:13], v[156:159], v[194:197], v[10:13]
	v_mfma_f32_16x16x32_bf16 v[54:57], v[198:201], v[160:163], v[54:57]
	v_mfma_f32_16x16x32_bf16 v[54:57], v[202:205], v[164:167], v[54:57]
	v_mfma_f32_16x16x32_bf16 v[38:41], v[198:201], v[168:171], v[38:41]
	v_mfma_f32_16x16x32_bf16 v[38:41], v[202:205], v[172:175], v[38:41]
	v_mfma_f32_16x16x32_bf16 v[22:25], v[198:201], v[182:185], v[22:25]
	v_mfma_f32_16x16x32_bf16 v[22:25], v[202:205], v[186:189], v[22:25]
	v_mfma_f32_16x16x32_bf16 v[6:9], v[198:201], v[190:193], v[6:9]
	v_mfma_f32_16x16x32_bf16 v[6:9], v[202:205], v[194:197], v[6:9]
	v_mfma_f32_16x16x32_bf16 v[50:53], v[206:209], v[160:163], v[50:53]
	v_mfma_f32_16x16x32_bf16 v[50:53], v[210:213], v[164:167], v[50:53]
	v_mfma_f32_16x16x32_bf16 v[34:37], v[206:209], v[168:171], v[34:37]
	v_mfma_f32_16x16x32_bf16 v[34:37], v[210:213], v[172:175], v[34:37]
	v_mfma_f32_16x16x32_bf16 v[18:21], v[206:209], v[182:185], v[18:21]
	v_mfma_f32_16x16x32_bf16 v[18:21], v[210:213], v[186:189], v[18:21]
	v_mfma_f32_16x16x32_bf16 v[2:5], v[206:209], v[190:193], v[2:5]
	v_mfma_f32_16x16x32_bf16 v[2:5], v[210:213], v[194:197], v[2:5]
	s_add_i32 s35, 0, 0x18000
	v_add_u32_e32 v1, s35, v141
	s_barrier
	ds_read_b128 v[144:147], v1
	ds_read_b128 v[148:151], v1 offset:1024
	ds_read_b128 v[152:155], v1 offset:2048
	ds_read_b128 v[156:159], v1 offset:3072
	ds_read_b128 v[160:163], v143 offset:32768
	ds_read_b128 v[164:167], v143 offset:33792
	ds_read_b128 v[168:171], v143 offset:34816
	ds_read_b128 v[172:175], v143 offset:35840
	ds_read_b128 v[182:185], v143 offset:36864
	ds_read_b128 v[186:189], v143 offset:37888
	ds_read_b128 v[190:193], v143 offset:38912
	ds_read_b128 v[194:197], v143 offset:39936
	s_mov_b32 m0, s52
	v_lshl_add_u64 v[216:217], s[28:29], 0, v[130:131]
	global_load_lds_dwordx4 v[216:217], off
	v_lshl_add_u64 v[218:219], s[28:29], 0, v[132:133]
	s_mov_b32 m0, s53
	s_nop 0
	global_load_lds_dwordx4 v[218:219], off
	s_add_u32 s22, s28, 0x160000
	s_addc_u32 s23, s29, 0
	s_mov_b32 m0, s54
	v_lshl_add_u64 v[236:237], s[22:23], 0, v[130:131]
	global_load_lds_dwordx4 v[236:237], off
	v_lshl_add_u64 v[236:237], s[22:23], 0, v[132:133]
	s_mov_b32 m0, s55
	s_nop 0
	global_load_lds_dwordx4 v[236:237], off
	s_add_i32 s28, 0, 0x1c000
	v_add_u32_e32 v1, s28, v141
	ds_read_b128 v[198:201], v1
	ds_read_b128 v[202:205], v1 offset:1024
	ds_read_b128 v[206:209], v1 offset:2048
	ds_read_b128 v[210:213], v1 offset:3072
	s_waitcnt lgkmcnt(0)
	s_barrier
; #define PG8_STAGE(bufoff, gbase, voff) do { _Pragma("unroll") for (int _i = 0; _i < 2; ++_i) \
;         __builtin_amdgcn_global_load_lds((const unsigned*)((const char*)(gbase) + (voff)[_i]), (LAS unsigned*)(lds + (bufoff) + ldsw + _i * 8192), 16, 0, 0); } while (0)
; #define PG8_LDA(dst, b, h) do { _Pragma("unroll") for (int m = 0; m < 4; ++m) _Pragma("unroll") for (int k = 0; k < 2; ++k) dst[m][k] = *(const LAS bf16x8*)(lds + PG8_SA(b, h) + aoff + m * 2048 + k * 1024); } while (0)
; #define PG8_LDB(dst, b, h) do { _Pragma("unroll") for (int n = 0; n < 2; ++n) _Pragma("unroll") for (int k = 0; k < 2; ++k) dst[n][k] = *(const LAS bf16x8*)(lds + PG8_SB(b, h) + boff + n * 2048 + k * 1024); } while (0)
; #define PG8_WAIT_V(n) asm volatile("s_waitcnt vmcnt(" #n ")" ::: "memory")
; #define PG8_WAIT_L(n) asm volatile("s_waitcnt lgkmcnt(" #n ")" ::: "memory")
; #define PG8_BAR __builtin_amdgcn_s_barrier()
; #define PG8_SCHED __builtin_amdgcn_sched_barrier(0)
; template <class Epi, class Sched>
; __device__ __forceinline__ void gemm_phase(LAS unsigned char* lds, const Gemm g, const Sched& S, const Epi& E) {
;     ...
;             PG8_LDB(B0, 0, 0); PG8_SCHED; PG8_LDA(At, 0, 0); PG8_STAGE(PG8_SA(1, 1), a1 + hstepA, voffA);
;             PG8_WAIT_L(8); PG8_BAR; PG8_WAIT_L(0); PG8_MMA(0, 0, At, B0); PG8_BAR; PG8_SCHED;
;             PG8_LDB(B1, 0, 1); PG8_STAGE(PG8_SB(0, 0), b2, voffB);
;             PG8_BAR; PG8_WAIT_L(0); PG8_MMA(0, 1, At, B1); PG8_BAR;
;             PG8_LDA(At, 0, 1); PG8_STAGE(PG8_SA(0, 0), a2, voffA);
;             PG8_BAR; PG8_WAIT_L(0); PG8_MMA(1, 0, At, B0); PG8_BAR; PG8_SCHED;
;             PG8_STAGE(PG8_SB(0, 1), b2 + hstepB, voffB);
;             PG8_WAIT_V(6); PG8_BAR; PG8_MMA(1, 1, At, B1); PG8_BAR;
;             PG8_LDB(B0, 1, 0); PG8_SCHED; PG8_LDA(At, 1, 0); PG8_STAGE(PG8_SA(0, 1), a2 + hstepA, voffA);
;             PG8_WAIT_L(8); PG8_BAR; PG8_WAIT_L(0); PG8_MMA(0, 0, At, B0); PG8_BAR; PG8_SCHED;
;             PG8_LDB(B1, 1, 1); PG8_STAGE(PG8_SB(1, 0), b3, voffB);
;             PG8_BAR; PG8_WAIT_L(0); PG8_MMA(0, 1, At, B1); PG8_BAR;
;             PG8_LDA(At, 1, 1); PG8_STAGE(PG8_SA(1, 0), a3, voffA);
;             PG8_BAR; PG8_WAIT_L(0); PG8_MMA(1, 0, At, B0); PG8_BAR; PG8_SCHED;
;             PG8_STAGE(PG8_SB(1, 1), b3 + hstepB, voffB);
;             PG8_WAIT_V(6); PG8_BAR; PG8_MMA(1, 1, At, B1); PG8_BAR;
;         }
	v_mfma_f32_16x16x32_bf16 v[126:129], v[144:147], v[160:163], v[126:129]
	v_mfma_f32_16x16x32_bf16 v[126:129], v[148:151], v[164:167], v[126:129]
	v_mfma_f32_16x16x32_bf16 v[110:113], v[144:147], v[168:171], v[110:113]
	v_mfma_f32_16x16x32_bf16 v[110:113], v[148:151], v[172:175], v[110:113]
	v_mfma_f32_16x16x32_bf16 v[94:97], v[144:147], v[182:185], v[94:97]
	v_mfma_f32_16x16x32_bf16 v[94:97], v[148:151], v[186:189], v[94:97]
	v_mfma_f32_16x16x32_bf16 v[78:81], v[144:147], v[190:193], v[78:81]
	v_mfma_f32_16x16x32_bf16 v[78:81], v[148:151], v[194:197], v[78:81]
	v_mfma_f32_16x16x32_bf16 v[122:125], v[152:155], v[160:163], v[122:125]
	v_mfma_f32_16x16x32_bf16 v[122:125], v[156:159], v[164:167], v[122:125]
	v_mfma_f32_16x16x32_bf16 v[106:109], v[152:155], v[168:171], v[106:109]
	v_mfma_f32_16x16x32_bf16 v[106:109], v[156:159], v[172:175], v[106:109]
	v_mfma_f32_16x16x32_bf16 v[90:93], v[152:155], v[182:185], v[90:93]
	v_mfma_f32_16x16x32_bf16 v[90:93], v[156:159], v[186:189], v[90:93]
	v_mfma_f32_16x16x32_bf16 v[74:77], v[152:155], v[190:193], v[74:77]
	v_mfma_f32_16x16x32_bf16 v[74:77], v[156:159], v[194:197], v[74:77]
	v_mfma_f32_16x16x32_bf16 v[118:121], v[198:201], v[160:163], v[118:121]
	v_mfma_f32_16x16x32_bf16 v[118:121], v[202:205], v[164:167], v[118:121]
	v_mfma_f32_16x16x32_bf16 v[102:105], v[198:201], v[168:171], v[102:105]
	v_mfma_f32_16x16x32_bf16 v[102:105], v[202:205], v[172:175], v[102:105]
	v_mfma_f32_16x16x32_bf16 v[86:89], v[198:201], v[182:185], v[86:89]
	v_mfma_f32_16x16x32_bf16 v[86:89], v[202:205], v[186:189], v[86:89]
	v_mfma_f32_16x16x32_bf16 v[70:73], v[198:201], v[190:193], v[70:73]
	v_mfma_f32_16x16x32_bf16 v[70:73], v[202:205], v[194:197], v[70:73]
	v_mfma_f32_16x16x32_bf16 v[114:117], v[206:209], v[160:163], v[114:117]
	v_mfma_f32_16x16x32_bf16 v[114:117], v[210:213], v[164:167], v[114:117]
	v_mfma_f32_16x16x32_bf16 v[98:101], v[206:209], v[168:171], v[98:101]
	v_mfma_f32_16x16x32_bf16 v[98:101], v[210:213], v[172:175], v[98:101]
	v_mfma_f32_16x16x32_bf16 v[82:85], v[206:209], v[182:185], v[82:85]
	v_mfma_f32_16x16x32_bf16 v[82:85], v[210:213], v[186:189], v[82:85]
	v_mfma_f32_16x16x32_bf16 v[66:69], v[206:209], v[190:193], v[66:69]
	v_mfma_f32_16x16x32_bf16 v[66:69], v[210:213], v[194:197], v[66:69]
	s_barrier
	ds_read_b128 v[160:163], v143 offset:49152
	ds_read_b128 v[164:167], v143 offset:50176
	ds_read_b128 v[168:171], v143 offset:51200
	ds_read_b128 v[172:175], v143 offset:52224
	ds_read_b128 v[182:185], v143 offset:53248
	ds_read_b128 v[186:189], v143 offset:54272
	ds_read_b128 v[190:193], v143 offset:55296
	ds_read_b128 v[194:197], v143 offset:56320
	s_add_i32 s22, s35, s50
	v_lshl_add_u64 v[176:177], v[176:177], 0, s[92:93]
	s_mov_b32 m0, s22
	s_nop 0
	global_load_lds_dwordx4 v[176:177], off
	v_lshl_add_u64 v[176:177], v[214:215], 0, s[92:93]
	s_add_i32 m0, s22, 0x2000
	s_nop 0
	global_load_lds_dwordx4 v[176:177], off
	s_add_u32 s22, s26, 0x160080
	s_addc_u32 s23, s27, 0
	s_add_i32 s26, s28, s50
	v_lshl_add_u64 v[238:239], s[22:23], 0, v[178:179]
	s_mov_b32 m0, s26
	s_nop 0
	global_load_lds_dwordx4 v[238:239], off
	v_lshl_add_u64 v[238:239], s[22:23], 0, v[134:135]
	s_add_i32 m0, s26, 0x2000
	s_nop 0
	global_load_lds_dwordx4 v[238:239], off
	s_waitcnt vmcnt(4)
	s_waitcnt lgkmcnt(0)
	s_barrier
	v_mfma_f32_16x16x32_bf16 v[62:65], v[144:147], v[160:163], v[62:65]
	v_mfma_f32_16x16x32_bf16 v[62:65], v[148:151], v[164:167], v[62:65]
	v_mfma_f32_16x16x32_bf16 v[46:49], v[144:147], v[168:171], v[46:49]
	v_mfma_f32_16x16x32_bf16 v[46:49], v[148:151], v[172:175], v[46:49]
	v_mfma_f32_16x16x32_bf16 v[30:33], v[144:147], v[182:185], v[30:33]
	v_mfma_f32_16x16x32_bf16 v[30:33], v[148:151], v[186:189], v[30:33]
	v_mfma_f32_16x16x32_bf16 v[14:17], v[144:147], v[190:193], v[14:17]
	v_mfma_f32_16x16x32_bf16 v[14:17], v[148:151], v[194:197], v[14:17]
	v_mfma_f32_16x16x32_bf16 v[58:61], v[152:155], v[160:163], v[58:61]
	v_mfma_f32_16x16x32_bf16 v[58:61], v[156:159], v[164:167], v[58:61]
	v_mfma_f32_16x16x32_bf16 v[42:45], v[152:155], v[168:171], v[42:45]
	v_mfma_f32_16x16x32_bf16 v[42:45], v[156:159], v[172:175], v[42:45]
	v_mfma_f32_16x16x32_bf16 v[26:29], v[152:155], v[182:185], v[26:29]
	v_mfma_f32_16x16x32_bf16 v[26:29], v[156:159], v[186:189], v[26:29]
	v_mfma_f32_16x16x32_bf16 v[10:13], v[152:155], v[190:193], v[10:13]
	v_mfma_f32_16x16x32_bf16 v[10:13], v[156:159], v[194:197], v[10:13]
	v_mfma_f32_16x16x32_bf16 v[54:57], v[198:201], v[160:163], v[54:57]
	v_mfma_f32_16x16x32_bf16 v[54:57], v[202:205], v[164:167], v[54:57]
	v_mfma_f32_16x16x32_bf16 v[38:41], v[198:201], v[168:171], v[38:41]
	v_mfma_f32_16x16x32_bf16 v[38:41], v[202:205], v[172:175], v[38:41]
	v_mfma_f32_16x16x32_bf16 v[22:25], v[198:201], v[182:185], v[22:25]
	v_mfma_f32_16x16x32_bf16 v[22:25], v[202:205], v[186:189], v[22:25]
	v_mfma_f32_16x16x32_bf16 v[6:9], v[198:201], v[190:193], v[6:9]
	v_mfma_f32_16x16x32_bf16 v[6:9], v[202:205], v[194:197], v[6:9]
	v_mfma_f32_16x16x32_bf16 v[50:53], v[206:209], v[160:163], v[50:53]
	v_mfma_f32_16x16x32_bf16 v[50:53], v[210:213], v[164:167], v[50:53]
	v_mfma_f32_16x16x32_bf16 v[34:37], v[206:209], v[168:171], v[34:37]
	v_mfma_f32_16x16x32_bf16 v[34:37], v[210:213], v[172:175], v[34:37]
	v_mfma_f32_16x16x32_bf16 v[18:21], v[206:209], v[182:185], v[18:21]
	v_mfma_f32_16x16x32_bf16 v[18:21], v[210:213], v[186:189], v[18:21]
	v_mfma_f32_16x16x32_bf16 v[2:5], v[206:209], v[190:193], v[2:5]
	v_mfma_f32_16x16x32_bf16 v[2:5], v[210:213], v[194:197], v[2:5]
	s_add_u32 s70, s70, 0x100
	s_addc_u32 s71, s71, 0
	s_cmp_ge_i32 s72, s68
	s_mov_b64 s[22:23], s[24:25]
	s_mov_b32 s26, s72
	s_barrier
	s_cbranch_scc0 .LBB0_1238
	v_readlane_b32 s76, v255, 26
	v_readlane_b32 s77, v255, 27
	s_branch .LBB0_1241
